# GEMM K-loop back-edge SALU rotated above the iteration's last barrier (9 loops)
# baseline (speedup 1.0000x reference)
; #define PG8_STAGE(bufoff, gbase, voff) do { _Pragma("unroll") for (int _i = 0; _i < 2; ++_i) \
;         __builtin_amdgcn_global_load_lds((const unsigned*)((const char*)(gbase) + (voff)[_i]), (LAS unsigned*)(lds + (bufoff) + ldsw + _i * 8192), 16, 0, 0); } while (0)
; #define PG8_WAIT_V(n) asm volatile("s_waitcnt vmcnt(" #n ")" ::: "memory")
; #define PG8_WAIT_L(n) asm volatile("s_waitcnt lgkmcnt(" #n ")" ::: "memory")
; #define PG8_BAR __builtin_amdgcn_s_barrier()
; #define PG8_SCHED __builtin_amdgcn_sched_barrier(0)
; template <bool F8 = false, class Epi, class Sched>
; __device__ __forceinline__ void gemm_phase(LAS unsigned char* lds, const int lda, const int ldb, const int K, const Sched& S, const Epi& E) {
;     ...
;         for (int t = 0; t < nt; t += 2) {
;             const bool last = (t == nt - 2);
;             const char* a1 = cA + (size_t)(t + 1) * kstep;
;             const char* a2 = last ? nA : cA + (size_t)(t + 2) * kstep; const char* b2 = last ? nB : cB + (size_t)(t + 2) * kstep;
;             const char* a3 = a2 + kstep; const char* b3 = b2 + kstep;
;             PG8_LDB(B0, 0, 0); PG8_LDB(B1, 0, 1); PG8_SCHED; PG8_LDA(At, 0, 0); PG8_STAGE(PG8_SA(1, 1), a1 + hstepA, voffA);
;             PG8_WAIT_V(8); PG8_WAIT_L(0); PG8_BAR; PG8_MMA(0, 0, At, B0); PG8_MMA(0, 1, At, B1); PG8_BAR; PG8_SCHED;
;             PG8_LDA(At, 0, 1); PG8_STAGE(PG8_SB(0, 0), b2, voffB); PG8_STAGE(PG8_SB(0, 1), b2 + hstepB, voffB); PG8_STAGE(PG8_SA(0, 0), a2, voffA);
;             PG8_WAIT_V(8); PG8_WAIT_L(0); PG8_BAR; PG8_MMA(1, 0, At, B0); PG8_MMA(1, 1, At, B1); PG8_BAR; PG8_SCHED;
.LBB0_242:
	s_add_u32 s29, s72, 0xfff80080
	s_addc_u32 s30, s73, -1
	s_add_i32 s31, 0, 0x10000
	s_cmp_eq_u32 s28, 28
	s_cselect_b32 s75, s5, s30
	s_cselect_b32 s74, s13, s29
	s_cselect_b32 s53, s11, vcc_hi
	s_cselect_b32 s52, s15, vcc_lo
	s_add_i32 s29, 0, 0x14000
	v_add_u32_e32 v158, s31, v147
	v_add_u32_e32 v174, s29, v147
	ds_read_b128 v[142:145], v158
	ds_read_b128 v[150:153], v158 offset:1024
	ds_read_b128 v[154:157], v158 offset:2048
	ds_read_b128 v[158:161], v158 offset:3072
	ds_read_b128 v[162:165], v174
	ds_read_b128 v[166:169], v174 offset:1024
	ds_read_b128 v[170:173], v174 offset:2048
	ds_read_b128 v[174:177], v174 offset:3072
	v_lshl_add_u64 v[194:195], s[72:73], 0, v[136:137]
	s_add_i32 m0, s26, 0xc000
	ds_read_b128 v[178:181], v149
	ds_read_b128 v[182:185], v149 offset:1024
	ds_read_b128 v[186:189], v149 offset:2048
	ds_read_b128 v[190:193], v149 offset:3072
	ds_read_b128 v[202:205], v149 offset:4096
	ds_read_b128 v[206:209], v149 offset:5120
	ds_read_b128 v[210:213], v149 offset:6144
	ds_read_b128 v[214:217], v149 offset:7168
	global_load_lds_dwordx4 v[194:195], off
	v_lshl_add_u64 v[194:195], s[72:73], 0, v[138:139]
	s_add_i32 m0, s26, 0xe000
	s_nop 0
	global_load_lds_dwordx4 v[194:195], off
	s_waitcnt vmcnt(8)
	s_waitcnt lgkmcnt(0)
	s_barrier
	s_setprio 1
	s_waitcnt lgkmcnt(0)
	v_mfma_f32_16x16x32_bf16 v[126:129], v[142:145], v[178:181], v[126:129]
	v_mfma_f32_16x16x32_bf16 v[122:125], v[154:157], v[178:181], v[122:125]
	v_mfma_f32_16x16x32_bf16 v[114:117], v[142:145], v[186:189], v[114:117]
	v_mfma_f32_16x16x32_bf16 v[106:109], v[154:157], v[186:189], v[106:109]
	v_mfma_f32_16x16x32_bf16 v[98:101], v[142:145], v[202:205], v[98:101]
	v_mfma_f32_16x16x32_bf16 v[90:93], v[154:157], v[202:205], v[90:93]
	v_mfma_f32_16x16x32_bf16 v[82:85], v[142:145], v[210:213], v[82:85]
	v_mfma_f32_16x16x32_bf16 v[74:77], v[154:157], v[210:213], v[74:77]
	v_mfma_f32_16x16x32_bf16 v[126:129], v[150:153], v[182:185], v[126:129]
	v_mfma_f32_16x16x32_bf16 v[122:125], v[158:161], v[182:185], v[122:125]
	v_mfma_f32_16x16x32_bf16 v[114:117], v[150:153], v[190:193], v[114:117]
	v_mfma_f32_16x16x32_bf16 v[106:109], v[158:161], v[190:193], v[106:109]
	v_mfma_f32_16x16x32_bf16 v[98:101], v[150:153], v[206:209], v[98:101]
	v_mfma_f32_16x16x32_bf16 v[90:93], v[158:161], v[206:209], v[90:93]
	v_mfma_f32_16x16x32_bf16 v[82:85], v[150:153], v[214:217], v[82:85]
	v_mfma_f32_16x16x32_bf16 v[74:77], v[158:161], v[214:217], v[74:77]
	s_setprio 0
	s_setprio 1
	v_mfma_f32_16x16x32_bf16 v[118:121], v[162:165], v[178:181], v[118:121]
	v_mfma_f32_16x16x32_bf16 v[110:113], v[170:173], v[178:181], v[110:113]
	v_mfma_f32_16x16x32_bf16 v[102:105], v[162:165], v[186:189], v[102:105]
	v_mfma_f32_16x16x32_bf16 v[94:97], v[170:173], v[186:189], v[94:97]
	v_mfma_f32_16x16x32_bf16 v[86:89], v[162:165], v[202:205], v[86:89]
	v_mfma_f32_16x16x32_bf16 v[78:81], v[170:173], v[202:205], v[78:81]
	v_mfma_f32_16x16x32_bf16 v[70:73], v[162:165], v[210:213], v[70:73]
	v_mfma_f32_16x16x32_bf16 v[66:69], v[170:173], v[210:213], v[66:69]
	v_mfma_f32_16x16x32_bf16 v[118:121], v[166:169], v[182:185], v[118:121]
	v_mfma_f32_16x16x32_bf16 v[110:113], v[174:177], v[182:185], v[110:113]
	v_mfma_f32_16x16x32_bf16 v[102:105], v[166:169], v[190:193], v[102:105]
	v_mfma_f32_16x16x32_bf16 v[94:97], v[174:177], v[190:193], v[94:97]
	v_mfma_f32_16x16x32_bf16 v[86:89], v[166:169], v[206:209], v[86:89]
	v_mfma_f32_16x16x32_bf16 v[78:81], v[174:177], v[206:209], v[78:81]
	v_mfma_f32_16x16x32_bf16 v[70:73], v[166:169], v[214:217], v[70:73]
	v_mfma_f32_16x16x32_bf16 v[66:69], v[174:177], v[214:217], v[66:69]
	s_setprio 0
	s_barrier
	s_add_i32 s30, s31, s25
	v_lshl_add_u64 v[194:195], s[52:53], 0, v[0:1]
	s_mov_b32 m0, s30
	ds_read_b128 v[178:181], v149 offset:16384
	ds_read_b128 v[182:185], v149 offset:17408
	ds_read_b128 v[186:189], v149 offset:18432
	ds_read_b128 v[190:193], v149 offset:19456
	ds_read_b128 v[202:205], v149 offset:20480
	ds_read_b128 v[206:209], v149 offset:21504
	ds_read_b128 v[210:213], v149 offset:22528
	ds_read_b128 v[214:217], v149 offset:23552
	global_load_lds_dwordx4 v[194:195], off
	s_add_i32 m0, s30, 0x2000
	s_add_u32 s30, s52, 0x80000
	v_lshl_add_u64 v[218:219], s[52:53], 0, v[134:135]
	s_addc_u32 s31, s53, 0
	s_add_i32 s29, s29, s25
	global_load_lds_dwordx4 v[218:219], off
	v_lshl_add_u64 v[220:221], s[30:31], 0, v[0:1]
	s_mov_b32 m0, s29
	v_lshl_add_u64 v[222:223], s[74:75], 0, v[132:133]
	global_load_lds_dwordx4 v[220:221], off
	v_lshl_add_u64 v[220:221], s[30:31], 0, v[134:135]
	s_add_i32 m0, s29, 0x2000
	s_nop 0
	global_load_lds_dwordx4 v[220:221], off
	v_lshl_add_u64 v[220:221], s[74:75], 0, v[130:131]
	s_mov_b32 m0, s26
	s_nop 0
	global_load_lds_dwordx4 v[220:221], off
	s_mov_b32 m0, s27
	s_nop 0
	global_load_lds_dwordx4 v[222:223], off
	s_waitcnt vmcnt(8)
	s_waitcnt lgkmcnt(0)
	s_barrier
; #define PG8_STAGE(bufoff, gbase, voff) do { _Pragma("unroll") for (int _i = 0; _i < 2; ++_i) \
;         __builtin_amdgcn_global_load_lds((const unsigned*)((const char*)(gbase) + (voff)[_i]), (LAS unsigned*)(lds + (bufoff) + ldsw + _i * 8192), 16, 0, 0); } while (0)
; #define PG8_WAIT_V(n) asm volatile("s_waitcnt vmcnt(" #n ")" ::: "memory")
; #define PG8_WAIT_L(n) asm volatile("s_waitcnt lgkmcnt(" #n ")" ::: "memory")
; #define PG8_BAR __builtin_amdgcn_s_barrier()
; #define PG8_SCHED __builtin_amdgcn_sched_barrier(0)
; template <bool F8 = false, class Epi, class Sched>
; __device__ __forceinline__ void gemm_phase(LAS unsigned char* lds, const int lda, const int ldb, const int K, const Sched& S, const Epi& E) {
;     ...
;             PG8_WAIT_V(8); PG8_WAIT_L(0); PG8_BAR; PG8_MMA(0, 0, At, B0); PG8_MMA(0, 1, At, B1); PG8_BAR; PG8_SCHED;
;             PG8_LDA(At, 0, 1); PG8_STAGE(PG8_SB(0, 0), b2, voffB); PG8_STAGE(PG8_SB(0, 1), b2 + hstepB, voffB); PG8_STAGE(PG8_SA(0, 0), a2, voffA);
;             PG8_WAIT_V(8); PG8_WAIT_L(0); PG8_BAR; PG8_MMA(1, 0, At, B0); PG8_MMA(1, 1, At, B1); PG8_BAR; PG8_SCHED;
;             PG8_LDB(B0, 1, 0); PG8_LDB(B1, 1, 1); PG8_SCHED; PG8_LDA(At, 1, 0); PG8_STAGE(PG8_SA(0, 1), a2 + hstepA, voffA);
;             PG8_WAIT_V(8); PG8_WAIT_L(0); PG8_BAR; PG8_MMA(0, 0, At, B0); PG8_MMA(0, 1, At, B1); PG8_BAR; PG8_SCHED;
	s_setprio 1
	s_waitcnt lgkmcnt(0)
	v_mfma_f32_16x16x32_bf16 v[62:65], v[142:145], v[178:181], v[62:65]
	v_mfma_f32_16x16x32_bf16 v[58:61], v[154:157], v[178:181], v[58:61]
	v_mfma_f32_16x16x32_bf16 v[50:53], v[142:145], v[186:189], v[50:53]
	v_mfma_f32_16x16x32_bf16 v[42:45], v[154:157], v[186:189], v[42:45]
	v_mfma_f32_16x16x32_bf16 v[34:37], v[142:145], v[202:205], v[34:37]
	v_mfma_f32_16x16x32_bf16 v[26:29], v[154:157], v[202:205], v[26:29]
	v_mfma_f32_16x16x32_bf16 v[18:21], v[142:145], v[210:213], v[18:21]
	v_mfma_f32_16x16x32_bf16 v[10:13], v[154:157], v[210:213], v[10:13]
	v_mfma_f32_16x16x32_bf16 v[62:65], v[150:153], v[182:185], v[62:65]
	v_mfma_f32_16x16x32_bf16 v[58:61], v[158:161], v[182:185], v[58:61]
	v_mfma_f32_16x16x32_bf16 v[50:53], v[150:153], v[190:193], v[50:53]
	v_mfma_f32_16x16x32_bf16 v[42:45], v[158:161], v[190:193], v[42:45]
	v_mfma_f32_16x16x32_bf16 v[34:37], v[150:153], v[206:209], v[34:37]
	v_mfma_f32_16x16x32_bf16 v[26:29], v[158:161], v[206:209], v[26:29]
	v_mfma_f32_16x16x32_bf16 v[18:21], v[150:153], v[214:217], v[18:21]
	v_mfma_f32_16x16x32_bf16 v[10:13], v[158:161], v[214:217], v[10:13]
	s_setprio 0
	s_setprio 1
	v_mfma_f32_16x16x32_bf16 v[54:57], v[162:165], v[178:181], v[54:57]
	v_mfma_f32_16x16x32_bf16 v[46:49], v[170:173], v[178:181], v[46:49]
	v_mfma_f32_16x16x32_bf16 v[38:41], v[162:165], v[186:189], v[38:41]
	v_mfma_f32_16x16x32_bf16 v[30:33], v[170:173], v[186:189], v[30:33]
	v_mfma_f32_16x16x32_bf16 v[22:25], v[162:165], v[202:205], v[22:25]
	v_mfma_f32_16x16x32_bf16 v[14:17], v[170:173], v[202:205], v[14:17]
	v_mfma_f32_16x16x32_bf16 v[6:9], v[162:165], v[210:213], v[6:9]
	v_mfma_f32_16x16x32_bf16 v[2:5], v[170:173], v[210:213], v[2:5]
	v_mfma_f32_16x16x32_bf16 v[54:57], v[166:169], v[182:185], v[54:57]
	v_mfma_f32_16x16x32_bf16 v[46:49], v[174:177], v[182:185], v[46:49]
	v_mfma_f32_16x16x32_bf16 v[38:41], v[166:169], v[190:193], v[38:41]
	v_mfma_f32_16x16x32_bf16 v[30:33], v[174:177], v[190:193], v[30:33]
	v_mfma_f32_16x16x32_bf16 v[22:25], v[166:169], v[206:209], v[22:25]
	v_mfma_f32_16x16x32_bf16 v[14:17], v[174:177], v[206:209], v[14:17]
	v_mfma_f32_16x16x32_bf16 v[6:9], v[166:169], v[214:217], v[6:9]
	v_mfma_f32_16x16x32_bf16 v[2:5], v[174:177], v[214:217], v[2:5]
	s_setprio 0
	s_barrier
	s_add_i32 s29, 0, 0x18000
	s_add_i32 s33, 0, 0x1c000
	v_add_u32_e32 v158, s29, v147
	v_add_u32_e32 v174, s33, v147
	ds_read_b128 v[142:145], v158
	ds_read_b128 v[150:153], v158 offset:1024
	ds_read_b128 v[154:157], v158 offset:2048
	ds_read_b128 v[158:161], v158 offset:3072
	ds_read_b128 v[162:165], v174
	ds_read_b128 v[166:169], v174 offset:1024
	ds_read_b128 v[170:173], v174 offset:2048
	ds_read_b128 v[174:177], v174 offset:3072
	s_add_u32 s30, s74, 0x80000
	s_addc_u32 s31, s75, 0
	s_mov_b32 m0, s56
	v_lshl_add_u64 v[224:225], s[30:31], 0, v[130:131]
	ds_read_b128 v[178:181], v149 offset:32768
	ds_read_b128 v[182:185], v149 offset:33792
	ds_read_b128 v[186:189], v149 offset:34816
	ds_read_b128 v[190:193], v149 offset:35840
	ds_read_b128 v[202:205], v149 offset:36864
	ds_read_b128 v[206:209], v149 offset:37888
	ds_read_b128 v[210:213], v149 offset:38912
	ds_read_b128 v[214:217], v149 offset:39936
	global_load_lds_dwordx4 v[224:225], off
	v_lshl_add_u64 v[224:225], s[30:31], 0, v[132:133]
	s_mov_b32 m0, s57
	s_nop 0
	global_load_lds_dwordx4 v[224:225], off
	s_waitcnt vmcnt(8)
	s_waitcnt lgkmcnt(0)
	s_barrier
	s_setprio 1
	s_waitcnt lgkmcnt(0)
	v_mfma_f32_16x16x32_bf16 v[126:129], v[142:145], v[178:181], v[126:129]
	v_mfma_f32_16x16x32_bf16 v[122:125], v[154:157], v[178:181], v[122:125]
	v_mfma_f32_16x16x32_bf16 v[114:117], v[142:145], v[186:189], v[114:117]
	v_mfma_f32_16x16x32_bf16 v[106:109], v[154:157], v[186:189], v[106:109]
	v_mfma_f32_16x16x32_bf16 v[98:101], v[142:145], v[202:205], v[98:101]
	v_mfma_f32_16x16x32_bf16 v[90:93], v[154:157], v[202:205], v[90:93]
	v_mfma_f32_16x16x32_bf16 v[82:85], v[142:145], v[210:213], v[82:85]
	v_mfma_f32_16x16x32_bf16 v[74:77], v[154:157], v[210:213], v[74:77]
	v_mfma_f32_16x16x32_bf16 v[126:129], v[150:153], v[182:185], v[126:129]
	v_mfma_f32_16x16x32_bf16 v[122:125], v[158:161], v[182:185], v[122:125]
	v_mfma_f32_16x16x32_bf16 v[114:117], v[150:153], v[190:193], v[114:117]
	v_mfma_f32_16x16x32_bf16 v[106:109], v[158:161], v[190:193], v[106:109]
	v_mfma_f32_16x16x32_bf16 v[98:101], v[150:153], v[206:209], v[98:101]
	v_mfma_f32_16x16x32_bf16 v[90:93], v[158:161], v[206:209], v[90:93]
	v_mfma_f32_16x16x32_bf16 v[82:85], v[150:153], v[214:217], v[82:85]
	v_mfma_f32_16x16x32_bf16 v[74:77], v[158:161], v[214:217], v[74:77]
	s_setprio 0
	s_setprio 1
	v_mfma_f32_16x16x32_bf16 v[118:121], v[162:165], v[178:181], v[118:121]
	v_mfma_f32_16x16x32_bf16 v[110:113], v[170:173], v[178:181], v[110:113]
	v_mfma_f32_16x16x32_bf16 v[102:105], v[162:165], v[186:189], v[102:105]
	v_mfma_f32_16x16x32_bf16 v[94:97], v[170:173], v[186:189], v[94:97]
	v_mfma_f32_16x16x32_bf16 v[86:89], v[162:165], v[202:205], v[86:89]
	v_mfma_f32_16x16x32_bf16 v[78:81], v[170:173], v[202:205], v[78:81]
	v_mfma_f32_16x16x32_bf16 v[70:73], v[162:165], v[210:213], v[70:73]
	v_mfma_f32_16x16x32_bf16 v[66:69], v[170:173], v[210:213], v[66:69]
	v_mfma_f32_16x16x32_bf16 v[118:121], v[166:169], v[182:185], v[118:121]
	v_mfma_f32_16x16x32_bf16 v[110:113], v[174:177], v[182:185], v[110:113]
	v_mfma_f32_16x16x32_bf16 v[102:105], v[166:169], v[190:193], v[102:105]
	v_mfma_f32_16x16x32_bf16 v[94:97], v[174:177], v[190:193], v[94:97]
	v_mfma_f32_16x16x32_bf16 v[86:89], v[166:169], v[206:209], v[86:89]
	v_mfma_f32_16x16x32_bf16 v[78:81], v[174:177], v[206:209], v[78:81]
	v_mfma_f32_16x16x32_bf16 v[70:73], v[166:169], v[214:217], v[70:73]
	v_mfma_f32_16x16x32_bf16 v[66:69], v[174:177], v[214:217], v[66:69]
	s_setprio 0
	s_barrier
; #define PG8_STAGE(bufoff, gbase, voff) do { _Pragma("unroll") for (int _i = 0; _i < 2; ++_i) \
;         __builtin_amdgcn_global_load_lds((const unsigned*)((const char*)(gbase) + (voff)[_i]), (LAS unsigned*)(lds + (bufoff) + ldsw + _i * 8192), 16, 0, 0); } while (0)
; #define PG8_WAIT_V(n) asm volatile("s_waitcnt vmcnt(" #n ")" ::: "memory")
; #define PG8_WAIT_L(n) asm volatile("s_waitcnt lgkmcnt(" #n ")" ::: "memory")
; #define PG8_BAR __builtin_amdgcn_s_barrier()
; #define PG8_SCHED __builtin_amdgcn_sched_barrier(0)
; template <bool F8 = false, class Epi, class Sched>
; __device__ __forceinline__ void gemm_phase(LAS unsigned char* lds, const int lda, const int ldb, const int K, const Sched& S, const Epi& E) {
;     ...
;             PG8_WAIT_V(8); PG8_WAIT_L(0); PG8_BAR; PG8_MMA(0, 0, At, B0); PG8_MMA(0, 1, At, B1); PG8_BAR; PG8_SCHED;
;             PG8_LDA(At, 1, 1); PG8_STAGE(PG8_SB(1, 0), b3, voffB); PG8_STAGE(PG8_SB(1, 1), b3 + hstepB, voffB); PG8_STAGE(PG8_SA(1, 0), a3, voffA);
;             PG8_WAIT_V(8); PG8_WAIT_L(0); PG8_BAR; PG8_MMA(1, 0, At, B0); PG8_MMA(1, 1, At, B1); PG8_BAR; PG8_SCHED;
;         }
	s_add_i32 s29, s29, s25
	v_lshl_add_u64 v[194:195], v[194:195], 0, s[40:41]
	s_mov_b32 m0, s29
	ds_read_b128 v[178:181], v149 offset:49152
	ds_read_b128 v[182:185], v149 offset:50176
	ds_read_b128 v[186:189], v149 offset:51200
	ds_read_b128 v[190:193], v149 offset:52224
	ds_read_b128 v[202:205], v149 offset:53248
	ds_read_b128 v[206:209], v149 offset:54272
	ds_read_b128 v[210:213], v149 offset:55296
	ds_read_b128 v[214:217], v149 offset:56320
	global_load_lds_dwordx4 v[194:195], off
	s_add_i32 m0, s29, 0x2000
	s_add_u32 s30, s52, 0x80080
	v_lshl_add_u64 v[194:195], v[218:219], 0, s[40:41]
	s_addc_u32 s31, s53, 0
	s_add_i32 s29, s33, s25
	global_load_lds_dwordx4 v[194:195], off
	v_lshl_add_u64 v[194:195], s[30:31], 0, v[0:1]
	s_mov_b32 m0, s29
	s_nop 0
	global_load_lds_dwordx4 v[194:195], off
	v_lshl_add_u64 v[194:195], s[30:31], 0, v[134:135]
	s_add_i32 m0, s29, 0x2000
	s_nop 0
	global_load_lds_dwordx4 v[194:195], off
	v_lshl_add_u64 v[194:195], v[220:221], 0, s[40:41]
	s_mov_b32 m0, s94
	s_nop 0
	global_load_lds_dwordx4 v[194:195], off
	v_lshl_add_u64 v[194:195], v[222:223], 0, s[40:41]
	s_mov_b32 m0, s95
	s_nop 0
	global_load_lds_dwordx4 v[194:195], off
	s_waitcnt vmcnt(8)
	s_waitcnt lgkmcnt(0)
	s_barrier
	s_setprio 1
	s_waitcnt lgkmcnt(0)
	v_mfma_f32_16x16x32_bf16 v[62:65], v[142:145], v[178:181], v[62:65]
	v_mfma_f32_16x16x32_bf16 v[58:61], v[154:157], v[178:181], v[58:61]
	v_mfma_f32_16x16x32_bf16 v[50:53], v[142:145], v[186:189], v[50:53]
	v_mfma_f32_16x16x32_bf16 v[42:45], v[154:157], v[186:189], v[42:45]
	v_mfma_f32_16x16x32_bf16 v[34:37], v[142:145], v[202:205], v[34:37]
	v_mfma_f32_16x16x32_bf16 v[26:29], v[154:157], v[202:205], v[26:29]
	v_mfma_f32_16x16x32_bf16 v[18:21], v[142:145], v[210:213], v[18:21]
	v_mfma_f32_16x16x32_bf16 v[10:13], v[154:157], v[210:213], v[10:13]
	v_mfma_f32_16x16x32_bf16 v[62:65], v[150:153], v[182:185], v[62:65]
	v_mfma_f32_16x16x32_bf16 v[58:61], v[158:161], v[182:185], v[58:61]
	v_mfma_f32_16x16x32_bf16 v[50:53], v[150:153], v[190:193], v[50:53]
	v_mfma_f32_16x16x32_bf16 v[42:45], v[158:161], v[190:193], v[42:45]
	v_mfma_f32_16x16x32_bf16 v[34:37], v[150:153], v[206:209], v[34:37]
	v_mfma_f32_16x16x32_bf16 v[26:29], v[158:161], v[206:209], v[26:29]
	v_mfma_f32_16x16x32_bf16 v[18:21], v[150:153], v[214:217], v[18:21]
	v_mfma_f32_16x16x32_bf16 v[10:13], v[158:161], v[214:217], v[10:13]
	s_setprio 0
	s_setprio 1
	v_mfma_f32_16x16x32_bf16 v[54:57], v[162:165], v[178:181], v[54:57]
	v_mfma_f32_16x16x32_bf16 v[46:49], v[170:173], v[178:181], v[46:49]
	v_mfma_f32_16x16x32_bf16 v[38:41], v[162:165], v[186:189], v[38:41]
	v_mfma_f32_16x16x32_bf16 v[30:33], v[170:173], v[186:189], v[30:33]
	v_mfma_f32_16x16x32_bf16 v[22:25], v[162:165], v[202:205], v[22:25]
	v_mfma_f32_16x16x32_bf16 v[14:17], v[170:173], v[202:205], v[14:17]
	v_mfma_f32_16x16x32_bf16 v[6:9], v[162:165], v[210:213], v[6:9]
	v_mfma_f32_16x16x32_bf16 v[2:5], v[170:173], v[210:213], v[2:5]
	v_mfma_f32_16x16x32_bf16 v[54:57], v[166:169], v[182:185], v[54:57]
	v_mfma_f32_16x16x32_bf16 v[46:49], v[174:177], v[182:185], v[46:49]
	v_mfma_f32_16x16x32_bf16 v[38:41], v[166:169], v[190:193], v[38:41]
	v_mfma_f32_16x16x32_bf16 v[30:33], v[174:177], v[190:193], v[30:33]
	v_mfma_f32_16x16x32_bf16 v[22:25], v[166:169], v[206:209], v[22:25]
	v_mfma_f32_16x16x32_bf16 v[14:17], v[174:177], v[206:209], v[14:17]
	v_mfma_f32_16x16x32_bf16 v[6:9], v[166:169], v[214:217], v[6:9]
	v_mfma_f32_16x16x32_bf16 v[2:5], v[174:177], v[214:217], v[2:5]
	s_add_i32 s28, s28, 2
	s_add_u32 s72, s72, 0x100
	s_addc_u32 s73, s73, 0
	s_add_u32 vcc_lo, vcc_lo, 0x100
	s_addc_u32 vcc_hi, vcc_hi, 0
	s_cmp_gt_u32 s28, 29
	s_setprio 0
	s_barrier
	s_cbranch_scc0 .LBB0_242
	s_and_b64 vcc, exec, s[8:9]
	s_cbranch_vccz .LBB0_245
	s_barrier

; #define PG8_STAGE(bufoff, gbase, voff) do { _Pragma("unroll") for (int _i = 0; _i < 2; ++_i) \
;         __builtin_amdgcn_global_load_lds((const unsigned*)((const char*)(gbase) + (voff)[_i]), (LAS unsigned*)(lds + (bufoff) + ldsw + _i * 8192), 16, 0, 0); } while (0)
; #define PG8_WAIT_V(n) asm volatile("s_waitcnt vmcnt(" #n ")" ::: "memory")
; #define PG8_WAIT_L(n) asm volatile("s_waitcnt lgkmcnt(" #n ")" ::: "memory")
; #define PG8_BAR __builtin_amdgcn_s_barrier()
; #define PG8_SCHED __builtin_amdgcn_sched_barrier(0)
; template <bool F8 = false, class Epi, class Sched>
; __device__ __forceinline__ void gemm_phase(LAS unsigned char* lds, const int lda, const int ldb, const int K, const Sched& S, const Epi& E) {
;     ...
;         for (int t = 0; t < nt; t += 2) {
;             const bool last = (t == nt - 2);
;             const char* a1 = cA + (size_t)(t + 1) * kstep;
;             const char* a2 = last ? nA : cA + (size_t)(t + 2) * kstep; const char* b2 = last ? nB : cB + (size_t)(t + 2) * kstep;
;             const char* a3 = a2 + kstep; const char* b3 = b2 + kstep;
;             PG8_LDB(B0, 0, 0); PG8_LDB(B1, 0, 1); PG8_SCHED; PG8_LDA(At, 0, 0); PG8_STAGE(PG8_SA(1, 1), a1 + hstepA, voffA);
;             PG8_WAIT_V(8); PG8_WAIT_L(0); PG8_BAR; PG8_MMA(0, 0, At, B0); PG8_MMA(0, 1, At, B1); PG8_BAR; PG8_SCHED;
;             PG8_LDA(At, 0, 1); PG8_STAGE(PG8_SB(0, 0), b2, voffB); PG8_STAGE(PG8_SB(0, 1), b2 + hstepB, voffB); PG8_STAGE(PG8_SA(0, 0), a2, voffA);
;             PG8_WAIT_V(8); PG8_WAIT_L(0); PG8_BAR; PG8_MMA(1, 0, At, B0); PG8_MMA(1, 1, At, B1); PG8_BAR; PG8_SCHED;
.LBB0_292:
	s_add_u32 s29, s72, 0xfffc0080
	s_addc_u32 s30, s73, -1
	s_add_i32 s28, 0, 0x10000
	s_cmp_eq_u32 s97, 12
	s_cselect_b32 s53, s11, s30
	s_cselect_b32 s52, s13, s29
	s_cselect_b32 vcc_hi, s9, s19
	s_cselect_b32 vcc_lo, s96, s18
	s_add_i32 s29, 0, 0x14000
	v_add_u32_e32 v2, s28, v177
	v_add_u32_e32 v14, s29, v177
	ds_read_b128 v[18:21], v2
	ds_read_b128 v[22:25], v2 offset:1024
	ds_read_b128 v[26:29], v2 offset:2048
	ds_read_b128 v[30:33], v2 offset:3072
	ds_read_b128 v[2:5], v14
	ds_read_b128 v[6:9], v14 offset:1024
	ds_read_b128 v[10:13], v14 offset:2048
	ds_read_b128 v[14:17], v14 offset:3072
	v_lshl_add_u64 v[210:211], s[72:73], 0, v[164:165]
	s_add_i32 m0, s15, 0xc000
	ds_read_b128 v[168:171], v179
	ds_read_b128 v[172:175], v179 offset:1024
	ds_read_b128 v[180:183], v179 offset:2048
	ds_read_b128 v[184:187], v179 offset:3072
	ds_read_b128 v[188:191], v179 offset:4096
	ds_read_b128 v[192:195], v179 offset:5120
	ds_read_b128 v[202:205], v179 offset:6144
	ds_read_b128 v[206:209], v179 offset:7168
	global_load_lds_dwordx4 v[210:211], off
	v_lshl_add_u64 v[210:211], s[72:73], 0, v[166:167]
	s_add_i32 m0, s15, 0xe000
	s_nop 0
	global_load_lds_dwordx4 v[210:211], off
	s_waitcnt vmcnt(8)
	s_waitcnt lgkmcnt(0)
	s_barrier
	s_setprio 1
	s_waitcnt lgkmcnt(0)
	v_mfma_scale_f32_16x16x128_f8f6f4 v[158:161], v[18:25], v[168:175], v[158:161], v236, v236 op_sel_hi:[0,0,0]
	v_mfma_scale_f32_16x16x128_f8f6f4 v[154:157], v[26:33], v[168:175], v[154:157], v236, v236 op_sel_hi:[0,0,0]
	v_mfma_scale_f32_16x16x128_f8f6f4 v[150:153], v[18:25], v[180:187], v[150:153], v236, v236 op_sel_hi:[0,0,0]
	v_mfma_scale_f32_16x16x128_f8f6f4 v[142:145], v[26:33], v[180:187], v[142:145], v236, v236 op_sel_hi:[0,0,0]
	v_mfma_scale_f32_16x16x128_f8f6f4 v[134:137], v[18:25], v[188:195], v[134:137], v236, v236 op_sel_hi:[0,0,0]
	v_mfma_scale_f32_16x16x128_f8f6f4 v[126:129], v[26:33], v[188:195], v[126:129], v236, v236 op_sel_hi:[0,0,0]
	v_mfma_scale_f32_16x16x128_f8f6f4 v[118:121], v[18:25], v[202:209], v[118:121], v236, v236 op_sel_hi:[0,0,0]
	v_mfma_scale_f32_16x16x128_f8f6f4 v[110:113], v[26:33], v[202:209], v[110:113], v236, v236 op_sel_hi:[0,0,0]
	s_setprio 0
	s_setprio 1
	v_mfma_scale_f32_16x16x128_f8f6f4 v[146:149], v[2:9], v[168:175], v[146:149], v236, v236 op_sel_hi:[0,0,0]
	v_mfma_scale_f32_16x16x128_f8f6f4 v[138:141], v[10:17], v[168:175], v[138:141], v236, v236 op_sel_hi:[0,0,0]
	v_mfma_scale_f32_16x16x128_f8f6f4 v[130:133], v[2:9], v[180:187], v[130:133], v236, v236 op_sel_hi:[0,0,0]
	v_mfma_scale_f32_16x16x128_f8f6f4 v[122:125], v[10:17], v[180:187], v[122:125], v236, v236 op_sel_hi:[0,0,0]
	v_mfma_scale_f32_16x16x128_f8f6f4 v[114:117], v[2:9], v[188:195], v[114:117], v236, v236 op_sel_hi:[0,0,0]
	v_mfma_scale_f32_16x16x128_f8f6f4 v[106:109], v[10:17], v[188:195], v[106:109], v236, v236 op_sel_hi:[0,0,0]
	v_mfma_scale_f32_16x16x128_f8f6f4 v[102:105], v[2:9], v[202:209], v[102:105], v236, v236 op_sel_hi:[0,0,0]
	v_mfma_scale_f32_16x16x128_f8f6f4 v[98:101], v[10:17], v[202:209], v[98:101], v236, v236 op_sel_hi:[0,0,0]
	s_setprio 0
	s_barrier
	s_add_i32 s28, s28, s24
	v_lshl_add_u64 v[168:169], vcc, 0, v[0:1]
	s_mov_b32 m0, s28
	ds_read_b128 v[180:183], v179 offset:16384
	ds_read_b128 v[184:187], v179 offset:17408
	ds_read_b128 v[188:191], v179 offset:18432
	ds_read_b128 v[192:195], v179 offset:19456
	ds_read_b128 v[202:205], v179 offset:20480
	ds_read_b128 v[206:209], v179 offset:21504
	ds_read_b128 v[210:213], v179 offset:22528
	ds_read_b128 v[214:217], v179 offset:23552
	global_load_lds_dwordx4 v[168:169], off
	s_add_i32 m0, s28, 0x2000
	s_add_u32 s30, vcc_lo, 0x40000
	v_lshl_add_u64 v[170:171], vcc, 0, v[162:163]
	s_addc_u32 s31, vcc_hi, 0
	s_add_i32 s28, s29, s24
	global_load_lds_dwordx4 v[170:171], off
	v_lshl_add_u64 v[172:173], s[30:31], 0, v[0:1]
	s_mov_b32 m0, s28
	v_lshl_add_u64 v[174:175], s[52:53], 0, v[162:163]
	global_load_lds_dwordx4 v[172:173], off
	v_lshl_add_u64 v[172:173], s[30:31], 0, v[162:163]
	s_add_i32 m0, s28, 0x2000
	s_nop 0
	global_load_lds_dwordx4 v[172:173], off
	v_lshl_add_u64 v[172:173], s[52:53], 0, v[0:1]
	s_mov_b32 m0, s15
	s_nop 0
	global_load_lds_dwordx4 v[172:173], off
	s_mov_b32 m0, s26
	s_nop 0
	global_load_lds_dwordx4 v[174:175], off
	s_waitcnt vmcnt(8)
	s_waitcnt lgkmcnt(0)
	s_barrier
	s_setprio 1
	s_waitcnt lgkmcnt(0)
	v_mfma_scale_f32_16x16x128_f8f6f4 v[94:97], v[18:25], v[180:187], v[94:97], v236, v236 op_sel_hi:[0,0,0]
	v_mfma_scale_f32_16x16x128_f8f6f4 v[90:93], v[26:33], v[180:187], v[90:93], v236, v236 op_sel_hi:[0,0,0]
	v_mfma_scale_f32_16x16x128_f8f6f4 v[86:89], v[18:25], v[188:195], v[86:89], v236, v236 op_sel_hi:[0,0,0]
	v_mfma_scale_f32_16x16x128_f8f6f4 v[78:81], v[26:33], v[188:195], v[78:81], v236, v236 op_sel_hi:[0,0,0]
	v_mfma_scale_f32_16x16x128_f8f6f4 v[70:73], v[18:25], v[202:209], v[70:73], v236, v236 op_sel_hi:[0,0,0]
	v_mfma_scale_f32_16x16x128_f8f6f4 v[62:65], v[26:33], v[202:209], v[62:65], v236, v236 op_sel_hi:[0,0,0]
	v_mfma_scale_f32_16x16x128_f8f6f4 v[54:57], v[18:25], v[210:217], v[54:57], v236, v236 op_sel_hi:[0,0,0]
	v_mfma_scale_f32_16x16x128_f8f6f4 v[46:49], v[26:33], v[210:217], v[46:49], v236, v236 op_sel_hi:[0,0,0]
	s_setprio 0
	s_setprio 1
	v_mfma_scale_f32_16x16x128_f8f6f4 v[82:85], v[2:9], v[180:187], v[82:85], v236, v236 op_sel_hi:[0,0,0]
	v_mfma_scale_f32_16x16x128_f8f6f4 v[74:77], v[10:17], v[180:187], v[74:77], v236, v236 op_sel_hi:[0,0,0]
	v_mfma_scale_f32_16x16x128_f8f6f4 v[66:69], v[2:9], v[188:195], v[66:69], v236, v236 op_sel_hi:[0,0,0]
	v_mfma_scale_f32_16x16x128_f8f6f4 v[58:61], v[10:17], v[188:195], v[58:61], v236, v236 op_sel_hi:[0,0,0]
	v_mfma_scale_f32_16x16x128_f8f6f4 v[50:53], v[2:9], v[202:209], v[50:53], v236, v236 op_sel_hi:[0,0,0]
	v_mfma_scale_f32_16x16x128_f8f6f4 v[42:45], v[10:17], v[202:209], v[42:45], v236, v236 op_sel_hi:[0,0,0]
	v_mfma_scale_f32_16x16x128_f8f6f4 v[38:41], v[2:9], v[210:217], v[38:41], v236, v236 op_sel_hi:[0,0,0]
	v_mfma_scale_f32_16x16x128_f8f6f4 v[34:37], v[10:17], v[210:217], v[34:37], v236, v236 op_sel_hi:[0,0,0]
	s_setprio 0
	s_barrier
; #define PG8_STAGE(bufoff, gbase, voff) do { _Pragma("unroll") for (int _i = 0; _i < 2; ++_i) \
;         __builtin_amdgcn_global_load_lds((const unsigned*)((const char*)(gbase) + (voff)[_i]), (LAS unsigned*)(lds + (bufoff) + ldsw + _i * 8192), 16, 0, 0); } while (0)
; #define PG8_WAIT_V(n) asm volatile("s_waitcnt vmcnt(" #n ")" ::: "memory")
; #define PG8_WAIT_L(n) asm volatile("s_waitcnt lgkmcnt(" #n ")" ::: "memory")
; #define PG8_BAR __builtin_amdgcn_s_barrier()
; #define PG8_SCHED __builtin_amdgcn_sched_barrier(0)
; template <bool F8 = false, class Epi, class Sched>
; __device__ __forceinline__ void gemm_phase(LAS unsigned char* lds, const int lda, const int ldb, const int K, const Sched& S, const Epi& E) {
;     ...
;             PG8_LDB(B0, 1, 0); PG8_LDB(B1, 1, 1); PG8_SCHED; PG8_LDA(At, 1, 0); PG8_STAGE(PG8_SA(0, 1), a2 + hstepA, voffA);
;             PG8_WAIT_V(8); PG8_WAIT_L(0); PG8_BAR; PG8_MMA(0, 0, At, B0); PG8_MMA(0, 1, At, B1); PG8_BAR; PG8_SCHED;
;             PG8_LDA(At, 1, 1); PG8_STAGE(PG8_SB(1, 0), b3, voffB); PG8_STAGE(PG8_SB(1, 1), b3 + hstepB, voffB); PG8_STAGE(PG8_SA(1, 0), a3, voffA);
;             PG8_WAIT_V(8); PG8_WAIT_L(0); PG8_BAR; PG8_MMA(1, 0, At, B0); PG8_MMA(1, 1, At, B1); PG8_BAR; PG8_SCHED;
;         }
	s_add_i32 s30, 0, 0x18000
	s_add_i32 s31, 0, 0x1c000
	v_add_u32_e32 v14, s30, v177
	v_add_u32_e32 v30, s31, v177
	ds_read_b128 v[2:5], v14
	ds_read_b128 v[6:9], v14 offset:1024
	ds_read_b128 v[10:13], v14 offset:2048
	ds_read_b128 v[14:17], v14 offset:3072
	ds_read_b128 v[18:21], v30
	ds_read_b128 v[22:25], v30 offset:1024
	ds_read_b128 v[26:29], v30 offset:2048
	ds_read_b128 v[30:33], v30 offset:3072
	s_add_u32 s28, s52, 0x40000
	s_addc_u32 s29, s53, 0
	s_mov_b32 m0, s27
	v_lshl_add_u64 v[218:219], s[28:29], 0, v[0:1]
	ds_read_b128 v[180:183], v179 offset:32768
	ds_read_b128 v[184:187], v179 offset:33792
	ds_read_b128 v[188:191], v179 offset:34816
	ds_read_b128 v[192:195], v179 offset:35840
	ds_read_b128 v[202:205], v179 offset:36864
	ds_read_b128 v[206:209], v179 offset:37888
	ds_read_b128 v[210:213], v179 offset:38912
	ds_read_b128 v[214:217], v179 offset:39936
	global_load_lds_dwordx4 v[218:219], off
	v_lshl_add_u64 v[218:219], s[28:29], 0, v[162:163]
	s_mov_b32 m0, s56
	s_nop 0
	global_load_lds_dwordx4 v[218:219], off
	s_waitcnt vmcnt(8)
	s_waitcnt lgkmcnt(0)
	s_barrier
	s_setprio 1
	s_waitcnt lgkmcnt(0)
	v_mfma_scale_f32_16x16x128_f8f6f4 v[158:161], v[2:9], v[180:187], v[158:161], v236, v236 op_sel_hi:[0,0,0]
	v_mfma_scale_f32_16x16x128_f8f6f4 v[154:157], v[10:17], v[180:187], v[154:157], v236, v236 op_sel_hi:[0,0,0]
	v_mfma_scale_f32_16x16x128_f8f6f4 v[150:153], v[2:9], v[188:195], v[150:153], v236, v236 op_sel_hi:[0,0,0]
	v_mfma_scale_f32_16x16x128_f8f6f4 v[142:145], v[10:17], v[188:195], v[142:145], v236, v236 op_sel_hi:[0,0,0]
	v_mfma_scale_f32_16x16x128_f8f6f4 v[134:137], v[2:9], v[202:209], v[134:137], v236, v236 op_sel_hi:[0,0,0]
	v_mfma_scale_f32_16x16x128_f8f6f4 v[126:129], v[10:17], v[202:209], v[126:129], v236, v236 op_sel_hi:[0,0,0]
	v_mfma_scale_f32_16x16x128_f8f6f4 v[118:121], v[2:9], v[210:217], v[118:121], v236, v236 op_sel_hi:[0,0,0]
	v_mfma_scale_f32_16x16x128_f8f6f4 v[110:113], v[10:17], v[210:217], v[110:113], v236, v236 op_sel_hi:[0,0,0]
	s_setprio 0
	s_setprio 1
	v_mfma_scale_f32_16x16x128_f8f6f4 v[146:149], v[18:25], v[180:187], v[146:149], v236, v236 op_sel_hi:[0,0,0]
	v_mfma_scale_f32_16x16x128_f8f6f4 v[138:141], v[26:33], v[180:187], v[138:141], v236, v236 op_sel_hi:[0,0,0]
	v_mfma_scale_f32_16x16x128_f8f6f4 v[130:133], v[18:25], v[188:195], v[130:133], v236, v236 op_sel_hi:[0,0,0]
	v_mfma_scale_f32_16x16x128_f8f6f4 v[122:125], v[26:33], v[188:195], v[122:125], v236, v236 op_sel_hi:[0,0,0]
	v_mfma_scale_f32_16x16x128_f8f6f4 v[114:117], v[18:25], v[202:209], v[114:117], v236, v236 op_sel_hi:[0,0,0]
	v_mfma_scale_f32_16x16x128_f8f6f4 v[106:109], v[26:33], v[202:209], v[106:109], v236, v236 op_sel_hi:[0,0,0]
	v_mfma_scale_f32_16x16x128_f8f6f4 v[102:105], v[18:25], v[210:217], v[102:105], v236, v236 op_sel_hi:[0,0,0]
	v_mfma_scale_f32_16x16x128_f8f6f4 v[98:101], v[26:33], v[210:217], v[98:101], v236, v236 op_sel_hi:[0,0,0]
	s_setprio 0
	s_barrier
	s_add_i32 s28, s30, s24
	v_lshl_add_u64 v[168:169], v[168:169], 0, s[40:41]
	s_mov_b32 m0, s28
	ds_read_b128 v[180:183], v179 offset:49152
	ds_read_b128 v[184:187], v179 offset:50176
	ds_read_b128 v[188:191], v179 offset:51200
	ds_read_b128 v[192:195], v179 offset:52224
	ds_read_b128 v[202:205], v179 offset:53248
	ds_read_b128 v[206:209], v179 offset:54272
	ds_read_b128 v[210:213], v179 offset:55296
	ds_read_b128 v[214:217], v179 offset:56320
	global_load_lds_dwordx4 v[168:169], off
	s_add_i32 m0, s28, 0x2000
	s_add_u32 s28, vcc_lo, 0x40080
	v_lshl_add_u64 v[168:169], v[170:171], 0, s[40:41]
	s_addc_u32 s29, vcc_hi, 0
	s_add_i32 s30, s31, s24
	global_load_lds_dwordx4 v[168:169], off
	v_lshl_add_u64 v[168:169], s[28:29], 0, v[0:1]
	s_mov_b32 m0, s30
	s_nop 0
	global_load_lds_dwordx4 v[168:169], off
	v_lshl_add_u64 v[168:169], s[28:29], 0, v[162:163]
	s_add_i32 m0, s30, 0x2000
	s_nop 0
	global_load_lds_dwordx4 v[168:169], off
	v_lshl_add_u64 v[168:169], v[172:173], 0, s[40:41]
	s_mov_b32 m0, s57
	s_nop 0
	global_load_lds_dwordx4 v[168:169], off
	v_lshl_add_u64 v[168:169], v[174:175], 0, s[40:41]
	s_mov_b32 m0, s94
	s_nop 0
	global_load_lds_dwordx4 v[168:169], off
	s_waitcnt vmcnt(8)
	s_waitcnt lgkmcnt(0)
	s_barrier
	s_setprio 1
	s_waitcnt lgkmcnt(0)
	v_mfma_scale_f32_16x16x128_f8f6f4 v[94:97], v[2:9], v[180:187], v[94:97], v236, v236 op_sel_hi:[0,0,0]
	v_mfma_scale_f32_16x16x128_f8f6f4 v[90:93], v[10:17], v[180:187], v[90:93], v236, v236 op_sel_hi:[0,0,0]
	v_mfma_scale_f32_16x16x128_f8f6f4 v[86:89], v[2:9], v[188:195], v[86:89], v236, v236 op_sel_hi:[0,0,0]
	v_mfma_scale_f32_16x16x128_f8f6f4 v[78:81], v[10:17], v[188:195], v[78:81], v236, v236 op_sel_hi:[0,0,0]
	v_mfma_scale_f32_16x16x128_f8f6f4 v[70:73], v[2:9], v[202:209], v[70:73], v236, v236 op_sel_hi:[0,0,0]
	v_mfma_scale_f32_16x16x128_f8f6f4 v[62:65], v[10:17], v[202:209], v[62:65], v236, v236 op_sel_hi:[0,0,0]
	v_mfma_scale_f32_16x16x128_f8f6f4 v[54:57], v[2:9], v[210:217], v[54:57], v236, v236 op_sel_hi:[0,0,0]
	v_mfma_scale_f32_16x16x128_f8f6f4 v[46:49], v[10:17], v[210:217], v[46:49], v236, v236 op_sel_hi:[0,0,0]
	s_setprio 0
	s_setprio 1
	v_mfma_scale_f32_16x16x128_f8f6f4 v[82:85], v[18:25], v[180:187], v[82:85], v236, v236 op_sel_hi:[0,0,0]
	v_mfma_scale_f32_16x16x128_f8f6f4 v[74:77], v[26:33], v[180:187], v[74:77], v236, v236 op_sel_hi:[0,0,0]
	v_mfma_scale_f32_16x16x128_f8f6f4 v[66:69], v[18:25], v[188:195], v[66:69], v236, v236 op_sel_hi:[0,0,0]
	v_mfma_scale_f32_16x16x128_f8f6f4 v[58:61], v[26:33], v[188:195], v[58:61], v236, v236 op_sel_hi:[0,0,0]
	v_mfma_scale_f32_16x16x128_f8f6f4 v[50:53], v[18:25], v[202:209], v[50:53], v236, v236 op_sel_hi:[0,0,0]
	v_mfma_scale_f32_16x16x128_f8f6f4 v[42:45], v[26:33], v[202:209], v[42:45], v236, v236 op_sel_hi:[0,0,0]
	v_mfma_scale_f32_16x16x128_f8f6f4 v[38:41], v[18:25], v[210:217], v[38:41], v236, v236 op_sel_hi:[0,0,0]
	v_mfma_scale_f32_16x16x128_f8f6f4 v[34:37], v[26:33], v[210:217], v[34:37], v236, v236 op_sel_hi:[0,0,0]
	s_add_i32 s97, s97, 2
	s_add_u32 s72, s72, 0x100
	s_addc_u32 s73, s73, 0
	s_add_u32 s18, s18, 0x100
	s_addc_u32 s19, s19, 0
	s_cmp_gt_u32 s97, 13
	s_setprio 0
	s_barrier
	s_cbranch_scc0 .LBB0_292
	s_and_b64 vcc, exec, s[6:7]
	v_readlane_b32 s97, v249, 23
	s_cbranch_vccz .LBB0_295
	s_barrier

; #define PG8_STAGE(bufoff, gbase, voff) do { _Pragma("unroll") for (int _i = 0; _i < 2; ++_i) \
;         __builtin_amdgcn_global_load_lds((const unsigned*)((const char*)(gbase) + (voff)[_i]), (LAS unsigned*)(lds + (bufoff) + ldsw + _i * 8192), 16, 0, 0); } while (0)
; #define PG8_WAIT_V(n) asm volatile("s_waitcnt vmcnt(" #n ")" ::: "memory")
; #define PG8_WAIT_L(n) asm volatile("s_waitcnt lgkmcnt(" #n ")" ::: "memory")
; #define PG8_BAR __builtin_amdgcn_s_barrier()
; #define PG8_SCHED __builtin_amdgcn_sched_barrier(0)
; template <bool F8 = false, class Epi, class Sched>
; __device__ __forceinline__ void gemm_phase(LAS unsigned char* lds, const int lda, const int ldb, const int K, const Sched& S, const Epi& E) {
;     ...
;         for (int t = 0; t < nt; t += 2) {
;             const bool last = (t == nt - 2);
;             const char* a1 = cA + (size_t)(t + 1) * kstep;
;             const char* a2 = last ? nA : cA + (size_t)(t + 2) * kstep; const char* b2 = last ? nB : cB + (size_t)(t + 2) * kstep;
;             const char* a3 = a2 + kstep; const char* b3 = b2 + kstep;
;             PG8_LDB(B0, 0, 0); PG8_LDB(B1, 0, 1); PG8_SCHED; PG8_LDA(At, 0, 0); PG8_STAGE(PG8_SA(1, 1), a1 + hstepA, voffA);
;             PG8_WAIT_V(8); PG8_WAIT_L(0); PG8_BAR; PG8_MMA(0, 0, At, B0); PG8_MMA(0, 1, At, B1); PG8_BAR; PG8_SCHED;
.LBB0_436:
	s_add_u32 s20, s18, 0x100
	s_addc_u32 s21, s19, 0
	s_add_i32 s30, 0, 0x10000
	s_cmp_eq_u32 s29, 4
	s_cselect_b32 s73, s15, s21
	s_cselect_b32 s72, s14, s20
	v_add_u32_e32 v140, s30, v143
	s_cselect_b32 s53, s17, s28
	s_cselect_b32 s52, s16, s11
	s_add_i32 s31, 0, 0x14000
	ds_read_b128 v[146:149], v140
	ds_read_b128 v[150:153], v140 offset:1024
	ds_read_b128 v[154:157], v140 offset:2048
	ds_read_b128 v[158:161], v140 offset:3072
	v_add_u32_e32 v140, s31, v143
	ds_read_b128 v[162:165], v140
	ds_read_b128 v[166:169], v140 offset:1024
	ds_read_b128 v[170:173], v140 offset:2048
	ds_read_b128 v[174:177], v140 offset:3072
	v_lshl_add_u64 v[140:141], s[18:19], 0, v[136:137]
	s_add_i32 m0, s13, 0xc000
	ds_read_b128 v[178:181], v145
	ds_read_b128 v[182:185], v145 offset:1024
	ds_read_b128 v[186:189], v145 offset:2048
	ds_read_b128 v[190:193], v145 offset:3072
	ds_read_b128 v[202:205], v145 offset:4096
	ds_read_b128 v[206:209], v145 offset:5120
	ds_read_b128 v[210:213], v145 offset:6144
	ds_read_b128 v[214:217], v145 offset:7168
	global_load_lds_dwordx4 v[140:141], off
	v_lshl_add_u64 v[140:141], s[18:19], 0, v[138:139]
	s_add_i32 m0, s13, 0xe000
	s_nop 0
	global_load_lds_dwordx4 v[140:141], off
	s_waitcnt vmcnt(8)
	s_waitcnt lgkmcnt(0)
	s_barrier
	s_setprio 1
	s_waitcnt lgkmcnt(0)
	v_mfma_f32_16x16x32_bf16 v[126:129], v[146:149], v[178:181], v[126:129]
	v_mfma_f32_16x16x32_bf16 v[122:125], v[154:157], v[178:181], v[122:125]
	v_mfma_f32_16x16x32_bf16 v[118:121], v[146:149], v[186:189], v[118:121]
	v_mfma_f32_16x16x32_bf16 v[110:113], v[154:157], v[186:189], v[110:113]
	v_mfma_f32_16x16x32_bf16 v[102:105], v[146:149], v[202:205], v[102:105]
	v_mfma_f32_16x16x32_bf16 v[94:97], v[154:157], v[202:205], v[94:97]
	v_mfma_f32_16x16x32_bf16 v[86:89], v[146:149], v[210:213], v[86:89]
	v_mfma_f32_16x16x32_bf16 v[78:81], v[154:157], v[210:213], v[78:81]
	v_mfma_f32_16x16x32_bf16 v[126:129], v[150:153], v[182:185], v[126:129]
	v_mfma_f32_16x16x32_bf16 v[122:125], v[158:161], v[182:185], v[122:125]
	v_mfma_f32_16x16x32_bf16 v[118:121], v[150:153], v[190:193], v[118:121]
	v_mfma_f32_16x16x32_bf16 v[110:113], v[158:161], v[190:193], v[110:113]
	v_mfma_f32_16x16x32_bf16 v[102:105], v[150:153], v[206:209], v[102:105]
	v_mfma_f32_16x16x32_bf16 v[94:97], v[158:161], v[206:209], v[94:97]
	v_mfma_f32_16x16x32_bf16 v[86:89], v[150:153], v[214:217], v[86:89]
	v_mfma_f32_16x16x32_bf16 v[78:81], v[158:161], v[214:217], v[78:81]
	s_setprio 0
	s_setprio 1
	v_mfma_f32_16x16x32_bf16 v[114:117], v[162:165], v[178:181], v[114:117]
	v_mfma_f32_16x16x32_bf16 v[106:109], v[170:173], v[178:181], v[106:109]
	v_mfma_f32_16x16x32_bf16 v[98:101], v[162:165], v[186:189], v[98:101]
	v_mfma_f32_16x16x32_bf16 v[90:93], v[170:173], v[186:189], v[90:93]
	v_mfma_f32_16x16x32_bf16 v[82:85], v[162:165], v[202:205], v[82:85]
	v_mfma_f32_16x16x32_bf16 v[74:77], v[170:173], v[202:205], v[74:77]
	v_mfma_f32_16x16x32_bf16 v[70:73], v[162:165], v[210:213], v[70:73]
	v_mfma_f32_16x16x32_bf16 v[66:69], v[170:173], v[210:213], v[66:69]
	v_mfma_f32_16x16x32_bf16 v[114:117], v[166:169], v[182:185], v[114:117]
	v_mfma_f32_16x16x32_bf16 v[106:109], v[174:177], v[182:185], v[106:109]
	v_mfma_f32_16x16x32_bf16 v[98:101], v[166:169], v[190:193], v[98:101]
	v_mfma_f32_16x16x32_bf16 v[90:93], v[174:177], v[190:193], v[90:93]
	v_mfma_f32_16x16x32_bf16 v[82:85], v[166:169], v[206:209], v[82:85]
	v_mfma_f32_16x16x32_bf16 v[74:77], v[174:177], v[206:209], v[74:77]
	v_mfma_f32_16x16x32_bf16 v[70:73], v[166:169], v[214:217], v[70:73]
	v_mfma_f32_16x16x32_bf16 v[66:69], v[174:177], v[214:217], v[66:69]
	s_setprio 0
	s_barrier
	s_add_i32 s18, s30, s24
	v_lshl_add_u64 v[140:141], s[52:53], 0, v[0:1]
	s_mov_b32 m0, s18
	ds_read_b128 v[178:181], v145 offset:16384
	ds_read_b128 v[182:185], v145 offset:17408
	ds_read_b128 v[186:189], v145 offset:18432
	ds_read_b128 v[190:193], v145 offset:19456
	ds_read_b128 v[202:205], v145 offset:20480
	ds_read_b128 v[206:209], v145 offset:21504
	ds_read_b128 v[210:213], v145 offset:22528
	ds_read_b128 v[214:217], v145 offset:23552
	global_load_lds_dwordx4 v[140:141], off
	s_add_i32 m0, s18, 0x2000
	s_add_u32 s18, s52, 0x20000
	v_lshl_add_u64 v[194:195], s[52:53], 0, v[134:135]
	s_addc_u32 s19, s53, 0
	s_add_i32 s30, s31, s24
	global_load_lds_dwordx4 v[194:195], off
	v_lshl_add_u64 v[218:219], s[18:19], 0, v[0:1]
	s_mov_b32 m0, s30
	v_lshl_add_u64 v[220:221], s[72:73], 0, v[132:133]
	global_load_lds_dwordx4 v[218:219], off
	v_lshl_add_u64 v[218:219], s[18:19], 0, v[134:135]
	s_add_i32 m0, s30, 0x2000
	s_nop 0
	global_load_lds_dwordx4 v[218:219], off
	v_lshl_add_u64 v[218:219], s[72:73], 0, v[130:131]
	s_mov_b32 m0, s13
	s_nop 0
	global_load_lds_dwordx4 v[218:219], off
	s_mov_b32 m0, s25
	s_nop 0
	global_load_lds_dwordx4 v[220:221], off
	s_waitcnt vmcnt(8)
	s_waitcnt lgkmcnt(0)
	s_barrier
; #define PG8_STAGE(bufoff, gbase, voff) do { _Pragma("unroll") for (int _i = 0; _i < 2; ++_i) \
;         __builtin_amdgcn_global_load_lds((const unsigned*)((const char*)(gbase) + (voff)[_i]), (LAS unsigned*)(lds + (bufoff) + ldsw + _i * 8192), 16, 0, 0); } while (0)
; #define PG8_WAIT_V(n) asm volatile("s_waitcnt vmcnt(" #n ")" ::: "memory")
; #define PG8_WAIT_L(n) asm volatile("s_waitcnt lgkmcnt(" #n ")" ::: "memory")
; #define PG8_BAR __builtin_amdgcn_s_barrier()
; #define PG8_SCHED __builtin_amdgcn_sched_barrier(0)
; template <bool F8 = false, class Epi, class Sched>
; __device__ __forceinline__ void gemm_phase(LAS unsigned char* lds, const int lda, const int ldb, const int K, const Sched& S, const Epi& E) {
;     ...
;             PG8_WAIT_V(8); PG8_WAIT_L(0); PG8_BAR; PG8_MMA(0, 0, At, B0); PG8_MMA(0, 1, At, B1); PG8_BAR; PG8_SCHED;
;             PG8_LDA(At, 0, 1); PG8_STAGE(PG8_SB(0, 0), b2, voffB); PG8_STAGE(PG8_SB(0, 1), b2 + hstepB, voffB); PG8_STAGE(PG8_SA(0, 0), a2, voffA);
;             PG8_WAIT_V(8); PG8_WAIT_L(0); PG8_BAR; PG8_MMA(1, 0, At, B0); PG8_MMA(1, 1, At, B1); PG8_BAR; PG8_SCHED;
;             PG8_LDB(B0, 1, 0); PG8_LDB(B1, 1, 1); PG8_SCHED; PG8_LDA(At, 1, 0); PG8_STAGE(PG8_SA(0, 1), a2 + hstepA, voffA);
;             PG8_WAIT_V(8); PG8_WAIT_L(0); PG8_BAR; PG8_MMA(0, 0, At, B0); PG8_MMA(0, 1, At, B1); PG8_BAR; PG8_SCHED;
	s_setprio 1
	s_waitcnt lgkmcnt(0)
	v_mfma_f32_16x16x32_bf16 v[62:65], v[146:149], v[178:181], v[62:65]
	v_mfma_f32_16x16x32_bf16 v[58:61], v[154:157], v[178:181], v[58:61]
	v_mfma_f32_16x16x32_bf16 v[54:57], v[146:149], v[186:189], v[54:57]
	v_mfma_f32_16x16x32_bf16 v[46:49], v[154:157], v[186:189], v[46:49]
	v_mfma_f32_16x16x32_bf16 v[38:41], v[146:149], v[202:205], v[38:41]
	v_mfma_f32_16x16x32_bf16 v[30:33], v[154:157], v[202:205], v[30:33]
	v_mfma_f32_16x16x32_bf16 v[22:25], v[146:149], v[210:213], v[22:25]
	v_mfma_f32_16x16x32_bf16 v[14:17], v[154:157], v[210:213], v[14:17]
	v_mfma_f32_16x16x32_bf16 v[62:65], v[150:153], v[182:185], v[62:65]
	v_mfma_f32_16x16x32_bf16 v[58:61], v[158:161], v[182:185], v[58:61]
	v_mfma_f32_16x16x32_bf16 v[54:57], v[150:153], v[190:193], v[54:57]
	v_mfma_f32_16x16x32_bf16 v[46:49], v[158:161], v[190:193], v[46:49]
	v_mfma_f32_16x16x32_bf16 v[38:41], v[150:153], v[206:209], v[38:41]
	v_mfma_f32_16x16x32_bf16 v[30:33], v[158:161], v[206:209], v[30:33]
	v_mfma_f32_16x16x32_bf16 v[22:25], v[150:153], v[214:217], v[22:25]
	v_mfma_f32_16x16x32_bf16 v[14:17], v[158:161], v[214:217], v[14:17]
	s_setprio 0
	s_setprio 1
	v_mfma_f32_16x16x32_bf16 v[50:53], v[162:165], v[178:181], v[50:53]
	v_mfma_f32_16x16x32_bf16 v[42:45], v[170:173], v[178:181], v[42:45]
	v_mfma_f32_16x16x32_bf16 v[34:37], v[162:165], v[186:189], v[34:37]
	v_mfma_f32_16x16x32_bf16 v[26:29], v[170:173], v[186:189], v[26:29]
	v_mfma_f32_16x16x32_bf16 v[18:21], v[162:165], v[202:205], v[18:21]
	v_mfma_f32_16x16x32_bf16 v[10:13], v[170:173], v[202:205], v[10:13]
	v_mfma_f32_16x16x32_bf16 v[6:9], v[162:165], v[210:213], v[6:9]
	v_mfma_f32_16x16x32_bf16 v[2:5], v[170:173], v[210:213], v[2:5]
	v_mfma_f32_16x16x32_bf16 v[50:53], v[166:169], v[182:185], v[50:53]
	v_mfma_f32_16x16x32_bf16 v[42:45], v[174:177], v[182:185], v[42:45]
	v_mfma_f32_16x16x32_bf16 v[34:37], v[166:169], v[190:193], v[34:37]
	v_mfma_f32_16x16x32_bf16 v[26:29], v[174:177], v[190:193], v[26:29]
	v_mfma_f32_16x16x32_bf16 v[18:21], v[166:169], v[206:209], v[18:21]
	v_mfma_f32_16x16x32_bf16 v[10:13], v[174:177], v[206:209], v[10:13]
	v_mfma_f32_16x16x32_bf16 v[6:9], v[166:169], v[214:217], v[6:9]
	v_mfma_f32_16x16x32_bf16 v[2:5], v[174:177], v[214:217], v[2:5]
	s_setprio 0
	s_barrier
	s_add_i32 s30, 0, 0x18000
	s_add_i32 s31, 0, 0x1c000
	v_add_u32_e32 v158, s30, v143
	v_add_u32_e32 v174, s31, v143
	ds_read_b128 v[146:149], v158
	ds_read_b128 v[150:153], v158 offset:1024
	ds_read_b128 v[154:157], v158 offset:2048
	ds_read_b128 v[158:161], v158 offset:3072
	ds_read_b128 v[162:165], v174
	ds_read_b128 v[166:169], v174 offset:1024
	ds_read_b128 v[170:173], v174 offset:2048
	ds_read_b128 v[174:177], v174 offset:3072
	s_add_u32 s18, s72, 0x2e4000
	s_addc_u32 s19, s73, 0
	s_mov_b32 m0, s26
	v_lshl_add_u64 v[222:223], s[18:19], 0, v[130:131]
	ds_read_b128 v[178:181], v145 offset:32768
	ds_read_b128 v[182:185], v145 offset:33792
	ds_read_b128 v[186:189], v145 offset:34816
	ds_read_b128 v[190:193], v145 offset:35840
	ds_read_b128 v[202:205], v145 offset:36864
	ds_read_b128 v[206:209], v145 offset:37888
	ds_read_b128 v[210:213], v145 offset:38912
	ds_read_b128 v[214:217], v145 offset:39936
	global_load_lds_dwordx4 v[222:223], off
	v_lshl_add_u64 v[222:223], s[18:19], 0, v[132:133]
	s_mov_b32 m0, s27
	s_nop 0
	global_load_lds_dwordx4 v[222:223], off
	s_waitcnt vmcnt(8)
	s_waitcnt lgkmcnt(0)
	s_barrier
	s_setprio 1
	s_waitcnt lgkmcnt(0)
	v_mfma_f32_16x16x32_bf16 v[126:129], v[146:149], v[178:181], v[126:129]
	v_mfma_f32_16x16x32_bf16 v[122:125], v[154:157], v[178:181], v[122:125]
	v_mfma_f32_16x16x32_bf16 v[118:121], v[146:149], v[186:189], v[118:121]
	v_mfma_f32_16x16x32_bf16 v[110:113], v[154:157], v[186:189], v[110:113]
	v_mfma_f32_16x16x32_bf16 v[102:105], v[146:149], v[202:205], v[102:105]
	v_mfma_f32_16x16x32_bf16 v[94:97], v[154:157], v[202:205], v[94:97]
	v_mfma_f32_16x16x32_bf16 v[86:89], v[146:149], v[210:213], v[86:89]
	v_mfma_f32_16x16x32_bf16 v[78:81], v[154:157], v[210:213], v[78:81]
	v_mfma_f32_16x16x32_bf16 v[126:129], v[150:153], v[182:185], v[126:129]
	v_mfma_f32_16x16x32_bf16 v[122:125], v[158:161], v[182:185], v[122:125]
	v_mfma_f32_16x16x32_bf16 v[118:121], v[150:153], v[190:193], v[118:121]
	v_mfma_f32_16x16x32_bf16 v[110:113], v[158:161], v[190:193], v[110:113]
	v_mfma_f32_16x16x32_bf16 v[102:105], v[150:153], v[206:209], v[102:105]
	v_mfma_f32_16x16x32_bf16 v[94:97], v[158:161], v[206:209], v[94:97]
	v_mfma_f32_16x16x32_bf16 v[86:89], v[150:153], v[214:217], v[86:89]
	v_mfma_f32_16x16x32_bf16 v[78:81], v[158:161], v[214:217], v[78:81]
	s_setprio 0
	s_setprio 1
	v_mfma_f32_16x16x32_bf16 v[114:117], v[162:165], v[178:181], v[114:117]
	v_mfma_f32_16x16x32_bf16 v[106:109], v[170:173], v[178:181], v[106:109]
	v_mfma_f32_16x16x32_bf16 v[98:101], v[162:165], v[186:189], v[98:101]
	v_mfma_f32_16x16x32_bf16 v[90:93], v[170:173], v[186:189], v[90:93]
	v_mfma_f32_16x16x32_bf16 v[82:85], v[162:165], v[202:205], v[82:85]
	v_mfma_f32_16x16x32_bf16 v[74:77], v[170:173], v[202:205], v[74:77]
	v_mfma_f32_16x16x32_bf16 v[70:73], v[162:165], v[210:213], v[70:73]
	v_mfma_f32_16x16x32_bf16 v[66:69], v[170:173], v[210:213], v[66:69]
	v_mfma_f32_16x16x32_bf16 v[114:117], v[166:169], v[182:185], v[114:117]
	v_mfma_f32_16x16x32_bf16 v[106:109], v[174:177], v[182:185], v[106:109]
	v_mfma_f32_16x16x32_bf16 v[98:101], v[166:169], v[190:193], v[98:101]
	v_mfma_f32_16x16x32_bf16 v[90:93], v[174:177], v[190:193], v[90:93]
	v_mfma_f32_16x16x32_bf16 v[82:85], v[166:169], v[206:209], v[82:85]
	v_mfma_f32_16x16x32_bf16 v[74:77], v[174:177], v[206:209], v[74:77]
	v_mfma_f32_16x16x32_bf16 v[70:73], v[166:169], v[214:217], v[70:73]
	v_mfma_f32_16x16x32_bf16 v[66:69], v[174:177], v[214:217], v[66:69]
	s_setprio 0
	s_barrier
; #define PG8_STAGE(bufoff, gbase, voff) do { _Pragma("unroll") for (int _i = 0; _i < 2; ++_i) \
;         __builtin_amdgcn_global_load_lds((const unsigned*)((const char*)(gbase) + (voff)[_i]), (LAS unsigned*)(lds + (bufoff) + ldsw + _i * 8192), 16, 0, 0); } while (0)
; #define PG8_WAIT_V(n) asm volatile("s_waitcnt vmcnt(" #n ")" ::: "memory")
; #define PG8_WAIT_L(n) asm volatile("s_waitcnt lgkmcnt(" #n ")" ::: "memory")
; #define PG8_BAR __builtin_amdgcn_s_barrier()
; #define PG8_SCHED __builtin_amdgcn_sched_barrier(0)
; template <bool F8 = false, class Epi, class Sched>
; __device__ __forceinline__ void gemm_phase(LAS unsigned char* lds, const int lda, const int ldb, const int K, const Sched& S, const Epi& E) {
;     ...
;             PG8_LDA(At, 1, 1); PG8_STAGE(PG8_SB(1, 0), b3, voffB); PG8_STAGE(PG8_SB(1, 1), b3 + hstepB, voffB); PG8_STAGE(PG8_SA(1, 0), a3, voffA);
;             PG8_WAIT_V(8); PG8_WAIT_L(0); PG8_BAR; PG8_MMA(1, 0, At, B0); PG8_MMA(1, 1, At, B1); PG8_BAR; PG8_SCHED;
;         }
;         if (wr == 0) PG8_BAR;
	s_add_i32 s18, s30, s24
	v_lshl_add_u64 v[140:141], v[140:141], 0, s[40:41]
	s_mov_b32 m0, s18
	ds_read_b128 v[178:181], v145 offset:49152
	ds_read_b128 v[182:185], v145 offset:50176
	ds_read_b128 v[186:189], v145 offset:51200
	ds_read_b128 v[190:193], v145 offset:52224
	ds_read_b128 v[202:205], v145 offset:53248
	ds_read_b128 v[206:209], v145 offset:54272
	ds_read_b128 v[210:213], v145 offset:55296
	ds_read_b128 v[214:217], v145 offset:56320
	global_load_lds_dwordx4 v[140:141], off
	s_add_i32 m0, s18, 0x2000
	s_add_u32 s18, s52, 0x20080
	v_lshl_add_u64 v[140:141], v[194:195], 0, s[40:41]
	s_addc_u32 s19, s53, 0
	s_add_i32 s30, s31, s24
	global_load_lds_dwordx4 v[140:141], off
	v_lshl_add_u64 v[140:141], s[18:19], 0, v[0:1]
	s_mov_b32 m0, s30
	s_nop 0
	global_load_lds_dwordx4 v[140:141], off
	v_lshl_add_u64 v[140:141], s[18:19], 0, v[134:135]
	s_add_i32 m0, s30, 0x2000
	s_nop 0
	global_load_lds_dwordx4 v[140:141], off
	v_lshl_add_u64 v[140:141], v[218:219], 0, s[40:41]
	s_mov_b32 m0, s44
	s_nop 0
	global_load_lds_dwordx4 v[140:141], off
	v_lshl_add_u64 v[140:141], v[220:221], 0, s[40:41]
	s_mov_b32 m0, s56
	s_nop 0
	global_load_lds_dwordx4 v[140:141], off
	s_waitcnt vmcnt(8)
	s_waitcnt lgkmcnt(0)
	s_barrier
	s_setprio 1
	s_waitcnt lgkmcnt(0)
	v_mfma_f32_16x16x32_bf16 v[62:65], v[146:149], v[178:181], v[62:65]
	v_mfma_f32_16x16x32_bf16 v[58:61], v[154:157], v[178:181], v[58:61]
	v_mfma_f32_16x16x32_bf16 v[54:57], v[146:149], v[186:189], v[54:57]
	v_mfma_f32_16x16x32_bf16 v[46:49], v[154:157], v[186:189], v[46:49]
	v_mfma_f32_16x16x32_bf16 v[38:41], v[146:149], v[202:205], v[38:41]
	v_mfma_f32_16x16x32_bf16 v[30:33], v[154:157], v[202:205], v[30:33]
	v_mfma_f32_16x16x32_bf16 v[22:25], v[146:149], v[210:213], v[22:25]
	v_mfma_f32_16x16x32_bf16 v[14:17], v[154:157], v[210:213], v[14:17]
	v_mfma_f32_16x16x32_bf16 v[62:65], v[150:153], v[182:185], v[62:65]
	v_mfma_f32_16x16x32_bf16 v[58:61], v[158:161], v[182:185], v[58:61]
	v_mfma_f32_16x16x32_bf16 v[54:57], v[150:153], v[190:193], v[54:57]
	v_mfma_f32_16x16x32_bf16 v[46:49], v[158:161], v[190:193], v[46:49]
	v_mfma_f32_16x16x32_bf16 v[38:41], v[150:153], v[206:209], v[38:41]
	v_mfma_f32_16x16x32_bf16 v[30:33], v[158:161], v[206:209], v[30:33]
	v_mfma_f32_16x16x32_bf16 v[22:25], v[150:153], v[214:217], v[22:25]
	v_mfma_f32_16x16x32_bf16 v[14:17], v[158:161], v[214:217], v[14:17]
	s_setprio 0
	s_setprio 1
	v_mfma_f32_16x16x32_bf16 v[50:53], v[162:165], v[178:181], v[50:53]
	v_mfma_f32_16x16x32_bf16 v[42:45], v[170:173], v[178:181], v[42:45]
	v_mfma_f32_16x16x32_bf16 v[34:37], v[162:165], v[186:189], v[34:37]
	v_mfma_f32_16x16x32_bf16 v[26:29], v[170:173], v[186:189], v[26:29]
	v_mfma_f32_16x16x32_bf16 v[18:21], v[162:165], v[202:205], v[18:21]
	v_mfma_f32_16x16x32_bf16 v[10:13], v[170:173], v[202:205], v[10:13]
	v_mfma_f32_16x16x32_bf16 v[6:9], v[162:165], v[210:213], v[6:9]
	v_mfma_f32_16x16x32_bf16 v[2:5], v[170:173], v[210:213], v[2:5]
	v_mfma_f32_16x16x32_bf16 v[50:53], v[166:169], v[182:185], v[50:53]
	v_mfma_f32_16x16x32_bf16 v[42:45], v[174:177], v[182:185], v[42:45]
	v_mfma_f32_16x16x32_bf16 v[34:37], v[166:169], v[190:193], v[34:37]
	v_mfma_f32_16x16x32_bf16 v[26:29], v[174:177], v[190:193], v[26:29]
	v_mfma_f32_16x16x32_bf16 v[18:21], v[166:169], v[206:209], v[18:21]
	v_mfma_f32_16x16x32_bf16 v[10:13], v[174:177], v[206:209], v[10:13]
	v_mfma_f32_16x16x32_bf16 v[6:9], v[166:169], v[214:217], v[6:9]
	v_mfma_f32_16x16x32_bf16 v[2:5], v[174:177], v[214:217], v[2:5]
	s_add_i32 s29, s29, 2
	s_add_u32 s11, s11, 0x100
	s_addc_u32 s28, s28, 0
	s_cmp_gt_u32 s29, 5
	s_mov_b64 s[18:19], s[20:21]
	s_setprio 0
	s_barrier
	s_cbranch_scc0 .LBB0_436
	s_and_b64 vcc, exec, s[8:9]
	s_cbranch_vccz .LBB0_439
	s_barrier

; #define PG8_STAGE(bufoff, gbase, voff) do { _Pragma("unroll") for (int _i = 0; _i < 2; ++_i) \
;         __builtin_amdgcn_global_load_lds((const unsigned*)((const char*)(gbase) + (voff)[_i]), (LAS unsigned*)(lds + (bufoff) + ldsw + _i * 8192), 16, 0, 0); } while (0)
; #define PG8_WAIT_V(n) asm volatile("s_waitcnt vmcnt(" #n ")" ::: "memory")
; #define PG8_WAIT_L(n) asm volatile("s_waitcnt lgkmcnt(" #n ")" ::: "memory")
; #define PG8_BAR __builtin_amdgcn_s_barrier()
; #define PG8_SCHED __builtin_amdgcn_sched_barrier(0)
; template <bool F8 = false, class Epi, class Sched>
; __device__ __forceinline__ void gemm_phase(LAS unsigned char* lds, const int lda, const int ldb, const int K, const Sched& S, const Epi& E) {
;     ...
;             const bool last = (t == nt - 2);
;             const char* a1 = cA + (size_t)(t + 1) * kstep;
;             const char* a2 = last ? nA : cA + (size_t)(t + 2) * kstep; const char* b2 = last ? nB : cB + (size_t)(t + 2) * kstep;
;             const char* a3 = a2 + kstep; const char* b3 = b2 + kstep;
;             PG8_LDB(B0, 0, 0); PG8_LDB(B1, 0, 1); PG8_SCHED; PG8_LDA(At, 0, 0); PG8_STAGE(PG8_SA(1, 1), a1 + hstepA, voffA);
;             PG8_WAIT_V(8); PG8_WAIT_L(0); PG8_BAR; PG8_MMA(0, 0, At, B0); PG8_MMA(0, 1, At, B1); PG8_BAR; PG8_SCHED;
;             PG8_LDA(At, 0, 1); PG8_STAGE(PG8_SB(0, 0), b2, voffB); PG8_STAGE(PG8_SB(0, 1), b2 + hstepB, voffB); PG8_STAGE(PG8_SA(0, 0), a2, voffA);
;             PG8_WAIT_V(8); PG8_WAIT_L(0); PG8_BAR; PG8_MMA(1, 0, At, B0); PG8_MMA(1, 1, At, B1); PG8_BAR; PG8_SCHED;
.LBB0_690:
	s_add_u32 s52, s18, 0x100
	s_addc_u32 s53, s19, 0
	s_add_i32 s29, 0, 0x10000
	s_cmp_eq_u32 s28, 12
	s_cselect_b32 s75, s21, s53
	s_cselect_b32 s74, s20, s52
	s_cselect_b32 s73, s11, s17
	s_cselect_b32 s72, s10, s15
	s_add_i32 s30, 0, 0x14000
	v_add_u32_e32 v142, s29, v245
	v_add_u32_e32 v158, s30, v245
	ds_read_b128 v[130:133], v142
	ds_read_b128 v[134:137], v142 offset:1024
	ds_read_b128 v[138:141], v142 offset:2048
	ds_read_b128 v[142:145], v142 offset:3072
	ds_read_b128 v[146:149], v158
	ds_read_b128 v[150:153], v158 offset:1024
	ds_read_b128 v[154:157], v158 offset:2048
	ds_read_b128 v[158:161], v158 offset:3072
	v_lshl_add_u64 v[194:195], s[18:19], 0, v[208:209]
	s_add_i32 m0, s95, 0xc000
	ds_read_b128 v[162:165], v247
	ds_read_b128 v[166:169], v247 offset:1024
	ds_read_b128 v[170:173], v247 offset:2048
	ds_read_b128 v[174:177], v247 offset:3072
	ds_read_b128 v[178:181], v247 offset:4096
	ds_read_b128 v[182:185], v247 offset:5120
	ds_read_b128 v[186:189], v247 offset:6144
	ds_read_b128 v[190:193], v247 offset:7168
	global_load_lds_dwordx4 v[194:195], off
	v_lshl_add_u64 v[194:195], s[18:19], 0, v[210:211]
	s_add_i32 m0, s95, 0xe000
	s_nop 0
	global_load_lds_dwordx4 v[194:195], off
	s_waitcnt vmcnt(8)
	s_waitcnt lgkmcnt(0)
	s_barrier
	s_setprio 1
	s_waitcnt lgkmcnt(0)
	v_mfma_f32_16x16x32_bf16 v[126:129], v[130:133], v[162:165], v[126:129]
	v_mfma_f32_16x16x32_bf16 v[122:125], v[138:141], v[162:165], v[122:125]
	v_mfma_f32_16x16x32_bf16 v[110:113], v[130:133], v[170:173], v[110:113]
	v_mfma_f32_16x16x32_bf16 v[106:109], v[138:141], v[170:173], v[106:109]
	v_mfma_f32_16x16x32_bf16 v[94:97], v[130:133], v[178:181], v[94:97]
	v_mfma_f32_16x16x32_bf16 v[90:93], v[138:141], v[178:181], v[90:93]
	v_mfma_f32_16x16x32_bf16 v[78:81], v[130:133], v[186:189], v[78:81]
	v_mfma_f32_16x16x32_bf16 v[74:77], v[138:141], v[186:189], v[74:77]
	v_mfma_f32_16x16x32_bf16 v[126:129], v[134:137], v[166:169], v[126:129]
	v_mfma_f32_16x16x32_bf16 v[122:125], v[142:145], v[166:169], v[122:125]
	v_mfma_f32_16x16x32_bf16 v[110:113], v[134:137], v[174:177], v[110:113]
	v_mfma_f32_16x16x32_bf16 v[106:109], v[142:145], v[174:177], v[106:109]
	v_mfma_f32_16x16x32_bf16 v[94:97], v[134:137], v[182:185], v[94:97]
	v_mfma_f32_16x16x32_bf16 v[90:93], v[142:145], v[182:185], v[90:93]
	v_mfma_f32_16x16x32_bf16 v[78:81], v[134:137], v[190:193], v[78:81]
	v_mfma_f32_16x16x32_bf16 v[74:77], v[142:145], v[190:193], v[74:77]
	s_setprio 0
	s_setprio 1
	v_mfma_f32_16x16x32_bf16 v[118:121], v[146:149], v[162:165], v[118:121]
	v_mfma_f32_16x16x32_bf16 v[114:117], v[154:157], v[162:165], v[114:117]
	v_mfma_f32_16x16x32_bf16 v[102:105], v[146:149], v[170:173], v[102:105]
	v_mfma_f32_16x16x32_bf16 v[98:101], v[154:157], v[170:173], v[98:101]
	v_mfma_f32_16x16x32_bf16 v[86:89], v[146:149], v[178:181], v[86:89]
	v_mfma_f32_16x16x32_bf16 v[82:85], v[154:157], v[178:181], v[82:85]
	v_mfma_f32_16x16x32_bf16 v[70:73], v[146:149], v[186:189], v[70:73]
	v_mfma_f32_16x16x32_bf16 v[66:69], v[154:157], v[186:189], v[66:69]
	v_mfma_f32_16x16x32_bf16 v[118:121], v[150:153], v[166:169], v[118:121]
	v_mfma_f32_16x16x32_bf16 v[114:117], v[158:161], v[166:169], v[114:117]
	v_mfma_f32_16x16x32_bf16 v[102:105], v[150:153], v[174:177], v[102:105]
	v_mfma_f32_16x16x32_bf16 v[98:101], v[158:161], v[174:177], v[98:101]
	v_mfma_f32_16x16x32_bf16 v[86:89], v[150:153], v[182:185], v[86:89]
	v_mfma_f32_16x16x32_bf16 v[82:85], v[158:161], v[182:185], v[82:85]
	v_mfma_f32_16x16x32_bf16 v[70:73], v[150:153], v[190:193], v[70:73]
	v_mfma_f32_16x16x32_bf16 v[66:69], v[158:161], v[190:193], v[66:69]
	s_setprio 0
	s_barrier
	s_add_i32 s18, s29, s94
	v_lshl_add_u64 v[194:195], s[72:73], 0, v[0:1]
	s_mov_b32 m0, s18
	ds_read_b128 v[162:165], v247 offset:16384
	ds_read_b128 v[166:169], v247 offset:17408
	ds_read_b128 v[170:173], v247 offset:18432
	ds_read_b128 v[174:177], v247 offset:19456
	ds_read_b128 v[178:181], v247 offset:20480
	ds_read_b128 v[182:185], v247 offset:21504
	ds_read_b128 v[186:189], v247 offset:22528
	ds_read_b128 v[190:193], v247 offset:23552
	global_load_lds_dwordx4 v[194:195], off
	s_add_i32 m0, s18, 0x2000
	s_add_u32 s18, s72, 0x40000
	v_lshl_add_u64 v[212:213], s[72:73], 0, v[206:207]
	s_addc_u32 s19, s73, 0
	s_add_i32 s29, s30, s94
	global_load_lds_dwordx4 v[212:213], off
	v_lshl_add_u64 v[214:215], s[18:19], 0, v[0:1]
	s_mov_b32 m0, s29
	v_lshl_add_u64 v[216:217], s[74:75], 0, v[204:205]
	global_load_lds_dwordx4 v[214:215], off
	v_lshl_add_u64 v[214:215], s[18:19], 0, v[206:207]
	s_add_i32 m0, s29, 0x2000
	s_nop 0
	global_load_lds_dwordx4 v[214:215], off
	v_lshl_add_u64 v[214:215], s[74:75], 0, v[202:203]
	s_mov_b32 m0, s95
	s_nop 0
	global_load_lds_dwordx4 v[214:215], off
	s_mov_b32 m0, s96
	s_nop 0
	global_load_lds_dwordx4 v[216:217], off
	s_waitcnt vmcnt(8)
	s_waitcnt lgkmcnt(0)
	s_barrier
; #define PG8_STAGE(bufoff, gbase, voff) do { _Pragma("unroll") for (int _i = 0; _i < 2; ++_i) \
;         __builtin_amdgcn_global_load_lds((const unsigned*)((const char*)(gbase) + (voff)[_i]), (LAS unsigned*)(lds + (bufoff) + ldsw + _i * 8192), 16, 0, 0); } while (0)
; #define PG8_WAIT_V(n) asm volatile("s_waitcnt vmcnt(" #n ")" ::: "memory")
; #define PG8_WAIT_L(n) asm volatile("s_waitcnt lgkmcnt(" #n ")" ::: "memory")
; #define PG8_BAR __builtin_amdgcn_s_barrier()
; #define PG8_SCHED __builtin_amdgcn_sched_barrier(0)
; template <bool F8 = false, class Epi, class Sched>
; __device__ __forceinline__ void gemm_phase(LAS unsigned char* lds, const int lda, const int ldb, const int K, const Sched& S, const Epi& E) {
;     ...
;             PG8_WAIT_V(8); PG8_WAIT_L(0); PG8_BAR; PG8_MMA(1, 0, At, B0); PG8_MMA(1, 1, At, B1); PG8_BAR; PG8_SCHED;
;             PG8_LDB(B0, 1, 0); PG8_LDB(B1, 1, 1); PG8_SCHED; PG8_LDA(At, 1, 0); PG8_STAGE(PG8_SA(0, 1), a2 + hstepA, voffA);
;             PG8_WAIT_V(8); PG8_WAIT_L(0); PG8_BAR; PG8_MMA(0, 0, At, B0); PG8_MMA(0, 1, At, B1); PG8_BAR; PG8_SCHED;
	s_setprio 1
	s_waitcnt lgkmcnt(0)
	v_mfma_f32_16x16x32_bf16 v[62:65], v[130:133], v[162:165], v[62:65]
	v_mfma_f32_16x16x32_bf16 v[58:61], v[138:141], v[162:165], v[58:61]
	v_mfma_f32_16x16x32_bf16 v[46:49], v[130:133], v[170:173], v[46:49]
	v_mfma_f32_16x16x32_bf16 v[42:45], v[138:141], v[170:173], v[42:45]
	v_mfma_f32_16x16x32_bf16 v[30:33], v[130:133], v[178:181], v[30:33]
	v_mfma_f32_16x16x32_bf16 v[26:29], v[138:141], v[178:181], v[26:29]
	v_mfma_f32_16x16x32_bf16 v[14:17], v[130:133], v[186:189], v[14:17]
	v_mfma_f32_16x16x32_bf16 v[10:13], v[138:141], v[186:189], v[10:13]
	v_mfma_f32_16x16x32_bf16 v[62:65], v[134:137], v[166:169], v[62:65]
	v_mfma_f32_16x16x32_bf16 v[58:61], v[142:145], v[166:169], v[58:61]
	v_mfma_f32_16x16x32_bf16 v[46:49], v[134:137], v[174:177], v[46:49]
	v_mfma_f32_16x16x32_bf16 v[42:45], v[142:145], v[174:177], v[42:45]
	v_mfma_f32_16x16x32_bf16 v[30:33], v[134:137], v[182:185], v[30:33]
	v_mfma_f32_16x16x32_bf16 v[26:29], v[142:145], v[182:185], v[26:29]
	v_mfma_f32_16x16x32_bf16 v[14:17], v[134:137], v[190:193], v[14:17]
	v_mfma_f32_16x16x32_bf16 v[10:13], v[142:145], v[190:193], v[10:13]
	s_setprio 0
	s_setprio 1
	v_mfma_f32_16x16x32_bf16 v[54:57], v[146:149], v[162:165], v[54:57]
	v_mfma_f32_16x16x32_bf16 v[50:53], v[154:157], v[162:165], v[50:53]
	v_mfma_f32_16x16x32_bf16 v[38:41], v[146:149], v[170:173], v[38:41]
	v_mfma_f32_16x16x32_bf16 v[34:37], v[154:157], v[170:173], v[34:37]
	v_mfma_f32_16x16x32_bf16 v[22:25], v[146:149], v[178:181], v[22:25]
	v_mfma_f32_16x16x32_bf16 v[18:21], v[154:157], v[178:181], v[18:21]
	v_mfma_f32_16x16x32_bf16 v[6:9], v[146:149], v[186:189], v[6:9]
	v_mfma_f32_16x16x32_bf16 v[2:5], v[154:157], v[186:189], v[2:5]
	v_mfma_f32_16x16x32_bf16 v[54:57], v[150:153], v[166:169], v[54:57]
	v_mfma_f32_16x16x32_bf16 v[50:53], v[158:161], v[166:169], v[50:53]
	v_mfma_f32_16x16x32_bf16 v[38:41], v[150:153], v[174:177], v[38:41]
	v_mfma_f32_16x16x32_bf16 v[34:37], v[158:161], v[174:177], v[34:37]
	v_mfma_f32_16x16x32_bf16 v[22:25], v[150:153], v[182:185], v[22:25]
	v_mfma_f32_16x16x32_bf16 v[18:21], v[158:161], v[182:185], v[18:21]
	v_mfma_f32_16x16x32_bf16 v[6:9], v[150:153], v[190:193], v[6:9]
	v_mfma_f32_16x16x32_bf16 v[2:5], v[158:161], v[190:193], v[2:5]
	s_setprio 0
	s_barrier
	s_add_i32 s29, 0, 0x18000
	s_add_i32 s30, 0, 0x1c000
	v_add_u32_e32 v142, s29, v245
	v_add_u32_e32 v158, s30, v245
	ds_read_b128 v[130:133], v142
	ds_read_b128 v[134:137], v142 offset:1024
	ds_read_b128 v[138:141], v142 offset:2048
	ds_read_b128 v[142:145], v142 offset:3072
	ds_read_b128 v[146:149], v158
	ds_read_b128 v[150:153], v158 offset:1024
	ds_read_b128 v[154:157], v158 offset:2048
	ds_read_b128 v[158:161], v158 offset:3072
	s_add_u32 s18, s74, 0xc0000
	s_addc_u32 s19, s75, 0
	s_mov_b32 m0, s97
	v_lshl_add_u64 v[218:219], s[18:19], 0, v[202:203]
	ds_read_b128 v[162:165], v247 offset:32768
	ds_read_b128 v[166:169], v247 offset:33792
	ds_read_b128 v[170:173], v247 offset:34816
	ds_read_b128 v[174:177], v247 offset:35840
	ds_read_b128 v[178:181], v247 offset:36864
	ds_read_b128 v[182:185], v247 offset:37888
	ds_read_b128 v[186:189], v247 offset:38912
	ds_read_b128 v[190:193], v247 offset:39936
	global_load_lds_dwordx4 v[218:219], off
	v_lshl_add_u64 v[218:219], s[18:19], 0, v[204:205]
	s_mov_b32 m0, s56
	s_nop 0
	global_load_lds_dwordx4 v[218:219], off
	s_waitcnt vmcnt(8)
	s_waitcnt lgkmcnt(0)
	s_barrier
	s_setprio 1
	s_waitcnt lgkmcnt(0)
	v_mfma_f32_16x16x32_bf16 v[126:129], v[130:133], v[162:165], v[126:129]
	v_mfma_f32_16x16x32_bf16 v[122:125], v[138:141], v[162:165], v[122:125]
	v_mfma_f32_16x16x32_bf16 v[110:113], v[130:133], v[170:173], v[110:113]
	v_mfma_f32_16x16x32_bf16 v[106:109], v[138:141], v[170:173], v[106:109]
	v_mfma_f32_16x16x32_bf16 v[94:97], v[130:133], v[178:181], v[94:97]
	v_mfma_f32_16x16x32_bf16 v[90:93], v[138:141], v[178:181], v[90:93]
	v_mfma_f32_16x16x32_bf16 v[78:81], v[130:133], v[186:189], v[78:81]
	v_mfma_f32_16x16x32_bf16 v[74:77], v[138:141], v[186:189], v[74:77]
	v_mfma_f32_16x16x32_bf16 v[126:129], v[134:137], v[166:169], v[126:129]
	v_mfma_f32_16x16x32_bf16 v[122:125], v[142:145], v[166:169], v[122:125]
	v_mfma_f32_16x16x32_bf16 v[110:113], v[134:137], v[174:177], v[110:113]
	v_mfma_f32_16x16x32_bf16 v[106:109], v[142:145], v[174:177], v[106:109]
	v_mfma_f32_16x16x32_bf16 v[94:97], v[134:137], v[182:185], v[94:97]
	v_mfma_f32_16x16x32_bf16 v[90:93], v[142:145], v[182:185], v[90:93]
	v_mfma_f32_16x16x32_bf16 v[78:81], v[134:137], v[190:193], v[78:81]
	v_mfma_f32_16x16x32_bf16 v[74:77], v[142:145], v[190:193], v[74:77]
	s_setprio 0
	s_setprio 1
	v_mfma_f32_16x16x32_bf16 v[118:121], v[146:149], v[162:165], v[118:121]
	v_mfma_f32_16x16x32_bf16 v[114:117], v[154:157], v[162:165], v[114:117]
	v_mfma_f32_16x16x32_bf16 v[102:105], v[146:149], v[170:173], v[102:105]
	v_mfma_f32_16x16x32_bf16 v[98:101], v[154:157], v[170:173], v[98:101]
	v_mfma_f32_16x16x32_bf16 v[86:89], v[146:149], v[178:181], v[86:89]
	v_mfma_f32_16x16x32_bf16 v[82:85], v[154:157], v[178:181], v[82:85]
	v_mfma_f32_16x16x32_bf16 v[70:73], v[146:149], v[186:189], v[70:73]
	v_mfma_f32_16x16x32_bf16 v[66:69], v[154:157], v[186:189], v[66:69]
	v_mfma_f32_16x16x32_bf16 v[118:121], v[150:153], v[166:169], v[118:121]
	v_mfma_f32_16x16x32_bf16 v[114:117], v[158:161], v[166:169], v[114:117]
	v_mfma_f32_16x16x32_bf16 v[102:105], v[150:153], v[174:177], v[102:105]
	v_mfma_f32_16x16x32_bf16 v[98:101], v[158:161], v[174:177], v[98:101]
	v_mfma_f32_16x16x32_bf16 v[86:89], v[150:153], v[182:185], v[86:89]
	v_mfma_f32_16x16x32_bf16 v[82:85], v[158:161], v[182:185], v[82:85]
	v_mfma_f32_16x16x32_bf16 v[70:73], v[150:153], v[190:193], v[70:73]
	v_mfma_f32_16x16x32_bf16 v[66:69], v[158:161], v[190:193], v[66:69]
	s_setprio 0
	s_barrier
; #define PG8_STAGE(bufoff, gbase, voff) do { _Pragma("unroll") for (int _i = 0; _i < 2; ++_i) \
;         __builtin_amdgcn_global_load_lds((const unsigned*)((const char*)(gbase) + (voff)[_i]), (LAS unsigned*)(lds + (bufoff) + ldsw + _i * 8192), 16, 0, 0); } while (0)
; #define PG8_WAIT_V(n) asm volatile("s_waitcnt vmcnt(" #n ")" ::: "memory")
; #define PG8_WAIT_L(n) asm volatile("s_waitcnt lgkmcnt(" #n ")" ::: "memory")
; #define PG8_BAR __builtin_amdgcn_s_barrier()
; #define PG8_SCHED __builtin_amdgcn_sched_barrier(0)
; template <bool F8 = false, class Epi, class Sched>
; __device__ __forceinline__ void gemm_phase(LAS unsigned char* lds, const int lda, const int ldb, const int K, const Sched& S, const Epi& E) {
;     ...
;             PG8_LDA(At, 1, 1); PG8_STAGE(PG8_SB(1, 0), b3, voffB); PG8_STAGE(PG8_SB(1, 1), b3 + hstepB, voffB); PG8_STAGE(PG8_SA(1, 0), a3, voffA);
;             PG8_WAIT_V(8); PG8_WAIT_L(0); PG8_BAR; PG8_MMA(1, 0, At, B0); PG8_MMA(1, 1, At, B1); PG8_BAR; PG8_SCHED;
;         }
;         if (wr == 0) PG8_BAR;
	s_add_i32 s18, s29, s94
	v_lshl_add_u64 v[194:195], v[194:195], 0, s[40:41]
	s_mov_b32 m0, s18
	ds_read_b128 v[162:165], v247 offset:49152
	ds_read_b128 v[166:169], v247 offset:50176
	ds_read_b128 v[170:173], v247 offset:51200
	ds_read_b128 v[174:177], v247 offset:52224
	ds_read_b128 v[178:181], v247 offset:53248
	ds_read_b128 v[182:185], v247 offset:54272
	ds_read_b128 v[186:189], v247 offset:55296
	ds_read_b128 v[190:193], v247 offset:56320
	global_load_lds_dwordx4 v[194:195], off
	s_add_i32 m0, s18, 0x2000
	s_add_u32 s18, s72, 0x40080
	v_lshl_add_u64 v[194:195], v[212:213], 0, s[40:41]
	s_addc_u32 s19, s73, 0
	s_add_i32 s29, s30, s94
	global_load_lds_dwordx4 v[194:195], off
	v_lshl_add_u64 v[194:195], s[18:19], 0, v[0:1]
	s_mov_b32 m0, s29
	s_nop 0
	global_load_lds_dwordx4 v[194:195], off
	v_lshl_add_u64 v[194:195], s[18:19], 0, v[206:207]
	s_add_i32 m0, s29, 0x2000
	s_nop 0
	global_load_lds_dwordx4 v[194:195], off
	v_lshl_add_u64 v[194:195], v[214:215], 0, s[40:41]
	s_mov_b32 m0, s57
	s_nop 0
	global_load_lds_dwordx4 v[194:195], off
	v_lshl_add_u64 v[194:195], v[216:217], 0, s[40:41]
	s_mov_b32 m0, s24
	s_nop 0
	global_load_lds_dwordx4 v[194:195], off
	s_waitcnt vmcnt(8)
	s_waitcnt lgkmcnt(0)
	s_barrier
	s_setprio 1
	s_waitcnt lgkmcnt(0)
	v_mfma_f32_16x16x32_bf16 v[62:65], v[130:133], v[162:165], v[62:65]
	v_mfma_f32_16x16x32_bf16 v[58:61], v[138:141], v[162:165], v[58:61]
	v_mfma_f32_16x16x32_bf16 v[46:49], v[130:133], v[170:173], v[46:49]
	v_mfma_f32_16x16x32_bf16 v[42:45], v[138:141], v[170:173], v[42:45]
	v_mfma_f32_16x16x32_bf16 v[30:33], v[130:133], v[178:181], v[30:33]
	v_mfma_f32_16x16x32_bf16 v[26:29], v[138:141], v[178:181], v[26:29]
	v_mfma_f32_16x16x32_bf16 v[14:17], v[130:133], v[186:189], v[14:17]
	v_mfma_f32_16x16x32_bf16 v[10:13], v[138:141], v[186:189], v[10:13]
	v_mfma_f32_16x16x32_bf16 v[62:65], v[134:137], v[166:169], v[62:65]
	v_mfma_f32_16x16x32_bf16 v[58:61], v[142:145], v[166:169], v[58:61]
	v_mfma_f32_16x16x32_bf16 v[46:49], v[134:137], v[174:177], v[46:49]
	v_mfma_f32_16x16x32_bf16 v[42:45], v[142:145], v[174:177], v[42:45]
	v_mfma_f32_16x16x32_bf16 v[30:33], v[134:137], v[182:185], v[30:33]
	v_mfma_f32_16x16x32_bf16 v[26:29], v[142:145], v[182:185], v[26:29]
	v_mfma_f32_16x16x32_bf16 v[14:17], v[134:137], v[190:193], v[14:17]
	v_mfma_f32_16x16x32_bf16 v[10:13], v[142:145], v[190:193], v[10:13]
	s_setprio 0
	s_setprio 1
	v_mfma_f32_16x16x32_bf16 v[54:57], v[146:149], v[162:165], v[54:57]
	v_mfma_f32_16x16x32_bf16 v[50:53], v[154:157], v[162:165], v[50:53]
	v_mfma_f32_16x16x32_bf16 v[38:41], v[146:149], v[170:173], v[38:41]
	v_mfma_f32_16x16x32_bf16 v[34:37], v[154:157], v[170:173], v[34:37]
	v_mfma_f32_16x16x32_bf16 v[22:25], v[146:149], v[178:181], v[22:25]
	v_mfma_f32_16x16x32_bf16 v[18:21], v[154:157], v[178:181], v[18:21]
	v_mfma_f32_16x16x32_bf16 v[6:9], v[146:149], v[186:189], v[6:9]
	v_mfma_f32_16x16x32_bf16 v[2:5], v[154:157], v[186:189], v[2:5]
	v_mfma_f32_16x16x32_bf16 v[54:57], v[150:153], v[166:169], v[54:57]
	v_mfma_f32_16x16x32_bf16 v[50:53], v[158:161], v[166:169], v[50:53]
	v_mfma_f32_16x16x32_bf16 v[38:41], v[150:153], v[174:177], v[38:41]
	v_mfma_f32_16x16x32_bf16 v[34:37], v[158:161], v[174:177], v[34:37]
	v_mfma_f32_16x16x32_bf16 v[22:25], v[150:153], v[182:185], v[22:25]
	v_mfma_f32_16x16x32_bf16 v[18:21], v[158:161], v[182:185], v[18:21]
	v_mfma_f32_16x16x32_bf16 v[6:9], v[150:153], v[190:193], v[6:9]
	v_mfma_f32_16x16x32_bf16 v[2:5], v[158:161], v[190:193], v[2:5]
	s_add_i32 s28, s28, 2
	s_add_u32 s15, s15, 0x100
	s_addc_u32 s17, s17, 0
	s_cmp_gt_u32 s28, 13
	s_mov_b64 s[18:19], s[52:53]
	s_setprio 0
	s_barrier
	s_cbranch_scc0 .LBB0_690
	s_and_b64 vcc, exec, s[12:13]
	s_cbranch_vccz .LBB0_693
	s_barrier

; #define PG8_STAGE(bufoff, gbase, voff) do { _Pragma("unroll") for (int _i = 0; _i < 2; ++_i) \
;         __builtin_amdgcn_global_load_lds((const unsigned*)((const char*)(gbase) + (voff)[_i]), (LAS unsigned*)(lds + (bufoff) + ldsw + _i * 8192), 16, 0, 0); } while (0)
; #define PG8_WAIT_V(n) asm volatile("s_waitcnt vmcnt(" #n ")" ::: "memory")
; #define PG8_WAIT_L(n) asm volatile("s_waitcnt lgkmcnt(" #n ")" ::: "memory")
; #define PG8_BAR __builtin_amdgcn_s_barrier()
; #define PG8_SCHED __builtin_amdgcn_sched_barrier(0)
; template <bool F8 = false, class Epi, class Sched>
; __device__ __forceinline__ void gemm_phase(LAS unsigned char* lds, const int lda, const int ldb, const int K, const Sched& S, const Epi& E) {
;     ...
;             const bool last = (t == nt - 2);
;             const char* a1 = cA + (size_t)(t + 1) * kstep;
;             const char* a2 = last ? nA : cA + (size_t)(t + 2) * kstep; const char* b2 = last ? nB : cB + (size_t)(t + 2) * kstep;
;             const char* a3 = a2 + kstep; const char* b3 = b2 + kstep;
;             PG8_LDB(B0, 0, 0); PG8_LDB(B1, 0, 1); PG8_SCHED; PG8_LDA(At, 0, 0); PG8_STAGE(PG8_SA(1, 1), a1 + hstepA, voffA);
;             PG8_WAIT_V(8); PG8_WAIT_L(0); PG8_BAR; PG8_MMA(0, 0, At, B0); PG8_MMA(0, 1, At, B1); PG8_BAR; PG8_SCHED;
;             PG8_LDA(At, 0, 1); PG8_STAGE(PG8_SB(0, 0), b2, voffB); PG8_STAGE(PG8_SB(0, 1), b2 + hstepB, voffB); PG8_STAGE(PG8_SA(0, 0), a2, voffA);
;             PG8_WAIT_V(8); PG8_WAIT_L(0); PG8_BAR; PG8_MMA(1, 0, At, B0); PG8_MMA(1, 1, At, B1); PG8_BAR; PG8_SCHED;
.LBB0_807:
	s_add_u32 s20, s18, 0xfff80080
	s_addc_u32 s21, s19, -1
	s_add_i32 s29, 0, 0x10000
	s_cmp_eq_u32 s28, 28
	s_cselect_b32 s53, s11, s21
	s_cselect_b32 s52, s75, s20
	v_add_u32_e32 v140, s29, v143
	s_cselect_b32 s21, s9, s96
	s_cselect_b32 s20, s94, s95
	s_add_i32 s33, 0, 0x14000
	ds_read_b128 v[146:149], v140
	ds_read_b128 v[150:153], v140 offset:1024
	ds_read_b128 v[154:157], v140 offset:2048
	ds_read_b128 v[158:161], v140 offset:3072
	v_add_u32_e32 v140, s33, v143
	ds_read_b128 v[162:165], v140
	ds_read_b128 v[166:169], v140 offset:1024
	ds_read_b128 v[170:173], v140 offset:2048
	ds_read_b128 v[174:177], v140 offset:3072
	v_lshl_add_u64 v[140:141], s[18:19], 0, v[136:137]
	s_add_i32 m0, s25, 0xc000
	ds_read_b128 v[178:181], v145
	ds_read_b128 v[182:185], v145 offset:1024
	ds_read_b128 v[186:189], v145 offset:2048
	ds_read_b128 v[190:193], v145 offset:3072
	ds_read_b128 v[202:205], v145 offset:4096
	ds_read_b128 v[206:209], v145 offset:5120
	ds_read_b128 v[210:213], v145 offset:6144
	ds_read_b128 v[214:217], v145 offset:7168
	global_load_lds_dwordx4 v[140:141], off
	v_lshl_add_u64 v[140:141], s[18:19], 0, v[138:139]
	s_add_i32 m0, s25, 0xe000
	s_nop 0
	global_load_lds_dwordx4 v[140:141], off
	s_waitcnt vmcnt(8)
	s_waitcnt lgkmcnt(0)
	s_barrier
	s_setprio 1
	s_waitcnt lgkmcnt(0)
	v_mfma_f32_16x16x32_bf16 v[126:129], v[146:149], v[178:181], v[126:129]
	v_mfma_f32_16x16x32_bf16 v[122:125], v[154:157], v[178:181], v[122:125]
	v_mfma_f32_16x16x32_bf16 v[118:121], v[146:149], v[186:189], v[118:121]
	v_mfma_f32_16x16x32_bf16 v[110:113], v[154:157], v[186:189], v[110:113]
	v_mfma_f32_16x16x32_bf16 v[102:105], v[146:149], v[202:205], v[102:105]
	v_mfma_f32_16x16x32_bf16 v[94:97], v[154:157], v[202:205], v[94:97]
	v_mfma_f32_16x16x32_bf16 v[86:89], v[146:149], v[210:213], v[86:89]
	v_mfma_f32_16x16x32_bf16 v[78:81], v[154:157], v[210:213], v[78:81]
	v_mfma_f32_16x16x32_bf16 v[126:129], v[150:153], v[182:185], v[126:129]
	v_mfma_f32_16x16x32_bf16 v[122:125], v[158:161], v[182:185], v[122:125]
	v_mfma_f32_16x16x32_bf16 v[118:121], v[150:153], v[190:193], v[118:121]
	v_mfma_f32_16x16x32_bf16 v[110:113], v[158:161], v[190:193], v[110:113]
	v_mfma_f32_16x16x32_bf16 v[102:105], v[150:153], v[206:209], v[102:105]
	v_mfma_f32_16x16x32_bf16 v[94:97], v[158:161], v[206:209], v[94:97]
	v_mfma_f32_16x16x32_bf16 v[86:89], v[150:153], v[214:217], v[86:89]
	v_mfma_f32_16x16x32_bf16 v[78:81], v[158:161], v[214:217], v[78:81]
	s_setprio 0
	s_setprio 1
	v_mfma_f32_16x16x32_bf16 v[114:117], v[162:165], v[178:181], v[114:117]
	v_mfma_f32_16x16x32_bf16 v[106:109], v[170:173], v[178:181], v[106:109]
	v_mfma_f32_16x16x32_bf16 v[98:101], v[162:165], v[186:189], v[98:101]
	v_mfma_f32_16x16x32_bf16 v[90:93], v[170:173], v[186:189], v[90:93]
	v_mfma_f32_16x16x32_bf16 v[82:85], v[162:165], v[202:205], v[82:85]
	v_mfma_f32_16x16x32_bf16 v[74:77], v[170:173], v[202:205], v[74:77]
	v_mfma_f32_16x16x32_bf16 v[70:73], v[162:165], v[210:213], v[70:73]
	v_mfma_f32_16x16x32_bf16 v[66:69], v[170:173], v[210:213], v[66:69]
	v_mfma_f32_16x16x32_bf16 v[114:117], v[166:169], v[182:185], v[114:117]
	v_mfma_f32_16x16x32_bf16 v[106:109], v[174:177], v[182:185], v[106:109]
	v_mfma_f32_16x16x32_bf16 v[98:101], v[166:169], v[190:193], v[98:101]
	v_mfma_f32_16x16x32_bf16 v[90:93], v[174:177], v[190:193], v[90:93]
	v_mfma_f32_16x16x32_bf16 v[82:85], v[166:169], v[206:209], v[82:85]
	v_mfma_f32_16x16x32_bf16 v[74:77], v[174:177], v[206:209], v[74:77]
	v_mfma_f32_16x16x32_bf16 v[70:73], v[166:169], v[214:217], v[70:73]
	v_mfma_f32_16x16x32_bf16 v[66:69], v[174:177], v[214:217], v[66:69]
	s_setprio 0
	s_barrier
	s_add_i32 s29, s29, s24
	v_lshl_add_u64 v[140:141], s[20:21], 0, v[0:1]
	s_mov_b32 m0, s29
	ds_read_b128 v[178:181], v145 offset:16384
	ds_read_b128 v[182:185], v145 offset:17408
	ds_read_b128 v[186:189], v145 offset:18432
	ds_read_b128 v[190:193], v145 offset:19456
	ds_read_b128 v[202:205], v145 offset:20480
	ds_read_b128 v[206:209], v145 offset:21504
	ds_read_b128 v[210:213], v145 offset:22528
	ds_read_b128 v[214:217], v145 offset:23552
	global_load_lds_dwordx4 v[140:141], off
	s_add_i32 m0, s29, 0x2000
	s_add_u32 s30, s20, 0x80000
	v_lshl_add_u64 v[194:195], s[20:21], 0, v[130:131]
	s_addc_u32 s31, s21, 0
	s_add_i32 s29, s33, s24
	global_load_lds_dwordx4 v[194:195], off
	v_lshl_add_u64 v[218:219], s[30:31], 0, v[0:1]
	s_mov_b32 m0, s29
	v_lshl_add_u64 v[220:221], s[52:53], 0, v[132:133]
	global_load_lds_dwordx4 v[218:219], off
	v_lshl_add_u64 v[218:219], s[30:31], 0, v[130:131]
	s_add_i32 m0, s29, 0x2000
	s_nop 0
	global_load_lds_dwordx4 v[218:219], off
	v_lshl_add_u64 v[218:219], s[52:53], 0, v[134:135]
	s_mov_b32 m0, s25
	s_nop 0
	global_load_lds_dwordx4 v[218:219], off
	s_mov_b32 m0, s26
	s_nop 0
	global_load_lds_dwordx4 v[220:221], off
	s_waitcnt vmcnt(8)
	s_waitcnt lgkmcnt(0)
	s_barrier
; #define PG8_STAGE(bufoff, gbase, voff) do { _Pragma("unroll") for (int _i = 0; _i < 2; ++_i) \
;         __builtin_amdgcn_global_load_lds((const unsigned*)((const char*)(gbase) + (voff)[_i]), (LAS unsigned*)(lds + (bufoff) + ldsw + _i * 8192), 16, 0, 0); } while (0)
; #define PG8_WAIT_V(n) asm volatile("s_waitcnt vmcnt(" #n ")" ::: "memory")
; #define PG8_WAIT_L(n) asm volatile("s_waitcnt lgkmcnt(" #n ")" ::: "memory")
; #define PG8_BAR __builtin_amdgcn_s_barrier()
; #define PG8_SCHED __builtin_amdgcn_sched_barrier(0)
; template <bool F8 = false, class Epi, class Sched>
; __device__ __forceinline__ void gemm_phase(LAS unsigned char* lds, const int lda, const int ldb, const int K, const Sched& S, const Epi& E) {
;     ...
;             PG8_WAIT_V(8); PG8_WAIT_L(0); PG8_BAR; PG8_MMA(1, 0, At, B0); PG8_MMA(1, 1, At, B1); PG8_BAR; PG8_SCHED;
;             PG8_LDB(B0, 1, 0); PG8_LDB(B1, 1, 1); PG8_SCHED; PG8_LDA(At, 1, 0); PG8_STAGE(PG8_SA(0, 1), a2 + hstepA, voffA);
;             PG8_WAIT_V(8); PG8_WAIT_L(0); PG8_BAR; PG8_MMA(0, 0, At, B0); PG8_MMA(0, 1, At, B1); PG8_BAR; PG8_SCHED;
	s_setprio 1
	s_waitcnt lgkmcnt(0)
	v_mfma_f32_16x16x32_bf16 v[62:65], v[146:149], v[178:181], v[62:65]
	v_mfma_f32_16x16x32_bf16 v[58:61], v[154:157], v[178:181], v[58:61]
	v_mfma_f32_16x16x32_bf16 v[54:57], v[146:149], v[186:189], v[54:57]
	v_mfma_f32_16x16x32_bf16 v[46:49], v[154:157], v[186:189], v[46:49]
	v_mfma_f32_16x16x32_bf16 v[38:41], v[146:149], v[202:205], v[38:41]
	v_mfma_f32_16x16x32_bf16 v[30:33], v[154:157], v[202:205], v[30:33]
	v_mfma_f32_16x16x32_bf16 v[22:25], v[146:149], v[210:213], v[22:25]
	v_mfma_f32_16x16x32_bf16 v[14:17], v[154:157], v[210:213], v[14:17]
	v_mfma_f32_16x16x32_bf16 v[62:65], v[150:153], v[182:185], v[62:65]
	v_mfma_f32_16x16x32_bf16 v[58:61], v[158:161], v[182:185], v[58:61]
	v_mfma_f32_16x16x32_bf16 v[54:57], v[150:153], v[190:193], v[54:57]
	v_mfma_f32_16x16x32_bf16 v[46:49], v[158:161], v[190:193], v[46:49]
	v_mfma_f32_16x16x32_bf16 v[38:41], v[150:153], v[206:209], v[38:41]
	v_mfma_f32_16x16x32_bf16 v[30:33], v[158:161], v[206:209], v[30:33]
	v_mfma_f32_16x16x32_bf16 v[22:25], v[150:153], v[214:217], v[22:25]
	v_mfma_f32_16x16x32_bf16 v[14:17], v[158:161], v[214:217], v[14:17]
	s_setprio 0
	s_setprio 1
	v_mfma_f32_16x16x32_bf16 v[50:53], v[162:165], v[178:181], v[50:53]
	v_mfma_f32_16x16x32_bf16 v[42:45], v[170:173], v[178:181], v[42:45]
	v_mfma_f32_16x16x32_bf16 v[34:37], v[162:165], v[186:189], v[34:37]
	v_mfma_f32_16x16x32_bf16 v[26:29], v[170:173], v[186:189], v[26:29]
	v_mfma_f32_16x16x32_bf16 v[18:21], v[162:165], v[202:205], v[18:21]
	v_mfma_f32_16x16x32_bf16 v[10:13], v[170:173], v[202:205], v[10:13]
	v_mfma_f32_16x16x32_bf16 v[6:9], v[162:165], v[210:213], v[6:9]
	v_mfma_f32_16x16x32_bf16 v[2:5], v[170:173], v[210:213], v[2:5]
	v_mfma_f32_16x16x32_bf16 v[50:53], v[166:169], v[182:185], v[50:53]
	v_mfma_f32_16x16x32_bf16 v[42:45], v[174:177], v[182:185], v[42:45]
	v_mfma_f32_16x16x32_bf16 v[34:37], v[166:169], v[190:193], v[34:37]
	v_mfma_f32_16x16x32_bf16 v[26:29], v[174:177], v[190:193], v[26:29]
	v_mfma_f32_16x16x32_bf16 v[18:21], v[166:169], v[206:209], v[18:21]
	v_mfma_f32_16x16x32_bf16 v[10:13], v[174:177], v[206:209], v[10:13]
	v_mfma_f32_16x16x32_bf16 v[6:9], v[166:169], v[214:217], v[6:9]
	v_mfma_f32_16x16x32_bf16 v[2:5], v[174:177], v[214:217], v[2:5]
	s_setprio 0
	s_barrier
	s_add_i32 s29, 0, 0x18000
	s_add_i32 s33, 0, 0x1c000
	v_add_u32_e32 v158, s29, v143
	v_add_u32_e32 v174, s33, v143
	ds_read_b128 v[146:149], v158
	ds_read_b128 v[150:153], v158 offset:1024
	ds_read_b128 v[154:157], v158 offset:2048
	ds_read_b128 v[158:161], v158 offset:3072
	ds_read_b128 v[162:165], v174
	ds_read_b128 v[166:169], v174 offset:1024
	ds_read_b128 v[170:173], v174 offset:2048
	ds_read_b128 v[174:177], v174 offset:3072
	s_add_u32 s30, s52, 0x80000
	s_addc_u32 s31, s53, 0
	s_mov_b32 m0, s27
	v_lshl_add_u64 v[222:223], s[30:31], 0, v[134:135]
	ds_read_b128 v[178:181], v145 offset:32768
	ds_read_b128 v[182:185], v145 offset:33792
	ds_read_b128 v[186:189], v145 offset:34816
	ds_read_b128 v[190:193], v145 offset:35840
	ds_read_b128 v[202:205], v145 offset:36864
	ds_read_b128 v[206:209], v145 offset:37888
	ds_read_b128 v[210:213], v145 offset:38912
	ds_read_b128 v[214:217], v145 offset:39936
	global_load_lds_dwordx4 v[222:223], off
	v_lshl_add_u64 v[222:223], s[30:31], 0, v[132:133]
	s_mov_b32 m0, s44
	s_nop 0
	global_load_lds_dwordx4 v[222:223], off
	s_waitcnt vmcnt(8)
	s_waitcnt lgkmcnt(0)
	s_barrier
	s_setprio 1
	s_waitcnt lgkmcnt(0)
	v_mfma_f32_16x16x32_bf16 v[126:129], v[146:149], v[178:181], v[126:129]
	v_mfma_f32_16x16x32_bf16 v[122:125], v[154:157], v[178:181], v[122:125]
	v_mfma_f32_16x16x32_bf16 v[118:121], v[146:149], v[186:189], v[118:121]
	v_mfma_f32_16x16x32_bf16 v[110:113], v[154:157], v[186:189], v[110:113]
	v_mfma_f32_16x16x32_bf16 v[102:105], v[146:149], v[202:205], v[102:105]
	v_mfma_f32_16x16x32_bf16 v[94:97], v[154:157], v[202:205], v[94:97]
	v_mfma_f32_16x16x32_bf16 v[86:89], v[146:149], v[210:213], v[86:89]
	v_mfma_f32_16x16x32_bf16 v[78:81], v[154:157], v[210:213], v[78:81]
	v_mfma_f32_16x16x32_bf16 v[126:129], v[150:153], v[182:185], v[126:129]
	v_mfma_f32_16x16x32_bf16 v[122:125], v[158:161], v[182:185], v[122:125]
	v_mfma_f32_16x16x32_bf16 v[118:121], v[150:153], v[190:193], v[118:121]
	v_mfma_f32_16x16x32_bf16 v[110:113], v[158:161], v[190:193], v[110:113]
	v_mfma_f32_16x16x32_bf16 v[102:105], v[150:153], v[206:209], v[102:105]
	v_mfma_f32_16x16x32_bf16 v[94:97], v[158:161], v[206:209], v[94:97]
	v_mfma_f32_16x16x32_bf16 v[86:89], v[150:153], v[214:217], v[86:89]
	v_mfma_f32_16x16x32_bf16 v[78:81], v[158:161], v[214:217], v[78:81]
	s_setprio 0
	s_setprio 1
	v_mfma_f32_16x16x32_bf16 v[114:117], v[162:165], v[178:181], v[114:117]
	v_mfma_f32_16x16x32_bf16 v[106:109], v[170:173], v[178:181], v[106:109]
	v_mfma_f32_16x16x32_bf16 v[98:101], v[162:165], v[186:189], v[98:101]
	v_mfma_f32_16x16x32_bf16 v[90:93], v[170:173], v[186:189], v[90:93]
	v_mfma_f32_16x16x32_bf16 v[82:85], v[162:165], v[202:205], v[82:85]
	v_mfma_f32_16x16x32_bf16 v[74:77], v[170:173], v[202:205], v[74:77]
	v_mfma_f32_16x16x32_bf16 v[70:73], v[162:165], v[210:213], v[70:73]
	v_mfma_f32_16x16x32_bf16 v[66:69], v[170:173], v[210:213], v[66:69]
	v_mfma_f32_16x16x32_bf16 v[114:117], v[166:169], v[182:185], v[114:117]
	v_mfma_f32_16x16x32_bf16 v[106:109], v[174:177], v[182:185], v[106:109]
	v_mfma_f32_16x16x32_bf16 v[98:101], v[166:169], v[190:193], v[98:101]
	v_mfma_f32_16x16x32_bf16 v[90:93], v[174:177], v[190:193], v[90:93]
	v_mfma_f32_16x16x32_bf16 v[82:85], v[166:169], v[206:209], v[82:85]
	v_mfma_f32_16x16x32_bf16 v[74:77], v[174:177], v[206:209], v[74:77]
	v_mfma_f32_16x16x32_bf16 v[70:73], v[166:169], v[214:217], v[70:73]
	v_mfma_f32_16x16x32_bf16 v[66:69], v[174:177], v[214:217], v[66:69]
	s_setprio 0
	s_barrier
; #define PG8_STAGE(bufoff, gbase, voff) do { _Pragma("unroll") for (int _i = 0; _i < 2; ++_i) \
;         __builtin_amdgcn_global_load_lds((const unsigned*)((const char*)(gbase) + (voff)[_i]), (LAS unsigned*)(lds + (bufoff) + ldsw + _i * 8192), 16, 0, 0); } while (0)
; #define PG8_WAIT_V(n) asm volatile("s_waitcnt vmcnt(" #n ")" ::: "memory")
; #define PG8_WAIT_L(n) asm volatile("s_waitcnt lgkmcnt(" #n ")" ::: "memory")
; #define PG8_BAR __builtin_amdgcn_s_barrier()
; #define PG8_SCHED __builtin_amdgcn_sched_barrier(0)
; template <bool F8 = false, class Epi, class Sched>
; __device__ __forceinline__ void gemm_phase(LAS unsigned char* lds, const int lda, const int ldb, const int K, const Sched& S, const Epi& E) {
;     ...
;             PG8_LDA(At, 1, 1); PG8_STAGE(PG8_SB(1, 0), b3, voffB); PG8_STAGE(PG8_SB(1, 1), b3 + hstepB, voffB); PG8_STAGE(PG8_SA(1, 0), a3, voffA);
;             PG8_WAIT_V(8); PG8_WAIT_L(0); PG8_BAR; PG8_MMA(1, 0, At, B0); PG8_MMA(1, 1, At, B1); PG8_BAR; PG8_SCHED;
;         }
;         if (wr == 0) PG8_BAR;
	s_add_i32 s29, s29, s24
	v_lshl_add_u64 v[140:141], v[140:141], 0, s[40:41]
	s_mov_b32 m0, s29
	ds_read_b128 v[178:181], v145 offset:49152
	ds_read_b128 v[182:185], v145 offset:50176
	ds_read_b128 v[186:189], v145 offset:51200
	ds_read_b128 v[190:193], v145 offset:52224
	ds_read_b128 v[202:205], v145 offset:53248
	ds_read_b128 v[206:209], v145 offset:54272
	ds_read_b128 v[210:213], v145 offset:55296
	ds_read_b128 v[214:217], v145 offset:56320
	global_load_lds_dwordx4 v[140:141], off
	s_add_i32 m0, s29, 0x2000
	s_add_u32 s20, s20, 0x80080
	v_lshl_add_u64 v[140:141], v[194:195], 0, s[40:41]
	s_addc_u32 s21, s21, 0
	s_add_i32 s29, s33, s24
	global_load_lds_dwordx4 v[140:141], off
	v_lshl_add_u64 v[140:141], s[20:21], 0, v[0:1]
	s_mov_b32 m0, s29
	s_nop 0
	global_load_lds_dwordx4 v[140:141], off
	v_lshl_add_u64 v[140:141], s[20:21], 0, v[130:131]
	s_add_i32 m0, s29, 0x2000
	s_nop 0
	global_load_lds_dwordx4 v[140:141], off
	v_lshl_add_u64 v[140:141], v[218:219], 0, s[40:41]
	s_mov_b32 m0, s56
	s_nop 0
	global_load_lds_dwordx4 v[140:141], off
	v_lshl_add_u64 v[140:141], v[220:221], 0, s[40:41]
	s_mov_b32 m0, s57
	s_nop 0
	global_load_lds_dwordx4 v[140:141], off
	s_waitcnt vmcnt(8)
	s_waitcnt lgkmcnt(0)
	s_barrier
	s_setprio 1
	s_waitcnt lgkmcnt(0)
	v_mfma_f32_16x16x32_bf16 v[62:65], v[146:149], v[178:181], v[62:65]
	v_mfma_f32_16x16x32_bf16 v[58:61], v[154:157], v[178:181], v[58:61]
	v_mfma_f32_16x16x32_bf16 v[54:57], v[146:149], v[186:189], v[54:57]
	v_mfma_f32_16x16x32_bf16 v[46:49], v[154:157], v[186:189], v[46:49]
	v_mfma_f32_16x16x32_bf16 v[38:41], v[146:149], v[202:205], v[38:41]
	v_mfma_f32_16x16x32_bf16 v[30:33], v[154:157], v[202:205], v[30:33]
	v_mfma_f32_16x16x32_bf16 v[22:25], v[146:149], v[210:213], v[22:25]
	v_mfma_f32_16x16x32_bf16 v[14:17], v[154:157], v[210:213], v[14:17]
	v_mfma_f32_16x16x32_bf16 v[62:65], v[150:153], v[182:185], v[62:65]
	v_mfma_f32_16x16x32_bf16 v[58:61], v[158:161], v[182:185], v[58:61]
	v_mfma_f32_16x16x32_bf16 v[54:57], v[150:153], v[190:193], v[54:57]
	v_mfma_f32_16x16x32_bf16 v[46:49], v[158:161], v[190:193], v[46:49]
	v_mfma_f32_16x16x32_bf16 v[38:41], v[150:153], v[206:209], v[38:41]
	v_mfma_f32_16x16x32_bf16 v[30:33], v[158:161], v[206:209], v[30:33]
	v_mfma_f32_16x16x32_bf16 v[22:25], v[150:153], v[214:217], v[22:25]
	v_mfma_f32_16x16x32_bf16 v[14:17], v[158:161], v[214:217], v[14:17]
	s_setprio 0
	s_setprio 1
	v_mfma_f32_16x16x32_bf16 v[50:53], v[162:165], v[178:181], v[50:53]
	v_mfma_f32_16x16x32_bf16 v[42:45], v[170:173], v[178:181], v[42:45]
	v_mfma_f32_16x16x32_bf16 v[34:37], v[162:165], v[186:189], v[34:37]
	v_mfma_f32_16x16x32_bf16 v[26:29], v[170:173], v[186:189], v[26:29]
	v_mfma_f32_16x16x32_bf16 v[18:21], v[162:165], v[202:205], v[18:21]
	v_mfma_f32_16x16x32_bf16 v[10:13], v[170:173], v[202:205], v[10:13]
	v_mfma_f32_16x16x32_bf16 v[6:9], v[162:165], v[210:213], v[6:9]
	v_mfma_f32_16x16x32_bf16 v[2:5], v[170:173], v[210:213], v[2:5]
	v_mfma_f32_16x16x32_bf16 v[50:53], v[166:169], v[182:185], v[50:53]
	v_mfma_f32_16x16x32_bf16 v[42:45], v[174:177], v[182:185], v[42:45]
	v_mfma_f32_16x16x32_bf16 v[34:37], v[166:169], v[190:193], v[34:37]
	v_mfma_f32_16x16x32_bf16 v[26:29], v[174:177], v[190:193], v[26:29]
	v_mfma_f32_16x16x32_bf16 v[18:21], v[166:169], v[206:209], v[18:21]
	v_mfma_f32_16x16x32_bf16 v[10:13], v[174:177], v[206:209], v[10:13]
	v_mfma_f32_16x16x32_bf16 v[6:9], v[166:169], v[214:217], v[6:9]
	v_mfma_f32_16x16x32_bf16 v[2:5], v[174:177], v[214:217], v[2:5]
	s_add_i32 s28, s28, 2
	s_add_u32 s18, s18, 0x100
	s_addc_u32 s19, s19, 0
	s_add_u32 s95, s95, 0x100
	s_addc_u32 s96, s96, 0
	s_cmp_gt_u32 s28, 29
	s_setprio 0
	s_barrier
	s_cbranch_scc0 .LBB0_807
	s_and_b64 vcc, exec, s[6:7]
	s_cbranch_vccz .LBB0_810
	s_barrier

; #define PG8_STAGE(bufoff, gbase, voff) do { _Pragma("unroll") for (int _i = 0; _i < 2; ++_i) \
;         __builtin_amdgcn_global_load_lds((const unsigned*)((const char*)(gbase) + (voff)[_i]), (LAS unsigned*)(lds + (bufoff) + ldsw + _i * 8192), 16, 0, 0); } while (0)
; #define PG8_WAIT_V(n) asm volatile("s_waitcnt vmcnt(" #n ")" ::: "memory")
; #define PG8_WAIT_L(n) asm volatile("s_waitcnt lgkmcnt(" #n ")" ::: "memory")
; #define PG8_BAR __builtin_amdgcn_s_barrier()
; #define PG8_SCHED __builtin_amdgcn_sched_barrier(0)
; template <bool F8 = false, class Epi, class Sched>
; __device__ __forceinline__ void gemm_phase(LAS unsigned char* lds, const int lda, const int ldb, const int K, const Sched& S, const Epi& E) {
;     ...
;             const bool last = (t == nt - 2);
;             const char* a1 = cA + (size_t)(t + 1) * kstep;
;             const char* a2 = last ? nA : cA + (size_t)(t + 2) * kstep; const char* b2 = last ? nB : cB + (size_t)(t + 2) * kstep;
;             const char* a3 = a2 + kstep; const char* b3 = b2 + kstep;
;             PG8_LDB(B0, 0, 0); PG8_LDB(B1, 0, 1); PG8_SCHED; PG8_LDA(At, 0, 0); PG8_STAGE(PG8_SA(1, 1), a1 + hstepA, voffA);
;             PG8_WAIT_V(8); PG8_WAIT_L(0); PG8_BAR; PG8_MMA(0, 0, At, B0); PG8_MMA(0, 1, At, B1); PG8_BAR; PG8_SCHED;
;             PG8_LDA(At, 0, 1); PG8_STAGE(PG8_SB(0, 0), b2, voffB); PG8_STAGE(PG8_SB(0, 1), b2 + hstepB, voffB); PG8_STAGE(PG8_SA(0, 0), a2, voffA);
;             PG8_WAIT_V(8); PG8_WAIT_L(0); PG8_BAR; PG8_MMA(1, 0, At, B0); PG8_MMA(1, 1, At, B1); PG8_BAR; PG8_SCHED;
.LBB0_835:
	s_add_u32 s18, s16, 0xfff80080
	s_addc_u32 s19, s17, -1
	s_add_i32 s29, 0, 0x10000
	s_cmp_eq_u32 s28, 4
	s_cselect_b32 s21, s13, s19
	s_cselect_b32 s20, s12, s18
	v_add_u32_e32 v0, s29, v140
	s_cselect_b32 s19, s75, s96
	s_cselect_b32 s18, s94, s95
	s_add_i32 s33, 0, 0x14000
	ds_read_b128 v[144:147], v0
	ds_read_b128 v[148:151], v0 offset:1024
	ds_read_b128 v[152:155], v0 offset:2048
	ds_read_b128 v[156:159], v0 offset:3072
	v_add_u32_e32 v0, s33, v140
	ds_read_b128 v[160:163], v0
	ds_read_b128 v[164:167], v0 offset:1024
	ds_read_b128 v[168:171], v0 offset:2048
	ds_read_b128 v[172:175], v0 offset:3072
	v_lshl_add_u64 v[138:139], s[16:17], 0, v[134:135]
	s_add_i32 m0, s25, 0xc000
	ds_read_b128 v[176:179], v142
	ds_read_b128 v[180:183], v142 offset:1024
	ds_read_b128 v[184:187], v142 offset:2048
	ds_read_b128 v[188:191], v142 offset:3072
	ds_read_b128 v[192:195], v142 offset:4096
	ds_read_b128 v[202:205], v142 offset:5120
	ds_read_b128 v[206:209], v142 offset:6144
	ds_read_b128 v[210:213], v142 offset:7168
	global_load_lds_dwordx4 v[138:139], off
	v_lshl_add_u64 v[138:139], s[16:17], 0, v[136:137]
	s_add_i32 m0, s25, 0xe000
	s_nop 0
	global_load_lds_dwordx4 v[138:139], off
	s_waitcnt vmcnt(8)
	s_waitcnt lgkmcnt(0)
	s_barrier
	s_setprio 1
	s_waitcnt lgkmcnt(0)
	v_mfma_f32_16x16x32_bf16 v[126:129], v[144:147], v[176:179], v[126:129]
	v_mfma_f32_16x16x32_bf16 v[122:125], v[152:155], v[176:179], v[122:125]
	v_mfma_f32_16x16x32_bf16 v[118:121], v[144:147], v[184:187], v[118:121]
	v_mfma_f32_16x16x32_bf16 v[110:113], v[152:155], v[184:187], v[110:113]
	v_mfma_f32_16x16x32_bf16 v[102:105], v[144:147], v[192:195], v[102:105]
	v_mfma_f32_16x16x32_bf16 v[94:97], v[152:155], v[192:195], v[94:97]
	v_mfma_f32_16x16x32_bf16 v[86:89], v[144:147], v[206:209], v[86:89]
	v_mfma_f32_16x16x32_bf16 v[78:81], v[152:155], v[206:209], v[78:81]
	v_mfma_f32_16x16x32_bf16 v[126:129], v[148:151], v[180:183], v[126:129]
	v_mfma_f32_16x16x32_bf16 v[122:125], v[156:159], v[180:183], v[122:125]
	v_mfma_f32_16x16x32_bf16 v[118:121], v[148:151], v[188:191], v[118:121]
	v_mfma_f32_16x16x32_bf16 v[110:113], v[156:159], v[188:191], v[110:113]
	v_mfma_f32_16x16x32_bf16 v[102:105], v[148:151], v[202:205], v[102:105]
	v_mfma_f32_16x16x32_bf16 v[94:97], v[156:159], v[202:205], v[94:97]
	v_mfma_f32_16x16x32_bf16 v[86:89], v[148:151], v[210:213], v[86:89]
	v_mfma_f32_16x16x32_bf16 v[78:81], v[156:159], v[210:213], v[78:81]
	s_setprio 0
	s_setprio 1
	v_mfma_f32_16x16x32_bf16 v[114:117], v[160:163], v[176:179], v[114:117]
	v_mfma_f32_16x16x32_bf16 v[106:109], v[168:171], v[176:179], v[106:109]
	v_mfma_f32_16x16x32_bf16 v[98:101], v[160:163], v[184:187], v[98:101]
	v_mfma_f32_16x16x32_bf16 v[90:93], v[168:171], v[184:187], v[90:93]
	v_mfma_f32_16x16x32_bf16 v[82:85], v[160:163], v[192:195], v[82:85]
	v_mfma_f32_16x16x32_bf16 v[74:77], v[168:171], v[192:195], v[74:77]
	v_mfma_f32_16x16x32_bf16 v[70:73], v[160:163], v[206:209], v[70:73]
	v_mfma_f32_16x16x32_bf16 v[66:69], v[168:171], v[206:209], v[66:69]
	v_mfma_f32_16x16x32_bf16 v[114:117], v[164:167], v[180:183], v[114:117]
	v_mfma_f32_16x16x32_bf16 v[106:109], v[172:175], v[180:183], v[106:109]
	v_mfma_f32_16x16x32_bf16 v[98:101], v[164:167], v[188:191], v[98:101]
	v_mfma_f32_16x16x32_bf16 v[90:93], v[172:175], v[188:191], v[90:93]
	v_mfma_f32_16x16x32_bf16 v[82:85], v[164:167], v[202:205], v[82:85]
	v_mfma_f32_16x16x32_bf16 v[74:77], v[172:175], v[202:205], v[74:77]
	v_mfma_f32_16x16x32_bf16 v[70:73], v[164:167], v[210:213], v[70:73]
	v_mfma_f32_16x16x32_bf16 v[66:69], v[172:175], v[210:213], v[66:69]
	s_setprio 0
	s_barrier
	s_add_i32 s29, s29, s24
	v_lshl_add_u64 v[138:139], s[18:19], 0, v[132:133]
	s_mov_b32 m0, s29
	ds_read_b128 v[176:179], v142 offset:16384
	ds_read_b128 v[180:183], v142 offset:17408
	ds_read_b128 v[184:187], v142 offset:18432
	ds_read_b128 v[188:191], v142 offset:19456
	ds_read_b128 v[192:195], v142 offset:20480
	ds_read_b128 v[202:205], v142 offset:21504
	ds_read_b128 v[206:209], v142 offset:22528
	ds_read_b128 v[210:213], v142 offset:23552
	global_load_lds_dwordx4 v[138:139], off
	s_add_i32 m0, s29, 0x2000
	s_add_u32 s30, s18, 0x80000
	v_lshl_add_u64 v[214:215], s[18:19], 0, v[130:131]
	s_addc_u32 s31, s19, 0
	s_add_i32 s29, s33, s24
	global_load_lds_dwordx4 v[214:215], off
	v_lshl_add_u64 v[216:217], s[30:31], 0, v[132:133]
	s_mov_b32 m0, s29
	v_lshl_add_u64 v[218:219], s[20:21], 0, v[130:131]
	global_load_lds_dwordx4 v[216:217], off
	v_lshl_add_u64 v[216:217], s[30:31], 0, v[130:131]
	s_add_i32 m0, s29, 0x2000
	s_nop 0
	global_load_lds_dwordx4 v[216:217], off
	v_lshl_add_u64 v[216:217], s[20:21], 0, v[132:133]
	s_mov_b32 m0, s25
	s_nop 0
	global_load_lds_dwordx4 v[216:217], off
	s_mov_b32 m0, s26
	s_nop 0
	global_load_lds_dwordx4 v[218:219], off
	s_waitcnt vmcnt(8)
	s_waitcnt lgkmcnt(0)
	s_barrier
; #define PG8_STAGE(bufoff, gbase, voff) do { _Pragma("unroll") for (int _i = 0; _i < 2; ++_i) \
;         __builtin_amdgcn_global_load_lds((const unsigned*)((const char*)(gbase) + (voff)[_i]), (LAS unsigned*)(lds + (bufoff) + ldsw + _i * 8192), 16, 0, 0); } while (0)
; #define PG8_WAIT_V(n) asm volatile("s_waitcnt vmcnt(" #n ")" ::: "memory")
; #define PG8_WAIT_L(n) asm volatile("s_waitcnt lgkmcnt(" #n ")" ::: "memory")
; #define PG8_BAR __builtin_amdgcn_s_barrier()
; #define PG8_SCHED __builtin_amdgcn_sched_barrier(0)
; template <bool F8 = false, class Epi, class Sched>
; __device__ __forceinline__ void gemm_phase(LAS unsigned char* lds, const int lda, const int ldb, const int K, const Sched& S, const Epi& E) {
;     ...
;             PG8_WAIT_V(8); PG8_WAIT_L(0); PG8_BAR; PG8_MMA(1, 0, At, B0); PG8_MMA(1, 1, At, B1); PG8_BAR; PG8_SCHED;
;             PG8_LDB(B0, 1, 0); PG8_LDB(B1, 1, 1); PG8_SCHED; PG8_LDA(At, 1, 0); PG8_STAGE(PG8_SA(0, 1), a2 + hstepA, voffA);
;             PG8_WAIT_V(8); PG8_WAIT_L(0); PG8_BAR; PG8_MMA(0, 0, At, B0); PG8_MMA(0, 1, At, B1); PG8_BAR; PG8_SCHED;
	s_setprio 1
	s_waitcnt lgkmcnt(0)
	v_mfma_f32_16x16x32_bf16 v[62:65], v[144:147], v[176:179], v[62:65]
	v_mfma_f32_16x16x32_bf16 v[58:61], v[152:155], v[176:179], v[58:61]
	v_mfma_f32_16x16x32_bf16 v[54:57], v[144:147], v[184:187], v[54:57]
	v_mfma_f32_16x16x32_bf16 v[42:45], v[152:155], v[184:187], v[42:45]
	v_mfma_f32_16x16x32_bf16 v[38:41], v[144:147], v[192:195], v[38:41]
	v_mfma_f32_16x16x32_bf16 v[26:29], v[152:155], v[192:195], v[26:29]
	v_mfma_f32_16x16x32_bf16 v[22:25], v[144:147], v[206:209], v[22:25]
	v_mfma_f32_16x16x32_bf16 v[10:13], v[152:155], v[206:209], v[10:13]
	v_mfma_f32_16x16x32_bf16 v[62:65], v[148:151], v[180:183], v[62:65]
	v_mfma_f32_16x16x32_bf16 v[58:61], v[156:159], v[180:183], v[58:61]
	v_mfma_f32_16x16x32_bf16 v[54:57], v[148:151], v[188:191], v[54:57]
	v_mfma_f32_16x16x32_bf16 v[42:45], v[156:159], v[188:191], v[42:45]
	v_mfma_f32_16x16x32_bf16 v[38:41], v[148:151], v[202:205], v[38:41]
	v_mfma_f32_16x16x32_bf16 v[26:29], v[156:159], v[202:205], v[26:29]
	v_mfma_f32_16x16x32_bf16 v[22:25], v[148:151], v[210:213], v[22:25]
	v_mfma_f32_16x16x32_bf16 v[10:13], v[156:159], v[210:213], v[10:13]
	s_setprio 0
	s_setprio 1
	v_mfma_f32_16x16x32_bf16 v[50:53], v[160:163], v[176:179], v[50:53]
	v_mfma_f32_16x16x32_bf16 v[46:49], v[168:171], v[176:179], v[46:49]
	v_mfma_f32_16x16x32_bf16 v[34:37], v[160:163], v[184:187], v[34:37]
	v_mfma_f32_16x16x32_bf16 v[30:33], v[168:171], v[184:187], v[30:33]
	v_mfma_f32_16x16x32_bf16 v[18:21], v[160:163], v[192:195], v[18:21]
	v_mfma_f32_16x16x32_bf16 v[14:17], v[168:171], v[192:195], v[14:17]
	v_mfma_f32_16x16x32_bf16 v[6:9], v[160:163], v[206:209], v[6:9]
	v_mfma_f32_16x16x32_bf16 v[2:5], v[168:171], v[206:209], v[2:5]
	v_mfma_f32_16x16x32_bf16 v[50:53], v[164:167], v[180:183], v[50:53]
	v_mfma_f32_16x16x32_bf16 v[46:49], v[172:175], v[180:183], v[46:49]
	v_mfma_f32_16x16x32_bf16 v[34:37], v[164:167], v[188:191], v[34:37]
	v_mfma_f32_16x16x32_bf16 v[30:33], v[172:175], v[188:191], v[30:33]
	v_mfma_f32_16x16x32_bf16 v[18:21], v[164:167], v[202:205], v[18:21]
	v_mfma_f32_16x16x32_bf16 v[14:17], v[172:175], v[202:205], v[14:17]
	v_mfma_f32_16x16x32_bf16 v[6:9], v[164:167], v[210:213], v[6:9]
	v_mfma_f32_16x16x32_bf16 v[2:5], v[172:175], v[210:213], v[2:5]
	s_setprio 0
	s_barrier
	s_add_i32 s29, 0, 0x18000
	v_add_u32_e32 v0, s29, v140
	s_add_i32 s30, 0, 0x1c000
	ds_read_b128 v[144:147], v0
	ds_read_b128 v[148:151], v0 offset:1024
	ds_read_b128 v[152:155], v0 offset:2048
	ds_read_b128 v[156:159], v0 offset:3072
	v_add_u32_e32 v0, s30, v140
	ds_read_b128 v[160:163], v0
	ds_read_b128 v[164:167], v0 offset:1024
	ds_read_b128 v[168:171], v0 offset:2048
	ds_read_b128 v[172:175], v0 offset:3072
	s_add_u32 s20, s20, 0x80000
	s_addc_u32 s21, s21, 0
	s_mov_b32 m0, s27
	v_lshl_add_u64 v[220:221], s[20:21], 0, v[132:133]
	ds_read_b128 v[176:179], v142 offset:32768
	ds_read_b128 v[180:183], v142 offset:33792
	ds_read_b128 v[184:187], v142 offset:34816
	ds_read_b128 v[188:191], v142 offset:35840
	ds_read_b128 v[192:195], v142 offset:36864
	ds_read_b128 v[202:205], v142 offset:37888
	ds_read_b128 v[206:209], v142 offset:38912
	ds_read_b128 v[210:213], v142 offset:39936
	global_load_lds_dwordx4 v[220:221], off
	v_lshl_add_u64 v[220:221], s[20:21], 0, v[130:131]
	s_mov_b32 m0, s44
	s_nop 0
	global_load_lds_dwordx4 v[220:221], off
	s_waitcnt vmcnt(8)
	s_waitcnt lgkmcnt(0)
	s_barrier
	s_setprio 1
	s_waitcnt lgkmcnt(0)
	v_mfma_f32_16x16x32_bf16 v[126:129], v[144:147], v[176:179], v[126:129]
	v_mfma_f32_16x16x32_bf16 v[122:125], v[152:155], v[176:179], v[122:125]
	v_mfma_f32_16x16x32_bf16 v[118:121], v[144:147], v[184:187], v[118:121]
	v_mfma_f32_16x16x32_bf16 v[110:113], v[152:155], v[184:187], v[110:113]
	v_mfma_f32_16x16x32_bf16 v[102:105], v[144:147], v[192:195], v[102:105]
	v_mfma_f32_16x16x32_bf16 v[94:97], v[152:155], v[192:195], v[94:97]
	v_mfma_f32_16x16x32_bf16 v[86:89], v[144:147], v[206:209], v[86:89]
	v_mfma_f32_16x16x32_bf16 v[78:81], v[152:155], v[206:209], v[78:81]
	v_mfma_f32_16x16x32_bf16 v[126:129], v[148:151], v[180:183], v[126:129]
	v_mfma_f32_16x16x32_bf16 v[122:125], v[156:159], v[180:183], v[122:125]
	v_mfma_f32_16x16x32_bf16 v[118:121], v[148:151], v[188:191], v[118:121]
	v_mfma_f32_16x16x32_bf16 v[110:113], v[156:159], v[188:191], v[110:113]
	v_mfma_f32_16x16x32_bf16 v[102:105], v[148:151], v[202:205], v[102:105]
	v_mfma_f32_16x16x32_bf16 v[94:97], v[156:159], v[202:205], v[94:97]
	v_mfma_f32_16x16x32_bf16 v[86:89], v[148:151], v[210:213], v[86:89]
	v_mfma_f32_16x16x32_bf16 v[78:81], v[156:159], v[210:213], v[78:81]
	s_setprio 0
	s_setprio 1
	v_mfma_f32_16x16x32_bf16 v[114:117], v[160:163], v[176:179], v[114:117]
	v_mfma_f32_16x16x32_bf16 v[106:109], v[168:171], v[176:179], v[106:109]
	v_mfma_f32_16x16x32_bf16 v[98:101], v[160:163], v[184:187], v[98:101]
	v_mfma_f32_16x16x32_bf16 v[90:93], v[168:171], v[184:187], v[90:93]
	v_mfma_f32_16x16x32_bf16 v[82:85], v[160:163], v[192:195], v[82:85]
	v_mfma_f32_16x16x32_bf16 v[74:77], v[168:171], v[192:195], v[74:77]
	v_mfma_f32_16x16x32_bf16 v[70:73], v[160:163], v[206:209], v[70:73]
	v_mfma_f32_16x16x32_bf16 v[66:69], v[168:171], v[206:209], v[66:69]
	v_mfma_f32_16x16x32_bf16 v[114:117], v[164:167], v[180:183], v[114:117]
	v_mfma_f32_16x16x32_bf16 v[106:109], v[172:175], v[180:183], v[106:109]
	v_mfma_f32_16x16x32_bf16 v[98:101], v[164:167], v[188:191], v[98:101]
	v_mfma_f32_16x16x32_bf16 v[90:93], v[172:175], v[188:191], v[90:93]
	v_mfma_f32_16x16x32_bf16 v[82:85], v[164:167], v[202:205], v[82:85]
	v_mfma_f32_16x16x32_bf16 v[74:77], v[172:175], v[202:205], v[74:77]
	v_mfma_f32_16x16x32_bf16 v[70:73], v[164:167], v[210:213], v[70:73]
	v_mfma_f32_16x16x32_bf16 v[66:69], v[172:175], v[210:213], v[66:69]
	s_setprio 0
	s_barrier
; #define PG8_STAGE(bufoff, gbase, voff) do { _Pragma("unroll") for (int _i = 0; _i < 2; ++_i) \
;         __builtin_amdgcn_global_load_lds((const unsigned*)((const char*)(gbase) + (voff)[_i]), (LAS unsigned*)(lds + (bufoff) + ldsw + _i * 8192), 16, 0, 0); } while (0)
; #define PG8_WAIT_V(n) asm volatile("s_waitcnt vmcnt(" #n ")" ::: "memory")
; #define PG8_WAIT_L(n) asm volatile("s_waitcnt lgkmcnt(" #n ")" ::: "memory")
; #define PG8_BAR __builtin_amdgcn_s_barrier()
; #define PG8_SCHED __builtin_amdgcn_sched_barrier(0)
; template <bool F8 = false, class Epi, class Sched>
; __device__ __forceinline__ void gemm_phase(LAS unsigned char* lds, const int lda, const int ldb, const int K, const Sched& S, const Epi& E) {
;     ...
;             PG8_LDA(At, 1, 1); PG8_STAGE(PG8_SB(1, 0), b3, voffB); PG8_STAGE(PG8_SB(1, 1), b3 + hstepB, voffB); PG8_STAGE(PG8_SA(1, 0), a3, voffA);
;             PG8_WAIT_V(8); PG8_WAIT_L(0); PG8_BAR; PG8_MMA(1, 0, At, B0); PG8_MMA(1, 1, At, B1); PG8_BAR; PG8_SCHED;
;         }
;         if (wr == 0) PG8_BAR;
	s_add_i32 s20, s29, s24
	v_lshl_add_u64 v[138:139], v[138:139], 0, s[40:41]
	s_mov_b32 m0, s20
	ds_read_b128 v[176:179], v142 offset:49152
	ds_read_b128 v[180:183], v142 offset:50176
	ds_read_b128 v[184:187], v142 offset:51200
	ds_read_b128 v[188:191], v142 offset:52224
	ds_read_b128 v[192:195], v142 offset:53248
	ds_read_b128 v[202:205], v142 offset:54272
	ds_read_b128 v[206:209], v142 offset:55296
	ds_read_b128 v[210:213], v142 offset:56320
	global_load_lds_dwordx4 v[138:139], off
	s_add_i32 m0, s20, 0x2000
	s_add_u32 s18, s18, 0x80080
	v_lshl_add_u64 v[138:139], v[214:215], 0, s[40:41]
	s_addc_u32 s19, s19, 0
	s_add_i32 s20, s30, s24
	global_load_lds_dwordx4 v[138:139], off
	v_lshl_add_u64 v[138:139], s[18:19], 0, v[132:133]
	s_mov_b32 m0, s20
	s_nop 0
	global_load_lds_dwordx4 v[138:139], off
	v_lshl_add_u64 v[138:139], s[18:19], 0, v[130:131]
	s_add_i32 m0, s20, 0x2000
	s_nop 0
	global_load_lds_dwordx4 v[138:139], off
	v_lshl_add_u64 v[138:139], v[216:217], 0, s[40:41]
	s_mov_b32 m0, s52
	s_nop 0
	global_load_lds_dwordx4 v[138:139], off
	v_lshl_add_u64 v[138:139], v[218:219], 0, s[40:41]
	s_mov_b32 m0, s53
	s_nop 0
	global_load_lds_dwordx4 v[138:139], off
	s_waitcnt vmcnt(8)
	s_waitcnt lgkmcnt(0)
	s_barrier
	s_setprio 1
	s_waitcnt lgkmcnt(0)
	v_mfma_f32_16x16x32_bf16 v[62:65], v[144:147], v[176:179], v[62:65]
	v_mfma_f32_16x16x32_bf16 v[58:61], v[152:155], v[176:179], v[58:61]
	v_mfma_f32_16x16x32_bf16 v[54:57], v[144:147], v[184:187], v[54:57]
	v_mfma_f32_16x16x32_bf16 v[42:45], v[152:155], v[184:187], v[42:45]
	v_mfma_f32_16x16x32_bf16 v[38:41], v[144:147], v[192:195], v[38:41]
	v_mfma_f32_16x16x32_bf16 v[26:29], v[152:155], v[192:195], v[26:29]
	v_mfma_f32_16x16x32_bf16 v[22:25], v[144:147], v[206:209], v[22:25]
	v_mfma_f32_16x16x32_bf16 v[10:13], v[152:155], v[206:209], v[10:13]
	v_mfma_f32_16x16x32_bf16 v[62:65], v[148:151], v[180:183], v[62:65]
	v_mfma_f32_16x16x32_bf16 v[58:61], v[156:159], v[180:183], v[58:61]
	v_mfma_f32_16x16x32_bf16 v[54:57], v[148:151], v[188:191], v[54:57]
	v_mfma_f32_16x16x32_bf16 v[42:45], v[156:159], v[188:191], v[42:45]
	v_mfma_f32_16x16x32_bf16 v[38:41], v[148:151], v[202:205], v[38:41]
	v_mfma_f32_16x16x32_bf16 v[26:29], v[156:159], v[202:205], v[26:29]
	v_mfma_f32_16x16x32_bf16 v[22:25], v[148:151], v[210:213], v[22:25]
	v_mfma_f32_16x16x32_bf16 v[10:13], v[156:159], v[210:213], v[10:13]
	s_setprio 0
	s_setprio 1
	v_mfma_f32_16x16x32_bf16 v[50:53], v[160:163], v[176:179], v[50:53]
	v_mfma_f32_16x16x32_bf16 v[46:49], v[168:171], v[176:179], v[46:49]
	v_mfma_f32_16x16x32_bf16 v[34:37], v[160:163], v[184:187], v[34:37]
	v_mfma_f32_16x16x32_bf16 v[30:33], v[168:171], v[184:187], v[30:33]
	v_mfma_f32_16x16x32_bf16 v[18:21], v[160:163], v[192:195], v[18:21]
	v_mfma_f32_16x16x32_bf16 v[14:17], v[168:171], v[192:195], v[14:17]
	v_mfma_f32_16x16x32_bf16 v[6:9], v[160:163], v[206:209], v[6:9]
	v_mfma_f32_16x16x32_bf16 v[2:5], v[168:171], v[206:209], v[2:5]
	v_mfma_f32_16x16x32_bf16 v[50:53], v[164:167], v[180:183], v[50:53]
	v_mfma_f32_16x16x32_bf16 v[46:49], v[172:175], v[180:183], v[46:49]
	v_mfma_f32_16x16x32_bf16 v[34:37], v[164:167], v[188:191], v[34:37]
	v_mfma_f32_16x16x32_bf16 v[30:33], v[172:175], v[188:191], v[30:33]
	v_mfma_f32_16x16x32_bf16 v[18:21], v[164:167], v[202:205], v[18:21]
	v_mfma_f32_16x16x32_bf16 v[14:17], v[172:175], v[202:205], v[14:17]
	v_mfma_f32_16x16x32_bf16 v[6:9], v[164:167], v[210:213], v[6:9]
	v_mfma_f32_16x16x32_bf16 v[2:5], v[172:175], v[210:213], v[2:5]
	s_add_i32 s28, s28, 2
	s_add_u32 s16, s16, 0x100
	s_addc_u32 s17, s17, 0
	s_add_u32 s95, s95, 0x100
	s_addc_u32 s96, s96, 0
	s_cmp_gt_u32 s28, 5
	s_setprio 0
	s_barrier
	s_cbranch_scc0 .LBB0_835
	s_and_b64 vcc, exec, s[6:7]
	s_cbranch_vccz .LBB0_838
	s_barrier

; #define PG8_STAGE(bufoff, gbase, voff) do { _Pragma("unroll") for (int _i = 0; _i < 2; ++_i) \
;         __builtin_amdgcn_global_load_lds((const unsigned*)((const char*)(gbase) + (voff)[_i]), (LAS unsigned*)(lds + (bufoff) + ldsw + _i * 8192), 16, 0, 0); } while (0)
; #define PG8_WAIT_V(n) asm volatile("s_waitcnt vmcnt(" #n ")" ::: "memory")
; #define PG8_WAIT_L(n) asm volatile("s_waitcnt lgkmcnt(" #n ")" ::: "memory")
; #define PG8_BAR __builtin_amdgcn_s_barrier()
; #define PG8_SCHED __builtin_amdgcn_sched_barrier(0)
; template <bool F8 = false, class Epi, class Sched>
; __device__ __forceinline__ void gemm_phase(LAS unsigned char* lds, const int lda, const int ldb, const int K, const Sched& S, const Epi& E) {
;     ...
;             const bool last = (t == nt - 2);
;             const char* a1 = cA + (size_t)(t + 1) * kstep;
;             const char* a2 = last ? nA : cA + (size_t)(t + 2) * kstep; const char* b2 = last ? nB : cB + (size_t)(t + 2) * kstep;
;             const char* a3 = a2 + kstep; const char* b3 = b2 + kstep;
;             PG8_LDB(B0, 0, 0); PG8_LDB(B1, 0, 1); PG8_SCHED; PG8_LDA(At, 0, 0); PG8_STAGE(PG8_SA(1, 1), a1 + hstepA, voffA);
;             PG8_WAIT_V(8); PG8_WAIT_L(0); PG8_BAR; PG8_MMA(0, 0, At, B0); PG8_MMA(0, 1, At, B1); PG8_BAR; PG8_SCHED;
;             PG8_LDA(At, 0, 1); PG8_STAGE(PG8_SB(0, 0), b2, voffB); PG8_STAGE(PG8_SB(0, 1), b2 + hstepB, voffB); PG8_STAGE(PG8_SA(0, 0), a2, voffA);
;             PG8_WAIT_V(8); PG8_WAIT_L(0); PG8_BAR; PG8_MMA(1, 0, At, B0); PG8_MMA(1, 1, At, B1); PG8_BAR; PG8_SCHED;
.LBB0_1062:
	s_add_u32 s30, vcc_lo, 0xfff80080
	s_addc_u32 s31, vcc_hi, -1
	s_add_i32 s33, 0, 0x10000
	s_cmp_eq_u32 s29, 28
	s_cselect_b32 s75, s13, s31
	s_cselect_b32 s74, s26, s30
	s_cselect_b32 s53, s9, s28
	s_cselect_b32 s52, s27, s73
	s_add_i32 s93, 0, 0x14000
	v_add_u32_e32 v152, s33, v141
	v_add_u32_e32 v168, s93, v141
	ds_read_b128 v[136:139], v152
	ds_read_b128 v[144:147], v152 offset:1024
	ds_read_b128 v[148:151], v152 offset:2048
	ds_read_b128 v[152:155], v152 offset:3072
	ds_read_b128 v[156:159], v168
	ds_read_b128 v[160:163], v168 offset:1024
	ds_read_b128 v[164:167], v168 offset:2048
	ds_read_b128 v[168:171], v168 offset:3072
	v_lshl_add_u64 v[210:211], vcc, 0, v[132:133]
	s_add_i32 m0, s19, 0xc000
	ds_read_b128 v[172:175], v143
	ds_read_b128 v[176:179], v143 offset:1024
	ds_read_b128 v[180:183], v143 offset:2048
	ds_read_b128 v[184:187], v143 offset:3072
	ds_read_b128 v[188:191], v143 offset:4096
	ds_read_b128 v[192:195], v143 offset:5120
	ds_read_b128 v[202:205], v143 offset:6144
	ds_read_b128 v[206:209], v143 offset:7168
	global_load_lds_dwordx4 v[210:211], off
	v_lshl_add_u64 v[210:211], vcc, 0, v[134:135]
	s_add_i32 m0, s19, 0xe000
	s_nop 0
	global_load_lds_dwordx4 v[210:211], off
	s_waitcnt vmcnt(8)
	s_waitcnt lgkmcnt(0)
	s_barrier
	s_setprio 1
	s_waitcnt lgkmcnt(0)
	v_mfma_f32_16x16x32_bf16 v[126:129], v[136:139], v[172:175], v[126:129]
	v_mfma_f32_16x16x32_bf16 v[122:125], v[148:151], v[172:175], v[122:125]
	v_mfma_f32_16x16x32_bf16 v[110:113], v[136:139], v[180:183], v[110:113]
	v_mfma_f32_16x16x32_bf16 v[106:109], v[148:151], v[180:183], v[106:109]
	v_mfma_f32_16x16x32_bf16 v[94:97], v[136:139], v[188:191], v[94:97]
	v_mfma_f32_16x16x32_bf16 v[90:93], v[148:151], v[188:191], v[90:93]
	v_mfma_f32_16x16x32_bf16 v[78:81], v[136:139], v[202:205], v[78:81]
	v_mfma_f32_16x16x32_bf16 v[74:77], v[148:151], v[202:205], v[74:77]
	v_mfma_f32_16x16x32_bf16 v[126:129], v[144:147], v[176:179], v[126:129]
	v_mfma_f32_16x16x32_bf16 v[122:125], v[152:155], v[176:179], v[122:125]
	v_mfma_f32_16x16x32_bf16 v[110:113], v[144:147], v[184:187], v[110:113]
	v_mfma_f32_16x16x32_bf16 v[106:109], v[152:155], v[184:187], v[106:109]
	v_mfma_f32_16x16x32_bf16 v[94:97], v[144:147], v[192:195], v[94:97]
	v_mfma_f32_16x16x32_bf16 v[90:93], v[152:155], v[192:195], v[90:93]
	v_mfma_f32_16x16x32_bf16 v[78:81], v[144:147], v[206:209], v[78:81]
	v_mfma_f32_16x16x32_bf16 v[74:77], v[152:155], v[206:209], v[74:77]
	s_setprio 0
	s_setprio 1
	v_mfma_f32_16x16x32_bf16 v[118:121], v[156:159], v[172:175], v[118:121]
	v_mfma_f32_16x16x32_bf16 v[114:117], v[164:167], v[172:175], v[114:117]
	v_mfma_f32_16x16x32_bf16 v[102:105], v[156:159], v[180:183], v[102:105]
	v_mfma_f32_16x16x32_bf16 v[98:101], v[164:167], v[180:183], v[98:101]
	v_mfma_f32_16x16x32_bf16 v[86:89], v[156:159], v[188:191], v[86:89]
	v_mfma_f32_16x16x32_bf16 v[82:85], v[164:167], v[188:191], v[82:85]
	v_mfma_f32_16x16x32_bf16 v[70:73], v[156:159], v[202:205], v[70:73]
	v_mfma_f32_16x16x32_bf16 v[66:69], v[164:167], v[202:205], v[66:69]
	v_mfma_f32_16x16x32_bf16 v[118:121], v[160:163], v[176:179], v[118:121]
	v_mfma_f32_16x16x32_bf16 v[114:117], v[168:171], v[176:179], v[114:117]
	v_mfma_f32_16x16x32_bf16 v[102:105], v[160:163], v[184:187], v[102:105]
	v_mfma_f32_16x16x32_bf16 v[98:101], v[168:171], v[184:187], v[98:101]
	v_mfma_f32_16x16x32_bf16 v[86:89], v[160:163], v[192:195], v[86:89]
	v_mfma_f32_16x16x32_bf16 v[82:85], v[168:171], v[192:195], v[82:85]
	v_mfma_f32_16x16x32_bf16 v[70:73], v[160:163], v[206:209], v[70:73]
	v_mfma_f32_16x16x32_bf16 v[66:69], v[168:171], v[206:209], v[66:69]
	s_setprio 0
	s_barrier
	s_add_i32 s30, s33, s94
	v_lshl_add_u64 v[210:211], s[52:53], 0, v[0:1]
	s_mov_b32 m0, s30
	ds_read_b128 v[172:175], v143 offset:16384
	ds_read_b128 v[176:179], v143 offset:17408
	ds_read_b128 v[180:183], v143 offset:18432
	ds_read_b128 v[184:187], v143 offset:19456
	ds_read_b128 v[188:191], v143 offset:20480
	ds_read_b128 v[192:195], v143 offset:21504
	ds_read_b128 v[202:205], v143 offset:22528
	ds_read_b128 v[206:209], v143 offset:23552
	global_load_lds_dwordx4 v[210:211], off
	s_add_i32 m0, s30, 0x2000
	s_add_u32 s30, s52, 0x80000
	v_lshl_add_u64 v[212:213], s[52:53], 0, v[130:131]
	s_addc_u32 s31, s53, 0
	s_add_i32 s33, s93, s94
	global_load_lds_dwordx4 v[212:213], off
	v_lshl_add_u64 v[214:215], s[30:31], 0, v[0:1]
	s_mov_b32 m0, s33
	v_lshl_add_u64 v[216:217], s[74:75], 0, v[130:131]
	global_load_lds_dwordx4 v[214:215], off
	v_lshl_add_u64 v[214:215], s[30:31], 0, v[130:131]
	s_add_i32 m0, s33, 0x2000
	s_nop 0
	global_load_lds_dwordx4 v[214:215], off
	v_lshl_add_u64 v[214:215], s[74:75], 0, v[0:1]
	s_mov_b32 m0, s19
	s_nop 0
	global_load_lds_dwordx4 v[214:215], off
	s_mov_b32 m0, s56
	s_nop 0
	global_load_lds_dwordx4 v[216:217], off
	s_waitcnt vmcnt(8)
	s_waitcnt lgkmcnt(0)
	s_barrier
; #define PG8_STAGE(bufoff, gbase, voff) do { _Pragma("unroll") for (int _i = 0; _i < 2; ++_i) \
;         __builtin_amdgcn_global_load_lds((const unsigned*)((const char*)(gbase) + (voff)[_i]), (LAS unsigned*)(lds + (bufoff) + ldsw + _i * 8192), 16, 0, 0); } while (0)
; #define PG8_WAIT_V(n) asm volatile("s_waitcnt vmcnt(" #n ")" ::: "memory")
; #define PG8_WAIT_L(n) asm volatile("s_waitcnt lgkmcnt(" #n ")" ::: "memory")
; #define PG8_BAR __builtin_amdgcn_s_barrier()
; #define PG8_SCHED __builtin_amdgcn_sched_barrier(0)
; template <bool F8 = false, class Epi, class Sched>
; __device__ __forceinline__ void gemm_phase(LAS unsigned char* lds, const int lda, const int ldb, const int K, const Sched& S, const Epi& E) {
;     ...
;             PG8_WAIT_V(8); PG8_WAIT_L(0); PG8_BAR; PG8_MMA(1, 0, At, B0); PG8_MMA(1, 1, At, B1); PG8_BAR; PG8_SCHED;
;             PG8_LDB(B0, 1, 0); PG8_LDB(B1, 1, 1); PG8_SCHED; PG8_LDA(At, 1, 0); PG8_STAGE(PG8_SA(0, 1), a2 + hstepA, voffA);
;             PG8_WAIT_V(8); PG8_WAIT_L(0); PG8_BAR; PG8_MMA(0, 0, At, B0); PG8_MMA(0, 1, At, B1); PG8_BAR; PG8_SCHED;
	s_setprio 1
	s_waitcnt lgkmcnt(0)
	v_mfma_f32_16x16x32_bf16 v[62:65], v[136:139], v[172:175], v[62:65]
	v_mfma_f32_16x16x32_bf16 v[58:61], v[148:151], v[172:175], v[58:61]
	v_mfma_f32_16x16x32_bf16 v[46:49], v[136:139], v[180:183], v[46:49]
	v_mfma_f32_16x16x32_bf16 v[42:45], v[148:151], v[180:183], v[42:45]
	v_mfma_f32_16x16x32_bf16 v[30:33], v[136:139], v[188:191], v[30:33]
	v_mfma_f32_16x16x32_bf16 v[26:29], v[148:151], v[188:191], v[26:29]
	v_mfma_f32_16x16x32_bf16 v[14:17], v[136:139], v[202:205], v[14:17]
	v_mfma_f32_16x16x32_bf16 v[10:13], v[148:151], v[202:205], v[10:13]
	v_mfma_f32_16x16x32_bf16 v[62:65], v[144:147], v[176:179], v[62:65]
	v_mfma_f32_16x16x32_bf16 v[58:61], v[152:155], v[176:179], v[58:61]
	v_mfma_f32_16x16x32_bf16 v[46:49], v[144:147], v[184:187], v[46:49]
	v_mfma_f32_16x16x32_bf16 v[42:45], v[152:155], v[184:187], v[42:45]
	v_mfma_f32_16x16x32_bf16 v[30:33], v[144:147], v[192:195], v[30:33]
	v_mfma_f32_16x16x32_bf16 v[26:29], v[152:155], v[192:195], v[26:29]
	v_mfma_f32_16x16x32_bf16 v[14:17], v[144:147], v[206:209], v[14:17]
	v_mfma_f32_16x16x32_bf16 v[10:13], v[152:155], v[206:209], v[10:13]
	s_setprio 0
	s_setprio 1
	v_mfma_f32_16x16x32_bf16 v[54:57], v[156:159], v[172:175], v[54:57]
	v_mfma_f32_16x16x32_bf16 v[50:53], v[164:167], v[172:175], v[50:53]
	v_mfma_f32_16x16x32_bf16 v[38:41], v[156:159], v[180:183], v[38:41]
	v_mfma_f32_16x16x32_bf16 v[34:37], v[164:167], v[180:183], v[34:37]
	v_mfma_f32_16x16x32_bf16 v[22:25], v[156:159], v[188:191], v[22:25]
	v_mfma_f32_16x16x32_bf16 v[18:21], v[164:167], v[188:191], v[18:21]
	v_mfma_f32_16x16x32_bf16 v[6:9], v[156:159], v[202:205], v[6:9]
	v_mfma_f32_16x16x32_bf16 v[2:5], v[164:167], v[202:205], v[2:5]
	v_mfma_f32_16x16x32_bf16 v[54:57], v[160:163], v[176:179], v[54:57]
	v_mfma_f32_16x16x32_bf16 v[50:53], v[168:171], v[176:179], v[50:53]
	v_mfma_f32_16x16x32_bf16 v[38:41], v[160:163], v[184:187], v[38:41]
	v_mfma_f32_16x16x32_bf16 v[34:37], v[168:171], v[184:187], v[34:37]
	v_mfma_f32_16x16x32_bf16 v[22:25], v[160:163], v[192:195], v[22:25]
	v_mfma_f32_16x16x32_bf16 v[18:21], v[168:171], v[192:195], v[18:21]
	v_mfma_f32_16x16x32_bf16 v[6:9], v[160:163], v[206:209], v[6:9]
	v_mfma_f32_16x16x32_bf16 v[2:5], v[168:171], v[206:209], v[2:5]
	s_setprio 0
	s_barrier
	s_add_i32 s33, 0, 0x18000
	s_add_i32 s93, 0, 0x1c000
	v_add_u32_e32 v152, s33, v141
	v_add_u32_e32 v168, s93, v141
	ds_read_b128 v[136:139], v152
	ds_read_b128 v[144:147], v152 offset:1024
	ds_read_b128 v[148:151], v152 offset:2048
	ds_read_b128 v[152:155], v152 offset:3072
	ds_read_b128 v[156:159], v168
	ds_read_b128 v[160:163], v168 offset:1024
	ds_read_b128 v[164:167], v168 offset:2048
	ds_read_b128 v[168:171], v168 offset:3072
	s_add_u32 s30, s74, 0x80000
	s_addc_u32 s31, s75, 0
	s_mov_b32 m0, s57
	v_lshl_add_u64 v[218:219], s[30:31], 0, v[0:1]
	ds_read_b128 v[172:175], v143 offset:32768
	ds_read_b128 v[176:179], v143 offset:33792
	ds_read_b128 v[180:183], v143 offset:34816
	ds_read_b128 v[184:187], v143 offset:35840
	ds_read_b128 v[188:191], v143 offset:36864
	ds_read_b128 v[192:195], v143 offset:37888
	ds_read_b128 v[202:205], v143 offset:38912
	ds_read_b128 v[206:209], v143 offset:39936
	global_load_lds_dwordx4 v[218:219], off
	v_lshl_add_u64 v[218:219], s[30:31], 0, v[130:131]
	s_mov_b32 m0, s96
	s_nop 0
	global_load_lds_dwordx4 v[218:219], off
	s_waitcnt vmcnt(8)
	s_waitcnt lgkmcnt(0)
	s_barrier
	s_setprio 1
	s_waitcnt lgkmcnt(0)
	v_mfma_f32_16x16x32_bf16 v[126:129], v[136:139], v[172:175], v[126:129]
	v_mfma_f32_16x16x32_bf16 v[122:125], v[148:151], v[172:175], v[122:125]
	v_mfma_f32_16x16x32_bf16 v[110:113], v[136:139], v[180:183], v[110:113]
	v_mfma_f32_16x16x32_bf16 v[106:109], v[148:151], v[180:183], v[106:109]
	v_mfma_f32_16x16x32_bf16 v[94:97], v[136:139], v[188:191], v[94:97]
	v_mfma_f32_16x16x32_bf16 v[90:93], v[148:151], v[188:191], v[90:93]
	v_mfma_f32_16x16x32_bf16 v[78:81], v[136:139], v[202:205], v[78:81]
	v_mfma_f32_16x16x32_bf16 v[74:77], v[148:151], v[202:205], v[74:77]
	v_mfma_f32_16x16x32_bf16 v[126:129], v[144:147], v[176:179], v[126:129]
	v_mfma_f32_16x16x32_bf16 v[122:125], v[152:155], v[176:179], v[122:125]
	v_mfma_f32_16x16x32_bf16 v[110:113], v[144:147], v[184:187], v[110:113]
	v_mfma_f32_16x16x32_bf16 v[106:109], v[152:155], v[184:187], v[106:109]
	v_mfma_f32_16x16x32_bf16 v[94:97], v[144:147], v[192:195], v[94:97]
	v_mfma_f32_16x16x32_bf16 v[90:93], v[152:155], v[192:195], v[90:93]
	v_mfma_f32_16x16x32_bf16 v[78:81], v[144:147], v[206:209], v[78:81]
	v_mfma_f32_16x16x32_bf16 v[74:77], v[152:155], v[206:209], v[74:77]
	s_setprio 0
	s_setprio 1
	v_mfma_f32_16x16x32_bf16 v[118:121], v[156:159], v[172:175], v[118:121]
	v_mfma_f32_16x16x32_bf16 v[114:117], v[164:167], v[172:175], v[114:117]
	v_mfma_f32_16x16x32_bf16 v[102:105], v[156:159], v[180:183], v[102:105]
	v_mfma_f32_16x16x32_bf16 v[98:101], v[164:167], v[180:183], v[98:101]
	v_mfma_f32_16x16x32_bf16 v[86:89], v[156:159], v[188:191], v[86:89]
	v_mfma_f32_16x16x32_bf16 v[82:85], v[164:167], v[188:191], v[82:85]
	v_mfma_f32_16x16x32_bf16 v[70:73], v[156:159], v[202:205], v[70:73]
	v_mfma_f32_16x16x32_bf16 v[66:69], v[164:167], v[202:205], v[66:69]
	v_mfma_f32_16x16x32_bf16 v[118:121], v[160:163], v[176:179], v[118:121]
	v_mfma_f32_16x16x32_bf16 v[114:117], v[168:171], v[176:179], v[114:117]
	v_mfma_f32_16x16x32_bf16 v[102:105], v[160:163], v[184:187], v[102:105]
	v_mfma_f32_16x16x32_bf16 v[98:101], v[168:171], v[184:187], v[98:101]
	v_mfma_f32_16x16x32_bf16 v[86:89], v[160:163], v[192:195], v[86:89]
	v_mfma_f32_16x16x32_bf16 v[82:85], v[168:171], v[192:195], v[82:85]
	v_mfma_f32_16x16x32_bf16 v[70:73], v[160:163], v[206:209], v[70:73]
	v_mfma_f32_16x16x32_bf16 v[66:69], v[168:171], v[206:209], v[66:69]
	s_setprio 0
	s_barrier
; #define PG8_STAGE(bufoff, gbase, voff) do { _Pragma("unroll") for (int _i = 0; _i < 2; ++_i) \
;         __builtin_amdgcn_global_load_lds((const unsigned*)((const char*)(gbase) + (voff)[_i]), (LAS unsigned*)(lds + (bufoff) + ldsw + _i * 8192), 16, 0, 0); } while (0)
; #define PG8_WAIT_V(n) asm volatile("s_waitcnt vmcnt(" #n ")" ::: "memory")
; #define PG8_WAIT_L(n) asm volatile("s_waitcnt lgkmcnt(" #n ")" ::: "memory")
; #define PG8_BAR __builtin_amdgcn_s_barrier()
; #define PG8_SCHED __builtin_amdgcn_sched_barrier(0)
; template <bool F8 = false, class Epi, class Sched>
; __device__ __forceinline__ void gemm_phase(LAS unsigned char* lds, const int lda, const int ldb, const int K, const Sched& S, const Epi& E) {
;     ...
;             PG8_LDA(At, 1, 1); PG8_STAGE(PG8_SB(1, 0), b3, voffB); PG8_STAGE(PG8_SB(1, 1), b3 + hstepB, voffB); PG8_STAGE(PG8_SA(1, 0), a3, voffA);
;             PG8_WAIT_V(8); PG8_WAIT_L(0); PG8_BAR; PG8_MMA(1, 0, At, B0); PG8_MMA(1, 1, At, B1); PG8_BAR; PG8_SCHED;
;         }
;         if (wr == 0) PG8_BAR;
	s_add_i32 s30, s33, s94
	v_lshl_add_u64 v[210:211], v[210:211], 0, s[40:41]
	s_mov_b32 m0, s30
	ds_read_b128 v[172:175], v143 offset:49152
	ds_read_b128 v[176:179], v143 offset:50176
	ds_read_b128 v[180:183], v143 offset:51200
	ds_read_b128 v[184:187], v143 offset:52224
	ds_read_b128 v[188:191], v143 offset:53248
	ds_read_b128 v[192:195], v143 offset:54272
	ds_read_b128 v[202:205], v143 offset:55296
	ds_read_b128 v[206:209], v143 offset:56320
	global_load_lds_dwordx4 v[210:211], off
	s_add_i32 m0, s30, 0x2000
	s_add_u32 s30, s52, 0x80080
	v_lshl_add_u64 v[210:211], v[212:213], 0, s[40:41]
	s_addc_u32 s31, s53, 0
	s_add_i32 s33, s93, s94
	global_load_lds_dwordx4 v[210:211], off
	v_lshl_add_u64 v[210:211], s[30:31], 0, v[0:1]
	s_mov_b32 m0, s33
	s_nop 0
	global_load_lds_dwordx4 v[210:211], off
	v_lshl_add_u64 v[210:211], s[30:31], 0, v[130:131]
	s_add_i32 m0, s33, 0x2000
	s_nop 0
	global_load_lds_dwordx4 v[210:211], off
	v_lshl_add_u64 v[210:211], v[214:215], 0, s[40:41]
	s_mov_b32 m0, s24
	s_nop 0
	global_load_lds_dwordx4 v[210:211], off
	v_lshl_add_u64 v[210:211], v[216:217], 0, s[40:41]
	s_mov_b32 m0, s25
	s_nop 0
	global_load_lds_dwordx4 v[210:211], off
	s_waitcnt vmcnt(8)
	s_waitcnt lgkmcnt(0)
	s_barrier
	s_setprio 1
	s_waitcnt lgkmcnt(0)
	v_mfma_f32_16x16x32_bf16 v[62:65], v[136:139], v[172:175], v[62:65]
	v_mfma_f32_16x16x32_bf16 v[58:61], v[148:151], v[172:175], v[58:61]
	v_mfma_f32_16x16x32_bf16 v[46:49], v[136:139], v[180:183], v[46:49]
	v_mfma_f32_16x16x32_bf16 v[42:45], v[148:151], v[180:183], v[42:45]
	v_mfma_f32_16x16x32_bf16 v[30:33], v[136:139], v[188:191], v[30:33]
	v_mfma_f32_16x16x32_bf16 v[26:29], v[148:151], v[188:191], v[26:29]
	v_mfma_f32_16x16x32_bf16 v[14:17], v[136:139], v[202:205], v[14:17]
	v_mfma_f32_16x16x32_bf16 v[10:13], v[148:151], v[202:205], v[10:13]
	v_mfma_f32_16x16x32_bf16 v[62:65], v[144:147], v[176:179], v[62:65]
	v_mfma_f32_16x16x32_bf16 v[58:61], v[152:155], v[176:179], v[58:61]
	v_mfma_f32_16x16x32_bf16 v[46:49], v[144:147], v[184:187], v[46:49]
	v_mfma_f32_16x16x32_bf16 v[42:45], v[152:155], v[184:187], v[42:45]
	v_mfma_f32_16x16x32_bf16 v[30:33], v[144:147], v[192:195], v[30:33]
	v_mfma_f32_16x16x32_bf16 v[26:29], v[152:155], v[192:195], v[26:29]
	v_mfma_f32_16x16x32_bf16 v[14:17], v[144:147], v[206:209], v[14:17]
	v_mfma_f32_16x16x32_bf16 v[10:13], v[152:155], v[206:209], v[10:13]
	s_setprio 0
	s_setprio 1
	v_mfma_f32_16x16x32_bf16 v[54:57], v[156:159], v[172:175], v[54:57]
	v_mfma_f32_16x16x32_bf16 v[50:53], v[164:167], v[172:175], v[50:53]
	v_mfma_f32_16x16x32_bf16 v[38:41], v[156:159], v[180:183], v[38:41]
	v_mfma_f32_16x16x32_bf16 v[34:37], v[164:167], v[180:183], v[34:37]
	v_mfma_f32_16x16x32_bf16 v[22:25], v[156:159], v[188:191], v[22:25]
	v_mfma_f32_16x16x32_bf16 v[18:21], v[164:167], v[188:191], v[18:21]
	v_mfma_f32_16x16x32_bf16 v[6:9], v[156:159], v[202:205], v[6:9]
	v_mfma_f32_16x16x32_bf16 v[2:5], v[164:167], v[202:205], v[2:5]
	v_mfma_f32_16x16x32_bf16 v[54:57], v[160:163], v[176:179], v[54:57]
	v_mfma_f32_16x16x32_bf16 v[50:53], v[168:171], v[176:179], v[50:53]
	v_mfma_f32_16x16x32_bf16 v[38:41], v[160:163], v[184:187], v[38:41]
	v_mfma_f32_16x16x32_bf16 v[34:37], v[168:171], v[184:187], v[34:37]
	v_mfma_f32_16x16x32_bf16 v[22:25], v[160:163], v[192:195], v[22:25]
	v_mfma_f32_16x16x32_bf16 v[18:21], v[168:171], v[192:195], v[18:21]
	v_mfma_f32_16x16x32_bf16 v[6:9], v[160:163], v[206:209], v[6:9]
	v_mfma_f32_16x16x32_bf16 v[2:5], v[168:171], v[206:209], v[2:5]
	s_add_i32 s29, s29, 2
	s_add_u32 vcc_lo, vcc_lo, 0x100
	s_addc_u32 vcc_hi, vcc_hi, 0
	s_add_u32 s73, s73, 0x100
	s_addc_u32 s28, s28, 0
	s_cmp_gt_u32 s29, 29
	s_setprio 0
	s_barrier
	s_cbranch_scc0 .LBB0_1062
	s_and_b64 vcc, exec, s[6:7]
	s_cbranch_vccz .LBB0_1065
	s_barrier

; #define PG8_STAGE(bufoff, gbase, voff) do { _Pragma("unroll") for (int _i = 0; _i < 2; ++_i) \
;         __builtin_amdgcn_global_load_lds((const unsigned*)((const char*)(gbase) + (voff)[_i]), (LAS unsigned*)(lds + (bufoff) + ldsw + _i * 8192), 16, 0, 0); } while (0)
; #define PG8_WAIT_V(n) asm volatile("s_waitcnt vmcnt(" #n ")" ::: "memory")
; #define PG8_WAIT_L(n) asm volatile("s_waitcnt lgkmcnt(" #n ")" ::: "memory")
; #define PG8_BAR __builtin_amdgcn_s_barrier()
; #define PG8_SCHED __builtin_amdgcn_sched_barrier(0)
; template <bool F8 = false, class Epi, class Sched>
; __device__ __forceinline__ void gemm_phase(LAS unsigned char* lds, const int lda, const int ldb, const int K, const Sched& S, const Epi& E) {
;     ...
;             const bool last = (t == nt - 2);
;             const char* a1 = cA + (size_t)(t + 1) * kstep;
;             const char* a2 = last ? nA : cA + (size_t)(t + 2) * kstep; const char* b2 = last ? nB : cB + (size_t)(t + 2) * kstep;
;             const char* a3 = a2 + kstep; const char* b3 = b2 + kstep;
;             PG8_LDB(B0, 0, 0); PG8_LDB(B1, 0, 1); PG8_SCHED; PG8_LDA(At, 0, 0); PG8_STAGE(PG8_SA(1, 1), a1 + hstepA, voffA);
;             PG8_WAIT_V(8); PG8_WAIT_L(0); PG8_BAR; PG8_MMA(0, 0, At, B0); PG8_MMA(0, 1, At, B1); PG8_BAR; PG8_SCHED;
;             PG8_LDA(At, 0, 1); PG8_STAGE(PG8_SB(0, 0), b2, voffB); PG8_STAGE(PG8_SB(0, 1), b2 + hstepB, voffB); PG8_STAGE(PG8_SA(0, 0), a2, voffA);
;             PG8_WAIT_V(8); PG8_WAIT_L(0); PG8_BAR; PG8_MMA(1, 0, At, B0); PG8_MMA(1, 1, At, B1); PG8_BAR; PG8_SCHED;
.LBB0_1149:
	s_add_u32 s18, s16, 0x100
	s_addc_u32 s19, s17, 0
	s_add_i32 s30, 0, 0x10000
	s_cmpk_eq_i32 s94, 0x54
	s_cselect_b32 s53, s13, s19
	s_cselect_b32 s52, s12, s18
	v_add_u32_e32 v140, s30, v143
	s_cselect_b32 s21, s15, s29
	s_cselect_b32 s20, s14, s28
	s_add_i32 s31, 0, 0x14000
	ds_read_b128 v[146:149], v140
	ds_read_b128 v[150:153], v140 offset:1024
	ds_read_b128 v[154:157], v140 offset:2048
	ds_read_b128 v[158:161], v140 offset:3072
	v_add_u32_e32 v140, s31, v143
	ds_read_b128 v[162:165], v140
	ds_read_b128 v[166:169], v140 offset:1024
	ds_read_b128 v[170:173], v140 offset:2048
	ds_read_b128 v[174:177], v140 offset:3072
	v_lshl_add_u64 v[140:141], s[16:17], 0, v[136:137]
	s_add_i32 m0, s25, 0xc000
	ds_read_b128 v[178:181], v145
	ds_read_b128 v[182:185], v145 offset:1024
	ds_read_b128 v[186:189], v145 offset:2048
	ds_read_b128 v[190:193], v145 offset:3072
	ds_read_b128 v[202:205], v145 offset:4096
	ds_read_b128 v[206:209], v145 offset:5120
	ds_read_b128 v[210:213], v145 offset:6144
	ds_read_b128 v[214:217], v145 offset:7168
	global_load_lds_dwordx4 v[140:141], off
	v_lshl_add_u64 v[140:141], s[16:17], 0, v[138:139]
	s_add_i32 m0, s25, 0xe000
	s_nop 0
	global_load_lds_dwordx4 v[140:141], off
	s_waitcnt vmcnt(8)
	s_waitcnt lgkmcnt(0)
	s_barrier
	s_setprio 1
	s_waitcnt lgkmcnt(0)
	v_mfma_f32_16x16x32_bf16 v[126:129], v[146:149], v[178:181], v[126:129]
	v_mfma_f32_16x16x32_bf16 v[122:125], v[154:157], v[178:181], v[122:125]
	v_mfma_f32_16x16x32_bf16 v[118:121], v[146:149], v[186:189], v[118:121]
	v_mfma_f32_16x16x32_bf16 v[110:113], v[154:157], v[186:189], v[110:113]
	v_mfma_f32_16x16x32_bf16 v[102:105], v[146:149], v[202:205], v[102:105]
	v_mfma_f32_16x16x32_bf16 v[94:97], v[154:157], v[202:205], v[94:97]
	v_mfma_f32_16x16x32_bf16 v[86:89], v[146:149], v[210:213], v[86:89]
	v_mfma_f32_16x16x32_bf16 v[78:81], v[154:157], v[210:213], v[78:81]
	v_mfma_f32_16x16x32_bf16 v[126:129], v[150:153], v[182:185], v[126:129]
	v_mfma_f32_16x16x32_bf16 v[122:125], v[158:161], v[182:185], v[122:125]
	v_mfma_f32_16x16x32_bf16 v[118:121], v[150:153], v[190:193], v[118:121]
	v_mfma_f32_16x16x32_bf16 v[110:113], v[158:161], v[190:193], v[110:113]
	v_mfma_f32_16x16x32_bf16 v[102:105], v[150:153], v[206:209], v[102:105]
	v_mfma_f32_16x16x32_bf16 v[94:97], v[158:161], v[206:209], v[94:97]
	v_mfma_f32_16x16x32_bf16 v[86:89], v[150:153], v[214:217], v[86:89]
	v_mfma_f32_16x16x32_bf16 v[78:81], v[158:161], v[214:217], v[78:81]
	s_setprio 0
	s_setprio 1
	v_mfma_f32_16x16x32_bf16 v[114:117], v[162:165], v[178:181], v[114:117]
	v_mfma_f32_16x16x32_bf16 v[106:109], v[170:173], v[178:181], v[106:109]
	v_mfma_f32_16x16x32_bf16 v[98:101], v[162:165], v[186:189], v[98:101]
	v_mfma_f32_16x16x32_bf16 v[90:93], v[170:173], v[186:189], v[90:93]
	v_mfma_f32_16x16x32_bf16 v[82:85], v[162:165], v[202:205], v[82:85]
	v_mfma_f32_16x16x32_bf16 v[74:77], v[170:173], v[202:205], v[74:77]
	v_mfma_f32_16x16x32_bf16 v[70:73], v[162:165], v[210:213], v[70:73]
	v_mfma_f32_16x16x32_bf16 v[66:69], v[170:173], v[210:213], v[66:69]
	v_mfma_f32_16x16x32_bf16 v[114:117], v[166:169], v[182:185], v[114:117]
	v_mfma_f32_16x16x32_bf16 v[106:109], v[174:177], v[182:185], v[106:109]
	v_mfma_f32_16x16x32_bf16 v[98:101], v[166:169], v[190:193], v[98:101]
	v_mfma_f32_16x16x32_bf16 v[90:93], v[174:177], v[190:193], v[90:93]
	v_mfma_f32_16x16x32_bf16 v[82:85], v[166:169], v[206:209], v[82:85]
	v_mfma_f32_16x16x32_bf16 v[74:77], v[174:177], v[206:209], v[74:77]
	v_mfma_f32_16x16x32_bf16 v[70:73], v[166:169], v[214:217], v[70:73]
	v_mfma_f32_16x16x32_bf16 v[66:69], v[174:177], v[214:217], v[66:69]
	s_setprio 0
	s_barrier
	s_add_i32 s16, s30, s24
	v_lshl_add_u64 v[140:141], s[20:21], 0, v[0:1]
	s_mov_b32 m0, s16
	ds_read_b128 v[178:181], v145 offset:16384
	ds_read_b128 v[182:185], v145 offset:17408
	ds_read_b128 v[186:189], v145 offset:18432
	ds_read_b128 v[190:193], v145 offset:19456
	ds_read_b128 v[202:205], v145 offset:20480
	ds_read_b128 v[206:209], v145 offset:21504
	ds_read_b128 v[210:213], v145 offset:22528
	ds_read_b128 v[214:217], v145 offset:23552
	global_load_lds_dwordx4 v[140:141], off
	s_add_i32 m0, s16, 0x2000
	s_add_u32 s16, s20, 0x160000
	v_lshl_add_u64 v[194:195], s[20:21], 0, v[130:131]
	s_addc_u32 s17, s21, 0
	s_add_i32 s30, s31, s24
	global_load_lds_dwordx4 v[194:195], off
	v_lshl_add_u64 v[218:219], s[16:17], 0, v[0:1]
	s_mov_b32 m0, s30
	v_lshl_add_u64 v[220:221], s[52:53], 0, v[132:133]
	global_load_lds_dwordx4 v[218:219], off
	v_lshl_add_u64 v[218:219], s[16:17], 0, v[130:131]
	s_add_i32 m0, s30, 0x2000
	s_nop 0
	global_load_lds_dwordx4 v[218:219], off
	v_lshl_add_u64 v[218:219], s[52:53], 0, v[134:135]
	s_mov_b32 m0, s25
	s_nop 0
	global_load_lds_dwordx4 v[218:219], off
	s_mov_b32 m0, s26
	s_nop 0
	global_load_lds_dwordx4 v[220:221], off
	s_waitcnt vmcnt(8)
	s_waitcnt lgkmcnt(0)
	s_barrier
; #define PG8_STAGE(bufoff, gbase, voff) do { _Pragma("unroll") for (int _i = 0; _i < 2; ++_i) \
;         __builtin_amdgcn_global_load_lds((const unsigned*)((const char*)(gbase) + (voff)[_i]), (LAS unsigned*)(lds + (bufoff) + ldsw + _i * 8192), 16, 0, 0); } while (0)
; #define PG8_WAIT_V(n) asm volatile("s_waitcnt vmcnt(" #n ")" ::: "memory")
; #define PG8_WAIT_L(n) asm volatile("s_waitcnt lgkmcnt(" #n ")" ::: "memory")
; #define PG8_BAR __builtin_amdgcn_s_barrier()
; #define PG8_SCHED __builtin_amdgcn_sched_barrier(0)
; template <bool F8 = false, class Epi, class Sched>
; __device__ __forceinline__ void gemm_phase(LAS unsigned char* lds, const int lda, const int ldb, const int K, const Sched& S, const Epi& E) {
;     ...
;             PG8_WAIT_V(8); PG8_WAIT_L(0); PG8_BAR; PG8_MMA(1, 0, At, B0); PG8_MMA(1, 1, At, B1); PG8_BAR; PG8_SCHED;
;             PG8_LDB(B0, 1, 0); PG8_LDB(B1, 1, 1); PG8_SCHED; PG8_LDA(At, 1, 0); PG8_STAGE(PG8_SA(0, 1), a2 + hstepA, voffA);
;             PG8_WAIT_V(8); PG8_WAIT_L(0); PG8_BAR; PG8_MMA(0, 0, At, B0); PG8_MMA(0, 1, At, B1); PG8_BAR; PG8_SCHED;
	s_setprio 1
	s_waitcnt lgkmcnt(0)
	v_mfma_f32_16x16x32_bf16 v[62:65], v[146:149], v[178:181], v[62:65]
	v_mfma_f32_16x16x32_bf16 v[58:61], v[154:157], v[178:181], v[58:61]
	v_mfma_f32_16x16x32_bf16 v[54:57], v[146:149], v[186:189], v[54:57]
	v_mfma_f32_16x16x32_bf16 v[46:49], v[154:157], v[186:189], v[46:49]
	v_mfma_f32_16x16x32_bf16 v[38:41], v[146:149], v[202:205], v[38:41]
	v_mfma_f32_16x16x32_bf16 v[30:33], v[154:157], v[202:205], v[30:33]
	v_mfma_f32_16x16x32_bf16 v[22:25], v[146:149], v[210:213], v[22:25]
	v_mfma_f32_16x16x32_bf16 v[14:17], v[154:157], v[210:213], v[14:17]
	v_mfma_f32_16x16x32_bf16 v[62:65], v[150:153], v[182:185], v[62:65]
	v_mfma_f32_16x16x32_bf16 v[58:61], v[158:161], v[182:185], v[58:61]
	v_mfma_f32_16x16x32_bf16 v[54:57], v[150:153], v[190:193], v[54:57]
	v_mfma_f32_16x16x32_bf16 v[46:49], v[158:161], v[190:193], v[46:49]
	v_mfma_f32_16x16x32_bf16 v[38:41], v[150:153], v[206:209], v[38:41]
	v_mfma_f32_16x16x32_bf16 v[30:33], v[158:161], v[206:209], v[30:33]
	v_mfma_f32_16x16x32_bf16 v[22:25], v[150:153], v[214:217], v[22:25]
	v_mfma_f32_16x16x32_bf16 v[14:17], v[158:161], v[214:217], v[14:17]
	s_setprio 0
	s_setprio 1
	v_mfma_f32_16x16x32_bf16 v[50:53], v[162:165], v[178:181], v[50:53]
	v_mfma_f32_16x16x32_bf16 v[42:45], v[170:173], v[178:181], v[42:45]
	v_mfma_f32_16x16x32_bf16 v[34:37], v[162:165], v[186:189], v[34:37]
	v_mfma_f32_16x16x32_bf16 v[26:29], v[170:173], v[186:189], v[26:29]
	v_mfma_f32_16x16x32_bf16 v[18:21], v[162:165], v[202:205], v[18:21]
	v_mfma_f32_16x16x32_bf16 v[10:13], v[170:173], v[202:205], v[10:13]
	v_mfma_f32_16x16x32_bf16 v[6:9], v[162:165], v[210:213], v[6:9]
	v_mfma_f32_16x16x32_bf16 v[2:5], v[170:173], v[210:213], v[2:5]
	v_mfma_f32_16x16x32_bf16 v[50:53], v[166:169], v[182:185], v[50:53]
	v_mfma_f32_16x16x32_bf16 v[42:45], v[174:177], v[182:185], v[42:45]
	v_mfma_f32_16x16x32_bf16 v[34:37], v[166:169], v[190:193], v[34:37]
	v_mfma_f32_16x16x32_bf16 v[26:29], v[174:177], v[190:193], v[26:29]
	v_mfma_f32_16x16x32_bf16 v[18:21], v[166:169], v[206:209], v[18:21]
	v_mfma_f32_16x16x32_bf16 v[10:13], v[174:177], v[206:209], v[10:13]
	v_mfma_f32_16x16x32_bf16 v[6:9], v[166:169], v[214:217], v[6:9]
	v_mfma_f32_16x16x32_bf16 v[2:5], v[174:177], v[214:217], v[2:5]
	s_setprio 0
	s_barrier
	s_add_i32 s30, 0, 0x18000
	s_add_i32 s31, 0, 0x1c000
	v_add_u32_e32 v158, s30, v143
	v_add_u32_e32 v174, s31, v143
	ds_read_b128 v[146:149], v158
	ds_read_b128 v[150:153], v158 offset:1024
	ds_read_b128 v[154:157], v158 offset:2048
	ds_read_b128 v[158:161], v158 offset:3072
	ds_read_b128 v[162:165], v174
	ds_read_b128 v[166:169], v174 offset:1024
	ds_read_b128 v[170:173], v174 offset:2048
	ds_read_b128 v[174:177], v174 offset:3072
	s_add_u32 s16, s52, 0x160000
	s_addc_u32 s17, s53, 0
	s_mov_b32 m0, s27
	v_lshl_add_u64 v[222:223], s[16:17], 0, v[134:135]
	ds_read_b128 v[178:181], v145 offset:32768
	ds_read_b128 v[182:185], v145 offset:33792
	ds_read_b128 v[186:189], v145 offset:34816
	ds_read_b128 v[190:193], v145 offset:35840
	ds_read_b128 v[202:205], v145 offset:36864
	ds_read_b128 v[206:209], v145 offset:37888
	ds_read_b128 v[210:213], v145 offset:38912
	ds_read_b128 v[214:217], v145 offset:39936
	global_load_lds_dwordx4 v[222:223], off
	v_lshl_add_u64 v[222:223], s[16:17], 0, v[132:133]
	s_mov_b32 m0, s44
	s_nop 0
	global_load_lds_dwordx4 v[222:223], off
	s_waitcnt vmcnt(8)
	s_waitcnt lgkmcnt(0)
	s_barrier
	s_setprio 1
	s_waitcnt lgkmcnt(0)
	v_mfma_f32_16x16x32_bf16 v[126:129], v[146:149], v[178:181], v[126:129]
	v_mfma_f32_16x16x32_bf16 v[122:125], v[154:157], v[178:181], v[122:125]
	v_mfma_f32_16x16x32_bf16 v[118:121], v[146:149], v[186:189], v[118:121]
	v_mfma_f32_16x16x32_bf16 v[110:113], v[154:157], v[186:189], v[110:113]
	v_mfma_f32_16x16x32_bf16 v[102:105], v[146:149], v[202:205], v[102:105]
	v_mfma_f32_16x16x32_bf16 v[94:97], v[154:157], v[202:205], v[94:97]
	v_mfma_f32_16x16x32_bf16 v[86:89], v[146:149], v[210:213], v[86:89]
	v_mfma_f32_16x16x32_bf16 v[78:81], v[154:157], v[210:213], v[78:81]
	v_mfma_f32_16x16x32_bf16 v[126:129], v[150:153], v[182:185], v[126:129]
	v_mfma_f32_16x16x32_bf16 v[122:125], v[158:161], v[182:185], v[122:125]
	v_mfma_f32_16x16x32_bf16 v[118:121], v[150:153], v[190:193], v[118:121]
	v_mfma_f32_16x16x32_bf16 v[110:113], v[158:161], v[190:193], v[110:113]
	v_mfma_f32_16x16x32_bf16 v[102:105], v[150:153], v[206:209], v[102:105]
	v_mfma_f32_16x16x32_bf16 v[94:97], v[158:161], v[206:209], v[94:97]
	v_mfma_f32_16x16x32_bf16 v[86:89], v[150:153], v[214:217], v[86:89]
	v_mfma_f32_16x16x32_bf16 v[78:81], v[158:161], v[214:217], v[78:81]
	s_setprio 0
	s_setprio 1
	v_mfma_f32_16x16x32_bf16 v[114:117], v[162:165], v[178:181], v[114:117]
	v_mfma_f32_16x16x32_bf16 v[106:109], v[170:173], v[178:181], v[106:109]
	v_mfma_f32_16x16x32_bf16 v[98:101], v[162:165], v[186:189], v[98:101]
	v_mfma_f32_16x16x32_bf16 v[90:93], v[170:173], v[186:189], v[90:93]
	v_mfma_f32_16x16x32_bf16 v[82:85], v[162:165], v[202:205], v[82:85]
	v_mfma_f32_16x16x32_bf16 v[74:77], v[170:173], v[202:205], v[74:77]
	v_mfma_f32_16x16x32_bf16 v[70:73], v[162:165], v[210:213], v[70:73]
	v_mfma_f32_16x16x32_bf16 v[66:69], v[170:173], v[210:213], v[66:69]
	v_mfma_f32_16x16x32_bf16 v[114:117], v[166:169], v[182:185], v[114:117]
	v_mfma_f32_16x16x32_bf16 v[106:109], v[174:177], v[182:185], v[106:109]
	v_mfma_f32_16x16x32_bf16 v[98:101], v[166:169], v[190:193], v[98:101]
	v_mfma_f32_16x16x32_bf16 v[90:93], v[174:177], v[190:193], v[90:93]
	v_mfma_f32_16x16x32_bf16 v[82:85], v[166:169], v[206:209], v[82:85]
	v_mfma_f32_16x16x32_bf16 v[74:77], v[174:177], v[206:209], v[74:77]
	v_mfma_f32_16x16x32_bf16 v[70:73], v[166:169], v[214:217], v[70:73]
	v_mfma_f32_16x16x32_bf16 v[66:69], v[174:177], v[214:217], v[66:69]
	s_setprio 0
	s_barrier
; #define PG8_STAGE(bufoff, gbase, voff) do { _Pragma("unroll") for (int _i = 0; _i < 2; ++_i) \
;         __builtin_amdgcn_global_load_lds((const unsigned*)((const char*)(gbase) + (voff)[_i]), (LAS unsigned*)(lds + (bufoff) + ldsw + _i * 8192), 16, 0, 0); } while (0)
; #define PG8_WAIT_V(n) asm volatile("s_waitcnt vmcnt(" #n ")" ::: "memory")
; #define PG8_WAIT_L(n) asm volatile("s_waitcnt lgkmcnt(" #n ")" ::: "memory")
; #define PG8_BAR __builtin_amdgcn_s_barrier()
; #define PG8_SCHED __builtin_amdgcn_sched_barrier(0)
; template <bool F8 = false, class Epi, class Sched>
; __device__ __forceinline__ void gemm_phase(LAS unsigned char* lds, const int lda, const int ldb, const int K, const Sched& S, const Epi& E) {
;     ...
;             PG8_LDA(At, 1, 1); PG8_STAGE(PG8_SB(1, 0), b3, voffB); PG8_STAGE(PG8_SB(1, 1), b3 + hstepB, voffB); PG8_STAGE(PG8_SA(1, 0), a3, voffA);
;             PG8_WAIT_V(8); PG8_WAIT_L(0); PG8_BAR; PG8_MMA(1, 0, At, B0); PG8_MMA(1, 1, At, B1); PG8_BAR; PG8_SCHED;
;         }
;         if (wr == 0) PG8_BAR;
	s_add_i32 s16, s30, s24
	v_lshl_add_u64 v[140:141], v[140:141], 0, s[40:41]
	s_mov_b32 m0, s16
	ds_read_b128 v[178:181], v145 offset:49152
	ds_read_b128 v[182:185], v145 offset:50176
	ds_read_b128 v[186:189], v145 offset:51200
	ds_read_b128 v[190:193], v145 offset:52224
	ds_read_b128 v[202:205], v145 offset:53248
	ds_read_b128 v[206:209], v145 offset:54272
	ds_read_b128 v[210:213], v145 offset:55296
	ds_read_b128 v[214:217], v145 offset:56320
	global_load_lds_dwordx4 v[140:141], off
	s_add_i32 m0, s16, 0x2000
	s_add_u32 s16, s20, 0x160080
	v_lshl_add_u64 v[140:141], v[194:195], 0, s[40:41]
	s_addc_u32 s17, s21, 0
	s_add_i32 s20, s31, s24
	global_load_lds_dwordx4 v[140:141], off
	v_lshl_add_u64 v[140:141], s[16:17], 0, v[0:1]
	s_mov_b32 m0, s20
	s_nop 0
	global_load_lds_dwordx4 v[140:141], off
	v_lshl_add_u64 v[140:141], s[16:17], 0, v[130:131]
	s_add_i32 m0, s20, 0x2000
	s_nop 0
	global_load_lds_dwordx4 v[140:141], off
	v_lshl_add_u64 v[140:141], v[218:219], 0, s[40:41]
	s_mov_b32 m0, s56
	s_nop 0
	global_load_lds_dwordx4 v[140:141], off
	v_lshl_add_u64 v[140:141], v[220:221], 0, s[40:41]
	s_mov_b32 m0, s57
	s_nop 0
	global_load_lds_dwordx4 v[140:141], off
	s_waitcnt vmcnt(8)
	s_waitcnt lgkmcnt(0)
	s_barrier
	s_setprio 1
	s_waitcnt lgkmcnt(0)
	v_mfma_f32_16x16x32_bf16 v[62:65], v[146:149], v[178:181], v[62:65]
	v_mfma_f32_16x16x32_bf16 v[58:61], v[154:157], v[178:181], v[58:61]
	v_mfma_f32_16x16x32_bf16 v[54:57], v[146:149], v[186:189], v[54:57]
	v_mfma_f32_16x16x32_bf16 v[46:49], v[154:157], v[186:189], v[46:49]
	v_mfma_f32_16x16x32_bf16 v[38:41], v[146:149], v[202:205], v[38:41]
	v_mfma_f32_16x16x32_bf16 v[30:33], v[154:157], v[202:205], v[30:33]
	v_mfma_f32_16x16x32_bf16 v[22:25], v[146:149], v[210:213], v[22:25]
	v_mfma_f32_16x16x32_bf16 v[14:17], v[154:157], v[210:213], v[14:17]
	v_mfma_f32_16x16x32_bf16 v[62:65], v[150:153], v[182:185], v[62:65]
	v_mfma_f32_16x16x32_bf16 v[58:61], v[158:161], v[182:185], v[58:61]
	v_mfma_f32_16x16x32_bf16 v[54:57], v[150:153], v[190:193], v[54:57]
	v_mfma_f32_16x16x32_bf16 v[46:49], v[158:161], v[190:193], v[46:49]
	v_mfma_f32_16x16x32_bf16 v[38:41], v[150:153], v[206:209], v[38:41]
	v_mfma_f32_16x16x32_bf16 v[30:33], v[158:161], v[206:209], v[30:33]
	v_mfma_f32_16x16x32_bf16 v[22:25], v[150:153], v[214:217], v[22:25]
	v_mfma_f32_16x16x32_bf16 v[14:17], v[158:161], v[214:217], v[14:17]
	s_setprio 0
	s_setprio 1
	v_mfma_f32_16x16x32_bf16 v[50:53], v[162:165], v[178:181], v[50:53]
	v_mfma_f32_16x16x32_bf16 v[42:45], v[170:173], v[178:181], v[42:45]
	v_mfma_f32_16x16x32_bf16 v[34:37], v[162:165], v[186:189], v[34:37]
	v_mfma_f32_16x16x32_bf16 v[26:29], v[170:173], v[186:189], v[26:29]
	v_mfma_f32_16x16x32_bf16 v[18:21], v[162:165], v[202:205], v[18:21]
	v_mfma_f32_16x16x32_bf16 v[10:13], v[170:173], v[202:205], v[10:13]
	v_mfma_f32_16x16x32_bf16 v[6:9], v[162:165], v[210:213], v[6:9]
	v_mfma_f32_16x16x32_bf16 v[2:5], v[170:173], v[210:213], v[2:5]
	v_mfma_f32_16x16x32_bf16 v[50:53], v[166:169], v[182:185], v[50:53]
	v_mfma_f32_16x16x32_bf16 v[42:45], v[174:177], v[182:185], v[42:45]
	v_mfma_f32_16x16x32_bf16 v[34:37], v[166:169], v[190:193], v[34:37]
	v_mfma_f32_16x16x32_bf16 v[26:29], v[174:177], v[190:193], v[26:29]
	v_mfma_f32_16x16x32_bf16 v[18:21], v[166:169], v[206:209], v[18:21]
	v_mfma_f32_16x16x32_bf16 v[10:13], v[174:177], v[206:209], v[10:13]
	v_mfma_f32_16x16x32_bf16 v[6:9], v[166:169], v[214:217], v[6:9]
	v_mfma_f32_16x16x32_bf16 v[2:5], v[174:177], v[214:217], v[2:5]
	s_add_i32 s94, s94, 2
	s_add_u32 s28, s28, 0x100
	s_addc_u32 s29, s29, 0
	s_cmpk_gt_u32 s94, 0x55
	s_mov_b64 s[16:17], s[18:19]
	s_setprio 0
	s_barrier
	s_cbranch_scc0 .LBB0_1149
	s_and_b64 vcc, exec, s[6:7]
	s_cbranch_vccz .LBB0_1152
	s_barrier

; #define PG8_STAGE(bufoff, gbase, voff) do { _Pragma("unroll") for (int _i = 0; _i < 2; ++_i) \
;         __builtin_amdgcn_global_load_lds((const unsigned*)((const char*)(gbase) + (voff)[_i]), (LAS unsigned*)(lds + (bufoff) + ldsw + _i * 8192), 16, 0, 0); } while (0)
; #define PG8_WAIT_V(n) asm volatile("s_waitcnt vmcnt(" #n ")" ::: "memory")
; #define PG8_WAIT_L(n) asm volatile("s_waitcnt lgkmcnt(" #n ")" ::: "memory")
; #define PG8_BAR __builtin_amdgcn_s_barrier()
; #define PG8_SCHED __builtin_amdgcn_sched_barrier(0)
; template <bool F8 = false, class Epi, class Sched>
; __device__ __forceinline__ void gemm_phase(LAS unsigned char* lds, const int lda, const int ldb, const int K, const Sched& S, const Epi& E) {
;     ...
;             const bool last = (t == nt - 2);
;             const char* a1 = cA + (size_t)(t + 1) * kstep;
;             const char* a2 = last ? nA : cA + (size_t)(t + 2) * kstep; const char* b2 = last ? nB : cB + (size_t)(t + 2) * kstep;
;             const char* a3 = a2 + kstep; const char* b3 = b2 + kstep;
;             PG8_LDB(B0, 0, 0); PG8_LDB(B1, 0, 1); PG8_SCHED; PG8_LDA(At, 0, 0); PG8_STAGE(PG8_SA(1, 1), a1 + hstepA, voffA);
;             PG8_WAIT_V(8); PG8_WAIT_L(0); PG8_BAR; PG8_MMA(0, 0, At, B0); PG8_MMA(0, 1, At, B1); PG8_BAR; PG8_SCHED;
;             PG8_LDA(At, 0, 1); PG8_STAGE(PG8_SB(0, 0), b2, voffB); PG8_STAGE(PG8_SB(0, 1), b2 + hstepB, voffB); PG8_STAGE(PG8_SA(0, 0), a2, voffA);
;             PG8_WAIT_V(8); PG8_WAIT_L(0); PG8_BAR; PG8_MMA(1, 0, At, B0); PG8_MMA(1, 1, At, B1); PG8_BAR; PG8_SCHED;
.LBB0_1177:
	s_add_u32 s18, s16, 0x100
	s_addc_u32 s19, s17, 0
	s_add_i32 s30, 0, 0x10000
	s_cmp_eq_u32 s96, 18
	s_cselect_b32 s53, s13, s19
	s_cselect_b32 s52, s12, s18
	v_add_u32_e32 v0, s30, v140
	s_cselect_b32 s21, s15, s29
	s_cselect_b32 s20, s14, s28
	s_add_i32 s31, 0, 0x14000
	ds_read_b128 v[144:147], v0
	ds_read_b128 v[148:151], v0 offset:1024
	ds_read_b128 v[152:155], v0 offset:2048
	ds_read_b128 v[156:159], v0 offset:3072
	v_add_u32_e32 v0, s31, v140
	ds_read_b128 v[160:163], v0
	ds_read_b128 v[164:167], v0 offset:1024
	ds_read_b128 v[168:171], v0 offset:2048
	ds_read_b128 v[172:175], v0 offset:3072
	v_lshl_add_u64 v[138:139], s[16:17], 0, v[134:135]
	s_add_i32 m0, s25, 0xc000
	ds_read_b128 v[176:179], v142
	ds_read_b128 v[180:183], v142 offset:1024
	ds_read_b128 v[184:187], v142 offset:2048
	ds_read_b128 v[188:191], v142 offset:3072
	ds_read_b128 v[192:195], v142 offset:4096
	ds_read_b128 v[202:205], v142 offset:5120
	ds_read_b128 v[206:209], v142 offset:6144
	ds_read_b128 v[210:213], v142 offset:7168
	global_load_lds_dwordx4 v[138:139], off
	v_lshl_add_u64 v[138:139], s[16:17], 0, v[136:137]
	s_add_i32 m0, s25, 0xe000
	s_nop 0
	global_load_lds_dwordx4 v[138:139], off
	s_waitcnt vmcnt(8)
	s_waitcnt lgkmcnt(0)
	s_barrier
	s_setprio 1
	s_waitcnt lgkmcnt(0)
	v_mfma_f32_16x16x32_bf16 v[126:129], v[144:147], v[176:179], v[126:129]
	v_mfma_f32_16x16x32_bf16 v[122:125], v[152:155], v[176:179], v[122:125]
	v_mfma_f32_16x16x32_bf16 v[118:121], v[144:147], v[184:187], v[118:121]
	v_mfma_f32_16x16x32_bf16 v[110:113], v[152:155], v[184:187], v[110:113]
	v_mfma_f32_16x16x32_bf16 v[102:105], v[144:147], v[192:195], v[102:105]
	v_mfma_f32_16x16x32_bf16 v[94:97], v[152:155], v[192:195], v[94:97]
	v_mfma_f32_16x16x32_bf16 v[86:89], v[144:147], v[206:209], v[86:89]
	v_mfma_f32_16x16x32_bf16 v[78:81], v[152:155], v[206:209], v[78:81]
	v_mfma_f32_16x16x32_bf16 v[126:129], v[148:151], v[180:183], v[126:129]
	v_mfma_f32_16x16x32_bf16 v[122:125], v[156:159], v[180:183], v[122:125]
	v_mfma_f32_16x16x32_bf16 v[118:121], v[148:151], v[188:191], v[118:121]
	v_mfma_f32_16x16x32_bf16 v[110:113], v[156:159], v[188:191], v[110:113]
	v_mfma_f32_16x16x32_bf16 v[102:105], v[148:151], v[202:205], v[102:105]
	v_mfma_f32_16x16x32_bf16 v[94:97], v[156:159], v[202:205], v[94:97]
	v_mfma_f32_16x16x32_bf16 v[86:89], v[148:151], v[210:213], v[86:89]
	v_mfma_f32_16x16x32_bf16 v[78:81], v[156:159], v[210:213], v[78:81]
	s_setprio 0
	s_setprio 1
	v_mfma_f32_16x16x32_bf16 v[114:117], v[160:163], v[176:179], v[114:117]
	v_mfma_f32_16x16x32_bf16 v[106:109], v[168:171], v[176:179], v[106:109]
	v_mfma_f32_16x16x32_bf16 v[98:101], v[160:163], v[184:187], v[98:101]
	v_mfma_f32_16x16x32_bf16 v[90:93], v[168:171], v[184:187], v[90:93]
	v_mfma_f32_16x16x32_bf16 v[82:85], v[160:163], v[192:195], v[82:85]
	v_mfma_f32_16x16x32_bf16 v[74:77], v[168:171], v[192:195], v[74:77]
	v_mfma_f32_16x16x32_bf16 v[70:73], v[160:163], v[206:209], v[70:73]
	v_mfma_f32_16x16x32_bf16 v[66:69], v[168:171], v[206:209], v[66:69]
	v_mfma_f32_16x16x32_bf16 v[114:117], v[164:167], v[180:183], v[114:117]
	v_mfma_f32_16x16x32_bf16 v[106:109], v[172:175], v[180:183], v[106:109]
	v_mfma_f32_16x16x32_bf16 v[98:101], v[164:167], v[188:191], v[98:101]
	v_mfma_f32_16x16x32_bf16 v[90:93], v[172:175], v[188:191], v[90:93]
	v_mfma_f32_16x16x32_bf16 v[82:85], v[164:167], v[202:205], v[82:85]
	v_mfma_f32_16x16x32_bf16 v[74:77], v[172:175], v[202:205], v[74:77]
	v_mfma_f32_16x16x32_bf16 v[70:73], v[164:167], v[210:213], v[70:73]
	v_mfma_f32_16x16x32_bf16 v[66:69], v[172:175], v[210:213], v[66:69]
	s_setprio 0
	s_barrier
	s_add_i32 s16, s30, s24
	v_lshl_add_u64 v[138:139], s[20:21], 0, v[132:133]
	s_mov_b32 m0, s16
	ds_read_b128 v[176:179], v142 offset:16384
	ds_read_b128 v[180:183], v142 offset:17408
	ds_read_b128 v[184:187], v142 offset:18432
	ds_read_b128 v[188:191], v142 offset:19456
	ds_read_b128 v[192:195], v142 offset:20480
	ds_read_b128 v[202:205], v142 offset:21504
	ds_read_b128 v[206:209], v142 offset:22528
	ds_read_b128 v[210:213], v142 offset:23552
	global_load_lds_dwordx4 v[138:139], off
	s_add_i32 m0, s16, 0x2000
	s_add_u32 s16, s20, 0x160000
	v_lshl_add_u64 v[214:215], s[20:21], 0, v[130:131]
	s_addc_u32 s17, s21, 0
	s_add_i32 s30, s31, s24
	global_load_lds_dwordx4 v[214:215], off
	v_lshl_add_u64 v[216:217], s[16:17], 0, v[132:133]
	s_mov_b32 m0, s30
	v_lshl_add_u64 v[218:219], s[52:53], 0, v[130:131]
	global_load_lds_dwordx4 v[216:217], off
	v_lshl_add_u64 v[216:217], s[16:17], 0, v[130:131]
	s_add_i32 m0, s30, 0x2000
	s_nop 0
	global_load_lds_dwordx4 v[216:217], off
	v_lshl_add_u64 v[216:217], s[52:53], 0, v[132:133]
	s_mov_b32 m0, s25
	s_nop 0
	global_load_lds_dwordx4 v[216:217], off
	s_mov_b32 m0, s26
	s_nop 0
	global_load_lds_dwordx4 v[218:219], off
	s_waitcnt vmcnt(8)
	s_waitcnt lgkmcnt(0)
	s_barrier
; #define PG8_STAGE(bufoff, gbase, voff) do { _Pragma("unroll") for (int _i = 0; _i < 2; ++_i) \
;         __builtin_amdgcn_global_load_lds((const unsigned*)((const char*)(gbase) + (voff)[_i]), (LAS unsigned*)(lds + (bufoff) + ldsw + _i * 8192), 16, 0, 0); } while (0)
; #define PG8_WAIT_V(n) asm volatile("s_waitcnt vmcnt(" #n ")" ::: "memory")
; #define PG8_WAIT_L(n) asm volatile("s_waitcnt lgkmcnt(" #n ")" ::: "memory")
; #define PG8_BAR __builtin_amdgcn_s_barrier()
; #define PG8_SCHED __builtin_amdgcn_sched_barrier(0)
; template <bool F8 = false, class Epi, class Sched>
; __device__ __forceinline__ void gemm_phase(LAS unsigned char* lds, const int lda, const int ldb, const int K, const Sched& S, const Epi& E) {
;     ...
;             PG8_WAIT_V(8); PG8_WAIT_L(0); PG8_BAR; PG8_MMA(1, 0, At, B0); PG8_MMA(1, 1, At, B1); PG8_BAR; PG8_SCHED;
;             PG8_LDB(B0, 1, 0); PG8_LDB(B1, 1, 1); PG8_SCHED; PG8_LDA(At, 1, 0); PG8_STAGE(PG8_SA(0, 1), a2 + hstepA, voffA);
;             PG8_WAIT_V(8); PG8_WAIT_L(0); PG8_BAR; PG8_MMA(0, 0, At, B0); PG8_MMA(0, 1, At, B1); PG8_BAR; PG8_SCHED;
	s_setprio 1
	s_waitcnt lgkmcnt(0)
	v_mfma_f32_16x16x32_bf16 v[62:65], v[144:147], v[176:179], v[62:65]
	v_mfma_f32_16x16x32_bf16 v[58:61], v[152:155], v[176:179], v[58:61]
	v_mfma_f32_16x16x32_bf16 v[54:57], v[144:147], v[184:187], v[54:57]
	v_mfma_f32_16x16x32_bf16 v[42:45], v[152:155], v[184:187], v[42:45]
	v_mfma_f32_16x16x32_bf16 v[38:41], v[144:147], v[192:195], v[38:41]
	v_mfma_f32_16x16x32_bf16 v[26:29], v[152:155], v[192:195], v[26:29]
	v_mfma_f32_16x16x32_bf16 v[22:25], v[144:147], v[206:209], v[22:25]
	v_mfma_f32_16x16x32_bf16 v[10:13], v[152:155], v[206:209], v[10:13]
	v_mfma_f32_16x16x32_bf16 v[62:65], v[148:151], v[180:183], v[62:65]
	v_mfma_f32_16x16x32_bf16 v[58:61], v[156:159], v[180:183], v[58:61]
	v_mfma_f32_16x16x32_bf16 v[54:57], v[148:151], v[188:191], v[54:57]
	v_mfma_f32_16x16x32_bf16 v[42:45], v[156:159], v[188:191], v[42:45]
	v_mfma_f32_16x16x32_bf16 v[38:41], v[148:151], v[202:205], v[38:41]
	v_mfma_f32_16x16x32_bf16 v[26:29], v[156:159], v[202:205], v[26:29]
	v_mfma_f32_16x16x32_bf16 v[22:25], v[148:151], v[210:213], v[22:25]
	v_mfma_f32_16x16x32_bf16 v[10:13], v[156:159], v[210:213], v[10:13]
	s_setprio 0
	s_setprio 1
	v_mfma_f32_16x16x32_bf16 v[50:53], v[160:163], v[176:179], v[50:53]
	v_mfma_f32_16x16x32_bf16 v[46:49], v[168:171], v[176:179], v[46:49]
	v_mfma_f32_16x16x32_bf16 v[34:37], v[160:163], v[184:187], v[34:37]
	v_mfma_f32_16x16x32_bf16 v[30:33], v[168:171], v[184:187], v[30:33]
	v_mfma_f32_16x16x32_bf16 v[18:21], v[160:163], v[192:195], v[18:21]
	v_mfma_f32_16x16x32_bf16 v[14:17], v[168:171], v[192:195], v[14:17]
	v_mfma_f32_16x16x32_bf16 v[6:9], v[160:163], v[206:209], v[6:9]
	v_mfma_f32_16x16x32_bf16 v[2:5], v[168:171], v[206:209], v[2:5]
	v_mfma_f32_16x16x32_bf16 v[50:53], v[164:167], v[180:183], v[50:53]
	v_mfma_f32_16x16x32_bf16 v[46:49], v[172:175], v[180:183], v[46:49]
	v_mfma_f32_16x16x32_bf16 v[34:37], v[164:167], v[188:191], v[34:37]
	v_mfma_f32_16x16x32_bf16 v[30:33], v[172:175], v[188:191], v[30:33]
	v_mfma_f32_16x16x32_bf16 v[18:21], v[164:167], v[202:205], v[18:21]
	v_mfma_f32_16x16x32_bf16 v[14:17], v[172:175], v[202:205], v[14:17]
	v_mfma_f32_16x16x32_bf16 v[6:9], v[164:167], v[210:213], v[6:9]
	v_mfma_f32_16x16x32_bf16 v[2:5], v[172:175], v[210:213], v[2:5]
	s_setprio 0
	s_barrier
	s_add_i32 s30, 0, 0x18000
	v_add_u32_e32 v0, s30, v140
	s_add_i32 s31, 0, 0x1c000
	ds_read_b128 v[144:147], v0
	ds_read_b128 v[148:151], v0 offset:1024
	ds_read_b128 v[152:155], v0 offset:2048
	ds_read_b128 v[156:159], v0 offset:3072
	v_add_u32_e32 v0, s31, v140
	ds_read_b128 v[160:163], v0
	ds_read_b128 v[164:167], v0 offset:1024
	ds_read_b128 v[168:171], v0 offset:2048
	ds_read_b128 v[172:175], v0 offset:3072
	s_add_u32 s16, s52, 0x160000
	s_addc_u32 s17, s53, 0
	s_mov_b32 m0, s27
	v_lshl_add_u64 v[220:221], s[16:17], 0, v[132:133]
	ds_read_b128 v[176:179], v142 offset:32768
	ds_read_b128 v[180:183], v142 offset:33792
	ds_read_b128 v[184:187], v142 offset:34816
	ds_read_b128 v[188:191], v142 offset:35840
	ds_read_b128 v[192:195], v142 offset:36864
	ds_read_b128 v[202:205], v142 offset:37888
	ds_read_b128 v[206:209], v142 offset:38912
	ds_read_b128 v[210:213], v142 offset:39936
	global_load_lds_dwordx4 v[220:221], off
	v_lshl_add_u64 v[220:221], s[16:17], 0, v[130:131]
	s_mov_b32 m0, s44
	s_nop 0
	global_load_lds_dwordx4 v[220:221], off
	s_waitcnt vmcnt(8)
	s_waitcnt lgkmcnt(0)
	s_barrier
	s_setprio 1
	s_waitcnt lgkmcnt(0)
	v_mfma_f32_16x16x32_bf16 v[126:129], v[144:147], v[176:179], v[126:129]
	v_mfma_f32_16x16x32_bf16 v[122:125], v[152:155], v[176:179], v[122:125]
	v_mfma_f32_16x16x32_bf16 v[118:121], v[144:147], v[184:187], v[118:121]
	v_mfma_f32_16x16x32_bf16 v[110:113], v[152:155], v[184:187], v[110:113]
	v_mfma_f32_16x16x32_bf16 v[102:105], v[144:147], v[192:195], v[102:105]
	v_mfma_f32_16x16x32_bf16 v[94:97], v[152:155], v[192:195], v[94:97]
	v_mfma_f32_16x16x32_bf16 v[86:89], v[144:147], v[206:209], v[86:89]
	v_mfma_f32_16x16x32_bf16 v[78:81], v[152:155], v[206:209], v[78:81]
	v_mfma_f32_16x16x32_bf16 v[126:129], v[148:151], v[180:183], v[126:129]
	v_mfma_f32_16x16x32_bf16 v[122:125], v[156:159], v[180:183], v[122:125]
	v_mfma_f32_16x16x32_bf16 v[118:121], v[148:151], v[188:191], v[118:121]
	v_mfma_f32_16x16x32_bf16 v[110:113], v[156:159], v[188:191], v[110:113]
	v_mfma_f32_16x16x32_bf16 v[102:105], v[148:151], v[202:205], v[102:105]
	v_mfma_f32_16x16x32_bf16 v[94:97], v[156:159], v[202:205], v[94:97]
	v_mfma_f32_16x16x32_bf16 v[86:89], v[148:151], v[210:213], v[86:89]
	v_mfma_f32_16x16x32_bf16 v[78:81], v[156:159], v[210:213], v[78:81]
	s_setprio 0
	s_setprio 1
	v_mfma_f32_16x16x32_bf16 v[114:117], v[160:163], v[176:179], v[114:117]
	v_mfma_f32_16x16x32_bf16 v[106:109], v[168:171], v[176:179], v[106:109]
	v_mfma_f32_16x16x32_bf16 v[98:101], v[160:163], v[184:187], v[98:101]
	v_mfma_f32_16x16x32_bf16 v[90:93], v[168:171], v[184:187], v[90:93]
	v_mfma_f32_16x16x32_bf16 v[82:85], v[160:163], v[192:195], v[82:85]
	v_mfma_f32_16x16x32_bf16 v[74:77], v[168:171], v[192:195], v[74:77]
	v_mfma_f32_16x16x32_bf16 v[70:73], v[160:163], v[206:209], v[70:73]
	v_mfma_f32_16x16x32_bf16 v[66:69], v[168:171], v[206:209], v[66:69]
	v_mfma_f32_16x16x32_bf16 v[114:117], v[164:167], v[180:183], v[114:117]
	v_mfma_f32_16x16x32_bf16 v[106:109], v[172:175], v[180:183], v[106:109]
	v_mfma_f32_16x16x32_bf16 v[98:101], v[164:167], v[188:191], v[98:101]
	v_mfma_f32_16x16x32_bf16 v[90:93], v[172:175], v[188:191], v[90:93]
	v_mfma_f32_16x16x32_bf16 v[82:85], v[164:167], v[202:205], v[82:85]
	v_mfma_f32_16x16x32_bf16 v[74:77], v[172:175], v[202:205], v[74:77]
	v_mfma_f32_16x16x32_bf16 v[70:73], v[164:167], v[210:213], v[70:73]
	v_mfma_f32_16x16x32_bf16 v[66:69], v[172:175], v[210:213], v[66:69]
	s_setprio 0
	s_barrier
; #define PG8_STAGE(bufoff, gbase, voff) do { _Pragma("unroll") for (int _i = 0; _i < 2; ++_i) \
;         __builtin_amdgcn_global_load_lds((const unsigned*)((const char*)(gbase) + (voff)[_i]), (LAS unsigned*)(lds + (bufoff) + ldsw + _i * 8192), 16, 0, 0); } while (0)
; #define PG8_WAIT_V(n) asm volatile("s_waitcnt vmcnt(" #n ")" ::: "memory")
; #define PG8_WAIT_L(n) asm volatile("s_waitcnt lgkmcnt(" #n ")" ::: "memory")
; #define PG8_BAR __builtin_amdgcn_s_barrier()
; #define PG8_SCHED __builtin_amdgcn_sched_barrier(0)
; template <bool F8 = false, class Epi, class Sched>
; __device__ __forceinline__ void gemm_phase(LAS unsigned char* lds, const int lda, const int ldb, const int K, const Sched& S, const Epi& E) {
;     ...
;             PG8_LDA(At, 1, 1); PG8_STAGE(PG8_SB(1, 0), b3, voffB); PG8_STAGE(PG8_SB(1, 1), b3 + hstepB, voffB); PG8_STAGE(PG8_SA(1, 0), a3, voffA);
;             PG8_WAIT_V(8); PG8_WAIT_L(0); PG8_BAR; PG8_MMA(1, 0, At, B0); PG8_MMA(1, 1, At, B1); PG8_BAR; PG8_SCHED;
;         }
;         if (wr == 0) PG8_BAR;
	s_add_i32 s16, s30, s24
	v_lshl_add_u64 v[138:139], v[138:139], 0, s[40:41]
	s_mov_b32 m0, s16
	ds_read_b128 v[176:179], v142 offset:49152
	ds_read_b128 v[180:183], v142 offset:50176
	ds_read_b128 v[184:187], v142 offset:51200
	ds_read_b128 v[188:191], v142 offset:52224
	ds_read_b128 v[192:195], v142 offset:53248
	ds_read_b128 v[202:205], v142 offset:54272
	ds_read_b128 v[206:209], v142 offset:55296
	ds_read_b128 v[210:213], v142 offset:56320
	global_load_lds_dwordx4 v[138:139], off
	s_add_i32 m0, s16, 0x2000
	s_add_u32 s16, s20, 0x160080
	v_lshl_add_u64 v[138:139], v[214:215], 0, s[40:41]
	s_addc_u32 s17, s21, 0
	s_add_i32 s20, s31, s24
	global_load_lds_dwordx4 v[138:139], off
	v_lshl_add_u64 v[138:139], s[16:17], 0, v[132:133]
	s_mov_b32 m0, s20
	s_nop 0
	global_load_lds_dwordx4 v[138:139], off
	v_lshl_add_u64 v[138:139], s[16:17], 0, v[130:131]
	s_add_i32 m0, s20, 0x2000
	s_nop 0
	global_load_lds_dwordx4 v[138:139], off
	v_lshl_add_u64 v[138:139], v[216:217], 0, s[40:41]
	s_mov_b32 m0, s56
	s_nop 0
	global_load_lds_dwordx4 v[138:139], off
	v_lshl_add_u64 v[138:139], v[218:219], 0, s[40:41]
	s_mov_b32 m0, s57
	s_nop 0
	global_load_lds_dwordx4 v[138:139], off
	s_waitcnt vmcnt(8)
	s_waitcnt lgkmcnt(0)
	s_barrier
	s_setprio 1
	s_waitcnt lgkmcnt(0)
	v_mfma_f32_16x16x32_bf16 v[62:65], v[144:147], v[176:179], v[62:65]
	v_mfma_f32_16x16x32_bf16 v[58:61], v[152:155], v[176:179], v[58:61]
	v_mfma_f32_16x16x32_bf16 v[54:57], v[144:147], v[184:187], v[54:57]
	v_mfma_f32_16x16x32_bf16 v[42:45], v[152:155], v[184:187], v[42:45]
	v_mfma_f32_16x16x32_bf16 v[38:41], v[144:147], v[192:195], v[38:41]
	v_mfma_f32_16x16x32_bf16 v[26:29], v[152:155], v[192:195], v[26:29]
	v_mfma_f32_16x16x32_bf16 v[22:25], v[144:147], v[206:209], v[22:25]
	v_mfma_f32_16x16x32_bf16 v[10:13], v[152:155], v[206:209], v[10:13]
	v_mfma_f32_16x16x32_bf16 v[62:65], v[148:151], v[180:183], v[62:65]
	v_mfma_f32_16x16x32_bf16 v[58:61], v[156:159], v[180:183], v[58:61]
	v_mfma_f32_16x16x32_bf16 v[54:57], v[148:151], v[188:191], v[54:57]
	v_mfma_f32_16x16x32_bf16 v[42:45], v[156:159], v[188:191], v[42:45]
	v_mfma_f32_16x16x32_bf16 v[38:41], v[148:151], v[202:205], v[38:41]
	v_mfma_f32_16x16x32_bf16 v[26:29], v[156:159], v[202:205], v[26:29]
	v_mfma_f32_16x16x32_bf16 v[22:25], v[148:151], v[210:213], v[22:25]
	v_mfma_f32_16x16x32_bf16 v[10:13], v[156:159], v[210:213], v[10:13]
	s_setprio 0
	s_setprio 1
	v_mfma_f32_16x16x32_bf16 v[50:53], v[160:163], v[176:179], v[50:53]
	v_mfma_f32_16x16x32_bf16 v[46:49], v[168:171], v[176:179], v[46:49]
	v_mfma_f32_16x16x32_bf16 v[34:37], v[160:163], v[184:187], v[34:37]
	v_mfma_f32_16x16x32_bf16 v[30:33], v[168:171], v[184:187], v[30:33]
	v_mfma_f32_16x16x32_bf16 v[18:21], v[160:163], v[192:195], v[18:21]
	v_mfma_f32_16x16x32_bf16 v[14:17], v[168:171], v[192:195], v[14:17]
	v_mfma_f32_16x16x32_bf16 v[6:9], v[160:163], v[206:209], v[6:9]
	v_mfma_f32_16x16x32_bf16 v[2:5], v[168:171], v[206:209], v[2:5]
	v_mfma_f32_16x16x32_bf16 v[50:53], v[164:167], v[180:183], v[50:53]
	v_mfma_f32_16x16x32_bf16 v[46:49], v[172:175], v[180:183], v[46:49]
	v_mfma_f32_16x16x32_bf16 v[34:37], v[164:167], v[188:191], v[34:37]
	v_mfma_f32_16x16x32_bf16 v[30:33], v[172:175], v[188:191], v[30:33]
	v_mfma_f32_16x16x32_bf16 v[18:21], v[164:167], v[202:205], v[18:21]
	v_mfma_f32_16x16x32_bf16 v[14:17], v[172:175], v[202:205], v[14:17]
	v_mfma_f32_16x16x32_bf16 v[6:9], v[164:167], v[210:213], v[6:9]
	v_mfma_f32_16x16x32_bf16 v[2:5], v[172:175], v[210:213], v[2:5]
	s_add_i32 s96, s96, 2
	s_add_u32 s28, s28, 0x100
	s_addc_u32 s29, s29, 0
	s_cmp_gt_u32 s96, 19
	s_mov_b64 s[16:17], s[18:19]
	s_setprio 0
	s_barrier
	s_cbranch_scc0 .LBB0_1177
	s_and_b64 vcc, exec, s[8:9]
	s_cbranch_vccz .LBB0_1180
	s_barrier
